# speedup vs baseline: 1.0030x; 1.0030x over previous
; #define PG8_STAGE(bufoff, gbase, voff) do { _Pragma("unroll") for (int _i = 0; _i < 2; ++_i) \
;         __builtin_amdgcn_global_load_lds((const unsigned*)((const char*)(gbase) + (voff)[_i]), (PG8_LAS unsigned*)(lds + (bufoff) + ldsw + _i * 8192), 16, 0, 0); } while (0)
; #define PG8_WAIT_V(n) asm volatile("s_waitcnt vmcnt(" #n ")" ::: "memory")
; #define PG8_BAR __builtin_amdgcn_s_barrier()
; template <class Epi, class Sched, bool ALIGN_EPI = false, bool SP2 = false>
; __device__ __forceinline__ void gemm_phase(PG8_LAS unsigned char* lds, const Gemm g, const Sched& S, const Epi& E) {
;     ...
;     for (int i = 0; i < 2; ++i) { int R, C; stage_rc(tid * 16 + i * 8192, R, C); const int Rb = Epi::PERM ? ((R & ~31) + perm32(R & 31)) : R;
;         voffA[i] = (unsigned)(R * K + C) * 2u; voffB[i] = (unsigned)(Rb * K + C) * 2u; }
;     const size_t kstep = (size_t)(BK * 2);
;     const size_t hstep = (size_t)HALF * K * 2;
;     const size_t tstep = 2 * hstep;
;     const unsigned ldsw = (unsigned)wid * 1024u;
;     const int aoff = lds_byte(wr * 64 + fr, fq * 8), boff = lds_byte(wc * 32 + fr, fq * 8);
;     ...
;         PG8_STAGE(PG8_SB(0, 0), cB, voffB); PG8_STAGE(PG8_SB(0, 1), cB + hstep, voffB); PG8_STAGE(PG8_SA(0, 0), cA, voffA); PG8_STAGE(PG8_SA(0, 1), cA + hstep, voffA);
;         if (wr == 1) PG8_BAR;
;         PG8_WAIT_V(2); PG8_BAR;
;         PG8_STAGE(PG8_SB(1, 0), cB + kstep, voffB); PG8_STAGE(PG8_SA(1, 0), cA + kstep, voffA); PG8_STAGE(PG8_SB(1, 1), cB + hstep + kstep, voffB);
;         PG8_WAIT_V(6); PG8_BAR;
.LBB0_106:
	s_add_u32 s87, s6, 0x7500000
	s_addc_u32 s88, s7, 0
	s_add_u32 s28, s6, 0xb500000
	s_mov_b64 s[30:31], 0x80
	s_addc_u32 s29, s7, 0
	s_add_i32 m0, s64, 0x18000
	v_lshl_add_u64 v[10:11], v[10:11], 0, s[30:31]
	s_waitcnt vmcnt(2)
	s_barrier
	global_load_lds_dwordx4 v[10:11], off
	v_lshl_add_u64 v[6:7], v[6:7], 0, s[30:31]
	s_add_i32 m0, s64, 0x1a000
	s_add_i32 s89, s64, 0x8000
	global_load_lds_dwordx4 v[6:7], off
	v_lshl_add_u64 v[6:7], v[8:9], 0, s[30:31]
	s_mov_b32 m0, s89
	s_add_i32 s90, s64, 0xa000
	global_load_lds_dwordx4 v[6:7], off
	v_lshl_add_u64 v[6:7], v[12:13], 0, s[30:31]
	s_mov_b32 m0, s90
	v_lshl_add_u64 v[4:5], v[4:5], 0, s[30:31]
	global_load_lds_dwordx4 v[6:7], off
	s_add_i32 m0, s64, 0x1c000
	v_lshl_add_u64 v[2:3], v[2:3], 0, s[30:31]
	global_load_lds_dwordx4 v[4:5], off
	s_add_i32 m0, s64, 0x1e000
	s_lshr_b32 s5, s5, 26
	global_load_lds_dwordx4 v[2:3], off
	v_and_b32_e32 v1, 15, v0
	s_add_i32 s5, s4, s5
	v_lshlrev_b32_e32 v2, 1, v18
	v_lshlrev_b32_e32 v4, 2, v0
	s_ashr_i32 s91, s5, 6
	v_lshl_or_b32 v3, v1, 6, v2
	s_lshl_b32 s5, s35, 13
	v_and_b32_e32 v4, 32, v4
	v_bitop3_b32 v3, v3, s5, v4 bitop3:0xde
	s_lshl_b32 s5, s34, 5
	s_and_b32 s5, s5, 0x60
	v_lshlrev_b32_e32 v5, 6, v0
	s_movk_i32 s6, 0x3c0
	v_and_or_b32 v2, v5, s6, v2
	s_lshl_b32 s6, s5, 7
	v_bitop3_b32 v154, s6, v2, v4 bitop3:0xf6
	v_add_u32_e32 v2, v19, v16
	v_mul_lo_u32 v2, s4, v2
	s_lshl_b32 s92, s35, 6
	v_lshlrev_b32_e32 v2, 1, v2
	s_cmp_gt_i32 s4, 63
	v_add3_u32 v138, v14, v2, v15
	v_add_u32_e32 v2, v17, v16
	s_cselect_b64 s[34:35], -1, 0
	s_add_i32 s93, s91, -2
	v_mul_lo_u32 v2, s4, v2
	s_waitcnt vmcnt(6)
	s_cmpk_lt_u32 s0, 0x100
	v_lshlrev_b32_e32 v2, 1, v2
	s_cselect_b64 s[36:37], -1, 0
	v_lshl_add_u64 v[140:141], s[10:11], 0, v[138:139]
	v_add3_u32 v138, v14, v2, v15
	s_add_i32 s97, 0, 0x10000
	s_add_i32 s80, 0, 0x14000
	v_or_b32_e32 v155, 16, v1
	v_or_b32_e32 v156, 32, v1
	v_or_b32_e32 v157, 48, v1
	s_ashr_i32 s94, s82, 31
	s_mov_b32 s95, s82
	s_ashr_i32 s96, s2, 31
	v_or_b32_e32 v158, s5, v18
	v_lshl_add_u64 v[142:143], s[10:11], 0, v[138:139]
	v_mov_b64_e32 v[144:145], 0x400
	v_mov_b64_e32 v[146:147], 0x3ff
	v_add_u32_e32 v159, s97, v154
	v_add_u32_e32 v160, s80, v154
	v_add_u32_e32 v161, 0, v3
	v_mov_b32_e32 v162, 0x3e38aa3b
	v_mov_b32_e32 v163, 0x1fcf
	v_mov_b32_e32 v164, 0x1fdf
	v_mov_b32_e32 v165, 0x1fef
	v_mov_b32_e32 v166, 0x1fff
	s_barrier
	s_branch .LBB0_109
	.p2align	6
.LBB0_107:
	s_mov_b64 s[4:5], 0
	.p2align	6

; #define PG8_BAR __builtin_amdgcn_s_barrier()
; template <class Epi, class Sched, bool ALIGN_EPI = false, bool SP2 = false>
; __device__ __forceinline__ void gemm_phase(PG8_LAS unsigned char* lds, const Gemm g, const Sched& S, const Epi& E) {
;     ...
; #pragma unroll
;         for (int a = 0; a < 2; ++a)
; #pragma unroll
;             for (int b = 0; b < 2; ++b)
; #pragma unroll
;                 for (int m = 0; m < 4; ++m)
; #pragma unroll
;                     for (int n = 0; n < 2; ++n) acc[a][b][m][n] = (f32x4){0.f, 0.f, 0.f, 0.f};
;         cur = nxt; cA = nA; cB = nB; ++ui;
;         if constexpr (ALIGN_EPI) { if (wr == 1) PG8_BAR; }
.LBB0_119:
	v_mov_b32_e32 v129, 0
	s_andn2_b64 vcc, exec, s[34:35]
	v_mov_b32_e32 v128, v129
	v_mov_b32_e32 v127, v129
	v_mov_b32_e32 v126, v129
	v_mov_b32_e32 v125, v129
	v_mov_b32_e32 v124, v129
	v_mov_b32_e32 v123, v129
	v_mov_b32_e32 v122, v129
	v_mov_b32_e32 v113, v129
	v_mov_b32_e32 v112, v129
	v_mov_b32_e32 v111, v129
	v_mov_b32_e32 v110, v129
	v_mov_b32_e32 v109, v129
	v_mov_b32_e32 v108, v129
	v_mov_b32_e32 v107, v129
	v_mov_b32_e32 v106, v129
	v_mov_b32_e32 v97, v129
	v_mov_b32_e32 v96, v129
	v_mov_b32_e32 v95, v129
	v_mov_b32_e32 v94, v129
	v_mov_b32_e32 v93, v129
	v_mov_b32_e32 v92, v129
	v_mov_b32_e32 v91, v129
	v_mov_b32_e32 v90, v129
	v_mov_b32_e32 v81, v129
	v_mov_b32_e32 v80, v129
	v_mov_b32_e32 v79, v129
	v_mov_b32_e32 v78, v129
	v_mov_b32_e32 v77, v129
	v_mov_b32_e32 v76, v129
	v_mov_b32_e32 v75, v129
	v_mov_b32_e32 v74, v129
	v_mov_b32_e32 v121, v129
	v_mov_b32_e32 v120, v129
	v_mov_b32_e32 v119, v129
	v_mov_b32_e32 v118, v129
	v_mov_b32_e32 v117, v129
	v_mov_b32_e32 v116, v129
	v_mov_b32_e32 v115, v129
	v_mov_b32_e32 v114, v129
	v_mov_b32_e32 v105, v129
	v_mov_b32_e32 v104, v129
	v_mov_b32_e32 v103, v129
	v_mov_b32_e32 v102, v129
	v_mov_b32_e32 v101, v129
	v_mov_b32_e32 v100, v129
	v_mov_b32_e32 v99, v129
	v_mov_b32_e32 v98, v129
	v_mov_b32_e32 v89, v129
	v_mov_b32_e32 v88, v129
	v_mov_b32_e32 v87, v129
	v_mov_b32_e32 v86, v129
	v_mov_b32_e32 v85, v129
	v_mov_b32_e32 v84, v129
	v_mov_b32_e32 v83, v129
	v_mov_b32_e32 v82, v129
	v_mov_b32_e32 v73, v129
	v_mov_b32_e32 v72, v129
	v_mov_b32_e32 v71, v129
	v_mov_b32_e32 v70, v129
	v_mov_b32_e32 v69, v129
	v_mov_b32_e32 v68, v129
	v_mov_b32_e32 v67, v129
	v_mov_b32_e32 v66, v129
	v_mov_b32_e32 v65, v129
	v_mov_b32_e32 v64, v129
	v_mov_b32_e32 v63, v129
	v_mov_b32_e32 v62, v129
	v_mov_b32_e32 v61, v129
	v_mov_b32_e32 v60, v129
	v_mov_b32_e32 v59, v129
	v_mov_b32_e32 v58, v129
	v_mov_b32_e32 v49, v129
	v_mov_b32_e32 v48, v129
	v_mov_b32_e32 v47, v129
	v_mov_b32_e32 v46, v129
	v_mov_b32_e32 v45, v129
	v_mov_b32_e32 v44, v129
	v_mov_b32_e32 v43, v129
	v_mov_b32_e32 v42, v129
	v_mov_b32_e32 v33, v129
	v_mov_b32_e32 v32, v129
	v_mov_b32_e32 v31, v129
	v_mov_b32_e32 v30, v129
	v_mov_b32_e32 v29, v129
	v_mov_b32_e32 v28, v129
	v_mov_b32_e32 v27, v129
	v_mov_b32_e32 v26, v129
	v_mov_b32_e32 v17, v129
	v_mov_b32_e32 v16, v129
	v_mov_b32_e32 v15, v129
	v_mov_b32_e32 v14, v129
	v_mov_b32_e32 v13, v129
	v_mov_b32_e32 v12, v129
	v_mov_b32_e32 v11, v129
	v_mov_b32_e32 v10, v129
	v_mov_b32_e32 v57, v129
	v_mov_b32_e32 v56, v129
	v_mov_b32_e32 v55, v129
	v_mov_b32_e32 v54, v129
	v_mov_b32_e32 v53, v129
	v_mov_b32_e32 v52, v129
	v_mov_b32_e32 v51, v129
	v_mov_b32_e32 v50, v129
	v_mov_b32_e32 v41, v129
	v_mov_b32_e32 v40, v129
	v_mov_b32_e32 v39, v129
	v_mov_b32_e32 v38, v129
	v_mov_b32_e32 v37, v129
	v_mov_b32_e32 v36, v129
	v_mov_b32_e32 v35, v129
	v_mov_b32_e32 v34, v129
	v_mov_b32_e32 v25, v129
	v_mov_b32_e32 v24, v129
	v_mov_b32_e32 v23, v129
	v_mov_b32_e32 v22, v129
	v_mov_b32_e32 v21, v129
	v_mov_b32_e32 v20, v129
	v_mov_b32_e32 v19, v129
	v_mov_b32_e32 v18, v129
	v_mov_b32_e32 v9, v129
	v_mov_b32_e32 v8, v129
	v_mov_b32_e32 v7, v129
	v_mov_b32_e32 v6, v129
	v_mov_b32_e32 v5, v129
	v_mov_b32_e32 v4, v129
	v_mov_b32_e32 v3, v129
	v_mov_b32_e32 v2, v129
	s_cbranch_vccnz .LBB0_122
	s_add_u32 s0, s42, 0x100
	s_addc_u32 vcc_lo, s43, 0
	s_add_u32 s6, s46, 0x80
	v_mov_b32_e32 v2, 0
	s_addc_u32 s7, s47, 0
	s_mov_b32 s42, 0
	v_mov_b32_e32 v3, v2
	v_mov_b32_e32 v4, v2
	v_mov_b32_e32 v5, v2
	v_mov_b32_e32 v6, v2
	v_mov_b32_e32 v7, v2
	v_mov_b32_e32 v8, v2
	v_mov_b32_e32 v9, v2
	v_mov_b32_e32 v18, v2
	v_mov_b32_e32 v19, v2
	v_mov_b32_e32 v20, v2
	v_mov_b32_e32 v21, v2
	v_mov_b32_e32 v22, v2
	v_mov_b32_e32 v23, v2
	v_mov_b32_e32 v24, v2
	v_mov_b32_e32 v25, v2
	v_mov_b32_e32 v34, v2
	v_mov_b32_e32 v35, v2
	v_mov_b32_e32 v36, v2
	v_mov_b32_e32 v37, v2
	v_mov_b32_e32 v38, v2
	v_mov_b32_e32 v39, v2
	v_mov_b32_e32 v40, v2
	v_mov_b32_e32 v41, v2
	v_mov_b32_e32 v50, v2
	v_mov_b32_e32 v51, v2
	v_mov_b32_e32 v52, v2
	v_mov_b32_e32 v53, v2
	v_mov_b32_e32 v54, v2
	v_mov_b32_e32 v55, v2
	v_mov_b32_e32 v56, v2
	v_mov_b32_e32 v57, v2
	v_mov_b32_e32 v10, v2
	v_mov_b32_e32 v11, v2
	v_mov_b32_e32 v12, v2
	v_mov_b32_e32 v13, v2
	v_mov_b32_e32 v14, v2
	v_mov_b32_e32 v15, v2
	v_mov_b32_e32 v16, v2
	v_mov_b32_e32 v17, v2
	v_mov_b32_e32 v26, v2
	v_mov_b32_e32 v27, v2
	v_mov_b32_e32 v28, v2
	v_mov_b32_e32 v29, v2
	v_mov_b32_e32 v30, v2
	v_mov_b32_e32 v31, v2
	v_mov_b32_e32 v32, v2
	v_mov_b32_e32 v33, v2
	v_mov_b32_e32 v42, v2
	v_mov_b32_e32 v43, v2
	v_mov_b32_e32 v44, v2
	v_mov_b32_e32 v45, v2
	v_mov_b32_e32 v46, v2
	v_mov_b32_e32 v47, v2
	v_mov_b32_e32 v48, v2
	v_mov_b32_e32 v49, v2
	v_mov_b32_e32 v58, v2
	v_mov_b32_e32 v59, v2
	v_mov_b32_e32 v60, v2
	v_mov_b32_e32 v61, v2
	v_mov_b32_e32 v62, v2
	v_mov_b32_e32 v63, v2
	v_mov_b32_e32 v64, v2
	v_mov_b32_e32 v65, v2
	v_mov_b32_e32 v66, v2
	v_mov_b32_e32 v67, v2
	v_mov_b32_e32 v68, v2
	v_mov_b32_e32 v69, v2
	v_mov_b32_e32 v70, v2
	v_mov_b32_e32 v71, v2
	v_mov_b32_e32 v72, v2
	v_mov_b32_e32 v73, v2
	v_mov_b32_e32 v82, v2
	v_mov_b32_e32 v83, v2
	v_mov_b32_e32 v84, v2
	v_mov_b32_e32 v85, v2
	v_mov_b32_e32 v86, v2
	v_mov_b32_e32 v87, v2
	v_mov_b32_e32 v88, v2
	v_mov_b32_e32 v89, v2
	v_mov_b32_e32 v98, v2
	v_mov_b32_e32 v99, v2
	v_mov_b32_e32 v100, v2
	v_mov_b32_e32 v101, v2
	v_mov_b32_e32 v102, v2
	v_mov_b32_e32 v103, v2
	v_mov_b32_e32 v104, v2
	v_mov_b32_e32 v105, v2
	v_mov_b32_e32 v114, v2
	v_mov_b32_e32 v115, v2
	v_mov_b32_e32 v116, v2
	v_mov_b32_e32 v117, v2
	v_mov_b32_e32 v118, v2
	v_mov_b32_e32 v119, v2
	v_mov_b32_e32 v120, v2
	v_mov_b32_e32 v121, v2
	v_mov_b32_e32 v74, v2
	v_mov_b32_e32 v75, v2
	v_mov_b32_e32 v76, v2
	v_mov_b32_e32 v77, v2
	v_mov_b32_e32 v78, v2
	v_mov_b32_e32 v79, v2
	v_mov_b32_e32 v80, v2
	v_mov_b32_e32 v81, v2
	v_mov_b32_e32 v90, v2
	v_mov_b32_e32 v91, v2
	v_mov_b32_e32 v92, v2
	v_mov_b32_e32 v93, v2
	v_mov_b32_e32 v94, v2
	v_mov_b32_e32 v95, v2
	v_mov_b32_e32 v96, v2
	v_mov_b32_e32 v97, v2
	v_mov_b32_e32 v106, v2
	v_mov_b32_e32 v107, v2
	v_mov_b32_e32 v108, v2
	v_mov_b32_e32 v109, v2
	v_mov_b32_e32 v110, v2
	v_mov_b32_e32 v111, v2
	v_mov_b32_e32 v112, v2
	v_mov_b32_e32 v113, v2
	v_mov_b32_e32 v122, v2
	v_mov_b32_e32 v123, v2
	v_mov_b32_e32 v124, v2
	v_mov_b32_e32 v125, v2
	v_mov_b32_e32 v126, v2
	v_mov_b32_e32 v127, v2
	v_mov_b32_e32 v128, v2
	v_mov_b32_e32 v129, v2
	.p2align	6

; __device__ __forceinline__ void attn_phase(const bf16_t* __restrict__ Q, const bf16_t* __restrict__ Kb, const bf16_t* __restrict__ Vt, bf16_t* MIX, const float* subln, float lam, const unsigned* kmax2, unsigned* qctr, unsigned char* lds) {
;     constexpr int KP = 272, VP = 136, KBB = 64 * KP, VBB = 128 * VP, BUF = KBB + VBB;
;     const int tid = threadIdx.x, lane = tid & 63, wave = tid >> 6, fr = lane & 15, fq = lane >> 4;
;     const int mi = wave & 1, qs = wave >> 1;
;     const float NEG_INF = -__builtin_inff();
;     for (;;) {
;         {
;             int* uq = (int*)(lds + 2 * BUF + 64);
;             __syncthreads();
;             if (tid == 0) uq[0] = (int)atomicAdd(qctr, 1u);
;             __syncthreads();
;             const int u = __builtin_amdgcn_readfirstlane(uq[0]);
;             if (u >= 1024) break;
;             const int hd = 7 - (u >> 7), b = u & 1, qblk = 63 - ((u & 127) >> 1);
;             const float slope2 = exp2f(-(float)(hd + 1)) * LOG2E;
;             const int q0 = qblk * 128, nt = 2 * qblk + 2, qw0 = q0 + qs * 32;
;             bf16x8 qf[2][2];
; #pragma unroll
;             for (int qb2 = 0; qb2 < 2; ++qb2)
; #pragma unroll
;                 for (int ks = 0; ks < 2; ++ks) qf[qb2][ks] = *(const bf16x8*)(Q + (size_t)(b * SEQ + qw0 + qb2 * 16 + fr) * 1024 + hd * 128 + mi * 64 + ks * 32 + fq * 8);
;             const float cb0 = slope2 * (float)(4 * fq - 32 * qs - fr), cb1 = cb0 - 16.f * slope2;
;             f32x4 o[8][2];
; #pragma unroll
;             for (int db = 0; db < 8; ++db) { o[db][0] = (f32x4){0.f, 0.f, 0.f, 0.f}; o[db][1] = (f32x4){0.f, 0.f, 0.f, 0.f}; }
;             bool first = true;
;             float mref[2] = {0.f, 0.f}, lrow[2] = {0.f, 0.f};
;     ...
;             int kt_w;
;             { float qn0 = 0.f, qn1 = 0.f;
; #pragma unroll
;               for (int ks = 0; ks < 2; ++ks) { const u32x4 w0 = __builtin_bit_cast(u32x4, qf[0][ks]), w1 = __builtin_bit_cast(u32x4, qf[1][ks]);
; #pragma unroll
;                   for (int e = 0; e < 4; ++e) { qn0 += bflo(w0[e]) * bflo(w0[e]) + bfhi(w0[e]) * bfhi(w0[e]); qn1 += bflo(w1[e]) * bflo(w1[e]) + bfhi(w1[e]) * bfhi(w1[e]); } }
;               const float qm = row16_max(fmaxf(rows4_sum(qn0), rows4_sum(qn1)));
;               const float bound = 2.002f * sqrtf(qm * __uint_as_float(kmax2[b * 16 + hd * 2 + mi])) + 152.f;
.LBB0_333:
	s_cmp_lt_i32 s84, 4
	s_cselect_b64 s[22:23], -1, 0
	s_and_b64 s[24:25], s[22:23], s[4:5]
	s_andn2_b64 vcc, exec, s[24:25]
	s_cbranch_vccnz .LBB0_377
	s_mov_b64 s[0:1], s[78:79]
	v_mov_b32_e32 v1, 0x3200000
	global_load_dword v151, v1, s[0:1]
	v_bfe_u32 v159, v0, 6, 1
	v_mov_b32_e32 v133, 0
	v_lshlrev_b32_e32 v130, 7, v159
	v_mov_b32_e32 v131, v133
	s_add_u32 s28, s0, 0x9500000
	v_lshrrev_b32_e32 v8, 7, v0
	s_waitcnt lgkmcnt(0)
	v_lshl_add_u64 v[2:3], s[0:1], 0, v[130:131]
	v_and_b32_e32 v136, 48, v0
	v_mov_b32_e32 v137, v133
	s_addc_u32 s29, s1, 0
	v_and_b32_e32 v158, 15, v0
	v_bfe_u32 v7, v0, 4, 2
	v_lshlrev_b32_e32 v160, 5, v8
	v_lshl_add_u64 v[2:3], v[2:3], 0, v[136:137]
	s_mov_b64 s[4:5], 0x7500000
	s_add_u32 s30, s0, 0x3200100
	v_lshl_add_u64 v[138:139], v[2:3], 0, s[4:5]
	v_lshlrev_b32_e32 v131, 2, v7
	v_or_b32_e32 v2, v160, v158
	v_and_b32_e32 v4, 3, v0
	s_addc_u32 s31, s1, 0
	v_sub_u32_e32 v2, v131, v2
	v_lshlrev_b32_e32 v140, 5, v4
	v_mov_b32_e32 v141, v133
	s_add_u32 s34, s0, 0x3200200
	v_lshlrev_b32_e32 v134, 3, v7
	v_mov_b32_e32 v135, v133
	v_cvt_f32_i32_e32 v161, v2
	v_and_b32_e32 v3, 7, v0
	v_lshl_add_u64 v[4:5], s[0:1], 0, v[140:141]
	s_mov_b64 s[4:5], 0xb500000
	s_addc_u32 s35, s1, 0
	v_and_b32_e32 v1, 63, v0
	v_lshlrev_b32_e32 v2, 4, v3
	v_lshl_add_u64 v[142:143], v[4:5], 0, s[4:5]
	v_lshlrev_b32_e32 v165, 5, v3
	s_movk_i32 s6, 0x4200
	v_and_b32_e32 v3, 64, v0
	v_lshl_add_u64 v[4:5], s[0:1], 0, v[134:135]
	s_mov_b64 s[0:1], 0xf500000
	v_lshrrev_b32_e32 v6, 6, v0
	v_lshrrev_b32_e32 v162, 3, v0
	v_lshrrev_b32_e32 v163, 2, v0
	v_cmp_eq_u32_e64 s[4:5], 0, v1
	s_add_i32 s3, 0, 0x11000
	v_mad_u32_u24 v1, v8, s6, 0
	v_cmp_ne_u32_e64 s[8:9], 0, v3
	v_lshlrev_b32_e32 v3, 2, v158
	v_lshl_add_u64 v[144:145], v[4:5], 0, s[0:1]
	v_lshl_add_u64 v[146:147], s[56:57], 0, v[136:137]
	v_mul_u32_u24_e32 v4, 0x210, v7
	s_add_i32 s44, 0, 0x11040
	s_mov_b32 s38, 0x400020c5
	s_mov_b32 s40, 2.0
	s_mov_b32 s42, 0x41900000
	s_mov_b32 s46, 0x42000000
	s_mov_b32 s52, 0x42080000
	s_mov_b32 s54, 0x42400000
	s_mov_b32 s56, 0x42480000
	v_writelane_b32 v244, s22, 13
	s_mov_b32 s37, 0
	v_lshl_add_u32 v141, v6, 2, s3
	v_mul_u32_u24_e32 v164, 0x110, v162
	v_mul_u32_u24_e32 v166, 0x88, v163
	v_cmp_eq_u32_e64 s[6:7], 0, v159
	v_mul_u32_u24_e32 v135, 0x110, v158
	v_mul_u32_u24_e32 v137, 0x88, v158
	v_add3_u32 v167, v1, v3, v4
	v_mov_b32_e32 v168, s44
	v_mov_b32_e32 v169, 0x260
	s_mov_b32 s39, 0x3fb8aa3b
	v_lshlrev_b32_e32 v148, 1, v2
	s_add_i32 s45, 0, 0x11010
	s_mov_b32 s41, 0x40400000
	s_mov_b32 s43, 0x41980000
	s_mov_b32 s47, 0x42040000
	s_mov_b32 s53, 0x420c0000
	s_mov_b32 s55, 0x42440000
	s_mov_b32 s57, 0x424c0000
	s_mov_b32 s80, 0xff800000
	s_mov_b32 s81, 0x800000
	v_mov_b32_e32 v170, 0x42800000
	v_mov_b32_e32 v171, 0x41880000
	v_mov_b32_e32 v172, 0xff800000
	v_mov_b32_e32 v150, 0x3727c5ac
	v_writelane_b32 v244, s23, 14
	s_branch .LBB0_337
	.p2align	6

; __device__ __forceinline__ void attn_phase(const bf16_t* __restrict__ Q, const bf16_t* __restrict__ Kb, const bf16_t* __restrict__ Vt, bf16_t* MIX, const float* subln, float lam, const unsigned* kmax2, unsigned* qctr, unsigned char* lds) {
;     ...
;             int* uq = (int*)(lds + 2 * BUF + 64);
;             __syncthreads();
;             if (tid == 0) uq[0] = (int)atomicAdd(qctr, 1u);
;             __syncthreads();
;             const int u = __builtin_amdgcn_readfirstlane(uq[0]);
;             if (u >= 1024) break;
;             const int hd = 7 - (u >> 7), b = u & 1, qblk = 63 - ((u & 127) >> 1);
;             const float slope2 = exp2f(-(float)(hd + 1)) * LOG2E;
;             const int q0 = qblk * 128, nt = 2 * qblk + 2, qw0 = q0 + qs * 32;
;             bf16x8 qf[2][2];
; #pragma unroll
;             for (int qb2 = 0; qb2 < 2; ++qb2)
; #pragma unroll
;                 for (int ks = 0; ks < 2; ++ks) qf[qb2][ks] = *(const bf16x8*)(Q + (size_t)(b * SEQ + qw0 + qb2 * 16 + fr) * 1024 + hd * 128 + mi * 64 + ks * 32 + fq * 8);
;             const float cb0 = slope2 * (float)(4 * fq - 32 * qs - fr), cb1 = cb0 - 16.f * slope2;
;             f32x4 o[8][2];
; #pragma unroll
;             for (int db = 0; db < 8; ++db) { o[db][0] = (f32x4){0.f, 0.f, 0.f, 0.f}; o[db][1] = (f32x4){0.f, 0.f, 0.f, 0.f}; }
;             bool first = true;
;             float mref[2] = {0.f, 0.f}, lrow[2] = {0.f, 0.f};
;     ...
;             int kt_w;
;             { float qn0 = 0.f, qn1 = 0.f;
; #pragma unroll
;               for (int ks = 0; ks < 2; ++ks) { const u32x4 w0 = __builtin_bit_cast(u32x4, qf[0][ks]), w1 = __builtin_bit_cast(u32x4, qf[1][ks]);
; #pragma unroll
;                   for (int e = 0; e < 4; ++e) { qn0 += bflo(w0[e]) * bflo(w0[e]) + bfhi(w0[e]) * bfhi(w0[e]); qn1 += bflo(w1[e]) * bflo(w1[e]) + bfhi(w1[e]) * bfhi(w1[e]); } }
;               const float qm = row16_max(fmaxf(rows4_sum(qn0), rows4_sum(qn1)));
;               const float bound = 2.002f * sqrtf(qm * __uint_as_float(kmax2[b * 16 + hd * 2 + mi])) + 152.f;
;               const float x = (float)(qw0 - 63) - bound / slope2;
;               kt_w = x > 0.f ? (int)(x * (1.f / 64.f)) : 0; }
;             kt_w = __builtin_amdgcn_readfirstlane(kt_w);
;     ...
;             const int kt_w = 0;
;     ...
;             const int krow = tid >> 3, kseg = tid & 7;
;             const int vrow = tid >> 2, vseg = tid & 3;
.LBB0_341:
	s_or_b64 exec, exec, s[10:11]
	s_waitcnt lgkmcnt(0)
	s_barrier
	ds_read_b32 v1, v168
	s_mov_b64 s[10:11], -1
	s_waitcnt lgkmcnt(0)
	v_readfirstlane_b32 s0, v1
	s_cmpk_gt_i32 s0, 0x3ff
	s_cbranch_scc1 .LBB0_336
	s_ashr_i32 s1, s0, 7
	s_sub_i32 s22, 7, s1
	s_sub_i32 s1, 8, s1
	v_cvt_f32_u32_e32 v1, s1
	s_and_b32 s1, s0, 1
	s_not_b32 s0, s0
	s_mov_b32 s10, 0x42fc0000
	s_bfe_u32 s0, s0, 0x60001
	v_cmp_lt_f32_e32 vcc, s10, v1
	s_and_b64 s[10:11], vcc, exec
	s_cselect_b32 s10, 0xffffffc0, 0
	v_lshl_or_b32 v174, s0, 7, v160
	s_lshl_b32 s23, s1, 13
	v_or3_b32 v173, v174, s23, v158
	s_lshl_b32 s36, s22, 8
	v_lshl_add_u64 v[2:3], v[138:139], 0, s[36:37]
	v_lshlrev_b32_e32 v132, 11, v173
	v_lshl_add_u64 v[4:5], v[2:3], 0, v[132:133]
	v_or_b32_e32 v132, 16, v173
	global_load_dwordx4 v[6:9], v[4:5], off
	global_load_dwordx4 v[10:13], v[4:5], off offset:64
	v_mov_b32_e32 v5, v133
	v_lshlrev_b32_e32 v4, 11, v132
	v_lshl_add_u64 v[2:3], v[2:3], 0, v[4:5]
	global_load_dwordx4 v[18:21], v[2:3], off
	global_load_dwordx4 v[22:25], v[2:3], off offset:64
	s_lshl_b32 s11, s1, 4
	s_lshl_b32 s36, s22, 1
	s_add_i32 s36, s36, s11
	v_mov_b32_e32 v3, v133
	v_or_b32_e32 v2, s36, v159
	v_lshl_add_u64 v[2:3], v[2:3], 2, s[30:31]
	global_load_dword v2, v[2:3], off
	v_cndmask_b32_e32 v14, 0, v170, vcc
	v_sub_f32_e32 v1, v14, v1
	s_mov_b32 s11, 0xf800000
	v_exp_f32_e32 v1, v1
	s_barrier
	s_waitcnt vmcnt(4)
	v_and_b32_e32 v4, 0xffff0000, v6
	v_and_b32_e32 v14, 0xffff0000, v7
	v_lshlrev_b32_e32 v3, 16, v6
	v_lshlrev_b32_e32 v5, 16, v7
	v_and_b32_e32 v16, 0xffff0000, v8
	v_mul_f32_e32 v4, v4, v4
	v_mul_f32_e32 v14, v14, v14
	v_lshlrev_b32_e32 v15, 16, v8
	v_and_b32_e32 v26, 0xffff0000, v9
	v_mul_f32_e32 v16, v16, v16
	v_fmac_f32_e32 v4, v3, v3
	s_waitcnt vmcnt(2)
	v_and_b32_e32 v33, 0xffff0000, v18
	v_fmac_f32_e32 v14, v5, v5
	v_lshlrev_b32_e32 v17, 16, v9
	v_and_b32_e32 v28, 0xffff0000, v10
	v_mul_f32_e32 v26, v26, v26
	v_lshlrev_b32_e32 v3, 16, v18
	v_and_b32_e32 v34, 0xffff0000, v19
	v_fmac_f32_e32 v16, v15, v15
	v_mul_f32_e32 v33, v33, v33
	v_add_f32_e32 v4, v4, v14
	v_lshlrev_b32_e32 v27, 16, v10
	v_and_b32_e32 v30, 0xffff0000, v11
	v_mul_f32_e32 v28, v28, v28
	v_lshlrev_b32_e32 v5, 16, v19
	v_fmac_f32_e32 v26, v17, v17
	v_mul_f32_e32 v14, v34, v34
	v_fmac_f32_e32 v33, v3, v3
	v_add_f32_e32 v3, v16, v4
	v_lshlrev_b32_e32 v29, 16, v11
	v_and_b32_e32 v32, 0xffff0000, v12
	v_mul_f32_e32 v30, v30, v30
	v_fmac_f32_e32 v28, v27, v27
	v_fmac_f32_e32 v14, v5, v5
	v_add_f32_e32 v3, v26, v3
	v_lshlrev_b32_e32 v31, 16, v12
	v_mul_f32_e32 v32, v32, v32
	v_fmac_f32_e32 v30, v29, v29
	v_add_f32_e32 v4, v33, v14
	v_add_f32_e32 v3, v28, v3
	v_and_b32_e32 v14, 0xffff0000, v13
	v_and_b32_e32 v35, 0xffff0000, v20
	v_fmac_f32_e32 v32, v31, v31
	v_add_f32_e32 v3, v30, v3
	v_lshlrev_b32_e32 v5, 16, v13
	v_mul_f32_e32 v14, v14, v14
	v_lshlrev_b32_e32 v15, 16, v20
	v_and_b32_e32 v36, 0xffff0000, v21
	v_mul_f32_e32 v34, v35, v35
	v_add_f32_e32 v3, v32, v3
	v_fmac_f32_e32 v14, v5, v5
	v_lshlrev_b32_e32 v17, 16, v21
	s_waitcnt vmcnt(1)
	v_and_b32_e32 v37, 0xffff0000, v22
	v_mul_f32_e32 v35, v36, v36
	v_fmac_f32_e32 v34, v15, v15
	v_add_f32_e32 v3, v14, v3
	v_and_b32_e32 v14, 0xffff0000, v25
	v_lshlrev_b32_e32 v27, 16, v22
	v_and_b32_e32 v38, 0xffff0000, v23
	v_mul_f32_e32 v36, v37, v37
	v_fmac_f32_e32 v35, v17, v17
	v_add_f32_e32 v4, v34, v4
	v_lshlrev_b32_e32 v5, 16, v25
	v_mul_f32_e32 v14, v14, v14
	v_lshlrev_b32_e32 v29, 16, v23
	v_and_b32_e32 v39, 0xffff0000, v24
	v_mul_f32_e32 v37, v38, v38
	v_fmac_f32_e32 v36, v27, v27
	v_add_f32_e32 v4, v35, v4
	v_fmac_f32_e32 v14, v5, v5
	v_mov_b32_e32 v5, v3
	v_lshlrev_b32_e32 v31, 16, v24
	v_mul_f32_e32 v38, v39, v39
	v_fmac_f32_e32 v37, v29, v29
	v_add_f32_e32 v4, v36, v4
	v_permlane16_swap_b32_e32 v3, v5
	v_fmac_f32_e32 v38, v31, v31
	v_add_f32_e32 v4, v37, v4
	v_add_f32_e32 v3, v3, v5
	v_add_f32_e32 v4, v38, v4
	v_mov_b32_e32 v5, v3
	v_add_f32_e32 v4, v14, v4
	s_nop 0
	v_permlane32_swap_b32_e32 v3, v5
	v_add_f32_e32 v3, v3, v5
	v_mov_b32_e32 v5, v4
	s_nop 1
	v_permlane16_swap_b32_e32 v4, v5
	v_add_f32_e32 v4, v4, v5
	v_mov_b32_e32 v5, v4
	s_nop 1
	v_permlane32_swap_b32_e32 v4, v5
	v_add_f32_e32 v4, v4, v5
	v_max_f32_e32 v3, v3, v4
	s_nop 1
	v_mov_b32_dpp v4, v3 quad_perm:[1,0,3,2] row_mask:0xf bank_mask:0xf bound_ctrl:1
	v_max_f32_e32 v4, v4, v4
	v_max_f32_e32 v3, v3, v4
	s_nop 1
	v_mov_b32_dpp v4, v3 quad_perm:[2,3,0,1] row_mask:0xf bank_mask:0xf bound_ctrl:1
	v_max_f32_e32 v4, v4, v4
	v_max_f32_e32 v3, v3, v4
	s_nop 1
	v_mov_b32_dpp v4, v3 row_half_mirror row_mask:0xf bank_mask:0xf bound_ctrl:1
	v_max_f32_e32 v4, v4, v4
	v_max_f32_e32 v3, v3, v4
	s_nop 1
	v_mov_b32_dpp v4, v3 row_mirror row_mask:0xf bank_mask:0xf bound_ctrl:1
	v_max_f32_e32 v4, v4, v4
	v_max_f32_e32 v3, v3, v4
	s_waitcnt vmcnt(0)
	v_mul_f32_e32 v2, v2, v3
	v_mul_f32_e32 v3, 0x4f800000, v2
	v_cmp_gt_f32_e32 vcc, s11, v2
	s_nop 1
	v_cndmask_b32_e32 v2, v2, v3, vcc
	v_sqrt_f32_e32 v4, v2
	v_ldexp_f32 v3, v1, s10
	v_add_u32_e32 v1, -1, v4
	v_fma_f32 v5, -v1, v4, v2
	v_cmp_ge_f32_e64 s[10:11], 0, v5
	v_add_u32_e32 v5, 1, v4
	s_nop 0
	v_cndmask_b32_e64 v1, v4, v1, s[10:11]
	v_fma_f32 v4, -v5, v4, v2
	v_cmp_lt_f32_e64 s[10:11], 0, v4
	s_nop 1
	v_cndmask_b32_e64 v1, v1, v5, s[10:11]
	v_mul_f32_e32 v4, 0x37800000, v1
	v_cndmask_b32_e32 v1, v1, v4, vcc
	v_cmp_class_f32_e32 vcc, v2, v169
	v_subrev_u32_e32 v4, 63, v174
	v_cvt_f32_i32_e32 v4, v4
	v_cndmask_b32_e32 v2, v1, v2, vcc
	v_pk_mul_f32 v[152:153], v[2:3], s[38:39]
	s_nop 0
	v_add_f32_e32 v1, 0x43180000, v152
	v_div_scale_f32 v2, s[10:11], v153, v153, v1
	v_rcp_f32_e32 v3, v2
	s_nop 0
	v_fma_f32 v5, -v2, v3, 1.0
	v_fmac_f32_e32 v3, v5, v3
	v_div_scale_f32 v5, vcc, v1, v153, v1
	v_mul_f32_e32 v14, v5, v3
	v_fma_f32 v15, -v2, v14, v5
	v_fmac_f32_e32 v14, v15, v3
	v_fma_f32 v2, -v2, v14, v5
	v_div_fmas_f32 v2, v2, v3, v14
	v_div_fixup_f32 v1, v2, v153, v1
	v_sub_f32_e32 v1, v4, v1
	v_mul_f32_e32 v2, 0x3c800000, v1
	v_cvt_i32_f32_e32 v2, v2
	v_cmp_lt_f32_e32 vcc, 0, v1
	s_nop 1
	v_cndmask_b32_e32 v1, 0, v2, vcc
	s_nop 0
	v_readfirstlane_b32 s96, v1
	s_and_saveexec_b64 s[10:11], s[4:5]
	s_nop 0
	v_mov_b32_e32 v1, s96
	ds_write_b32 v141, v1
	s_or_b64 exec, exec, s[10:11]
	v_or_b32_e32 v1, s23, v162
	s_lshl_b32 s10, s22, 7
	v_lshlrev_b32_e32 v2, 11, v1
	v_mov_b32_e32 v3, v133
	v_lshl_add_u64 v[2:3], s[28:29], 0, v[2:3]
	s_lshl_b32 s36, s10, 1
	v_lshl_or_b32 v1, s1, 10, v163
	v_lshl_add_u64 v[2:3], v[2:3], 0, s[36:37]
	v_mov_b32_e32 v149, v133
	v_add_u32_e32 v26, s10, v1
	v_mov_b32_e32 v1, s3
	v_lshl_add_u64 v[154:155], v[2:3], 0, v[148:149]
	s_waitcnt lgkmcnt(0)
	s_barrier
; __device__ __forceinline__ void attn_phase(const bf16_t* __restrict__ Q, const bf16_t* __restrict__ Kb, const bf16_t* __restrict__ Vt, bf16_t* MIX, const float* subln, float lam, const unsigned* kmax2, unsigned* qctr, unsigned char* lds) {
;     ...
;             const float cb0 = slope2 * (float)(4 * fq - 32 * qs - fr), cb1 = cb0 - 16.f * slope2;
;             f32x4 o[8][2];
; #pragma unroll
;             for (int db = 0; db < 8; ++db) { o[db][0] = (f32x4){0.f, 0.f, 0.f, 0.f}; o[db][1] = (f32x4){0.f, 0.f, 0.f, 0.f}; }
;             bool first = true;
;             float mref[2] = {0.f, 0.f}, lrow[2] = {0.f, 0.f};
;     ...
;             int kt_w;
;             { float qn0 = 0.f, qn1 = 0.f;
; #pragma unroll
;               for (int ks = 0; ks < 2; ++ks) { const u32x4 w0 = __builtin_bit_cast(u32x4, qf[0][ks]), w1 = __builtin_bit_cast(u32x4, qf[1][ks]);
; #pragma unroll
;                   for (int e = 0; e < 4; ++e) { qn0 += bflo(w0[e]) * bflo(w0[e]) + bfhi(w0[e]) * bfhi(w0[e]); qn1 += bflo(w1[e]) * bflo(w1[e]) + bfhi(w1[e]) * bfhi(w1[e]); } }
;               const float qm = row16_max(fmaxf(rows4_sum(qn0), rows4_sum(qn1)));
;               const float bound = 2.002f * sqrtf(qm * __uint_as_float(kmax2[b * 16 + hd * 2 + mi])) + 152.f;
;               const float x = (float)(qw0 - 63) - bound / slope2;
;               kt_w = x > 0.f ? (int)(x * (1.f / 64.f)) : 0; }
;             kt_w = __builtin_amdgcn_readfirstlane(kt_w);
;     ...
;             const int kt_w = 0;
;     ...
;             const int krow = tid >> 3, kseg = tid & 7;
;             const int vrow = tid >> 2, vseg = tid & 3;
;             const bf16_t* kg = Kb + (size_t)(b * SEQ + krow) * 1024 + hd * 128 + kseg * 16;
;             const bf16_t* vg = Vt + (size_t)(b * 1024 + hd * 128 + vrow) * SEQ + vseg * 16;
;             u32x4 kr0, kr1, vr0, vr1;
;             __syncthreads();
;             int kt0 = 0;
;     ...
;             { int* kx = (int*)(lds + 2 * BUF); if (lane == 0) kx[wave] = kt_w; __syncthreads();
;               kt0 = min(min(min(kx[0], kx[1]), min(kx[2], kx[3])), min(min(kx[4], kx[5]), min(kx[6], kx[7]))); kt0 = __builtin_amdgcn_readfirstlane(kt0); }
;     ...
;             { const bf16_t* kg0 = kg + (size_t)(kt0 * 64) * 1024; const bf16_t* vg0 = vg + kt0 * 64;
;               kr0 = *(const u32x4*)(kg0); kr1 = *(const u32x4*)(kg0 + 8); vr0 = *(const u32x4*)(vg0); vr1 = *(const u32x4*)(vg0 + 8); }
	ds_read_b128 v[2:5], v1
	v_mov_b32_e32 v1, s45
	ds_read_b128 v[14:17], v1
	v_mov_b32_e32 v27, v133
	v_lshlrev_b64 v[26:27], 14, v[26:27]
	s_waitcnt lgkmcnt(1)
	v_min_i32_e32 v1, v2, v3
	v_min_i32_e32 v2, v4, v5
	s_waitcnt lgkmcnt(0)
	v_min_i32_e32 v3, v16, v17
	v_min3_i32 v3, v14, v15, v3
	v_min3_i32 v1, v1, v2, v3
	v_lshl_add_u64 v[156:157], v[142:143], 0, v[26:27]
	v_readfirstlane_b32 s1, v1
	s_lshl_b32 s64, s1, 6
	s_ashr_i32 s65, s64, 31
	s_lshl_b64 s[10:11], s[64:65], 11
	v_lshl_add_u64 v[2:3], v[154:155], 0, s[10:11]
	global_load_dwordx4 v[82:85], v[2:3], off offset:16
	global_load_dwordx4 v[86:89], v[2:3], off
	v_lshl_add_u64 v[2:3], s[64:65], 1, v[156:157]
	global_load_dwordx4 v[90:93], v[2:3], off
	global_load_dwordx4 v[94:97], v[2:3], off offset:16
	s_lshl_b32 s97, s0, 1
	s_add_i32 s97, s97, 2
	s_bitcmp1_b32 s1, 0
	s_cselect_b32 s10, 0x8800, 0
	s_add_i32 s10, s10, 0
	v_add3_u32 v1, s10, v164, v165
	v_add3_u32 v2, s10, v166, v140
	s_cmp_ge_i32 s1, s97
	v_add_u32_e32 v3, 0x4400, v2
	v_add_u32_e32 v2, 0x4410, v2
	s_waitcnt vmcnt(2)
	ds_write_b128 v1, v[86:89]
	ds_write_b128 v1, v[82:85] offset:16
	s_waitcnt vmcnt(1)
	ds_write2_b64 v3, v[90:91], v[92:93] offset1:1
	s_waitcnt vmcnt(0)
	ds_write2_b64 v2, v[94:95], v[96:97] offset1:1
	s_waitcnt lgkmcnt(0)
	s_barrier
	s_cbranch_scc1 .LBB0_370
	v_mov_b32_e32 v4, v133
	v_mov_b32_e32 v5, v133
	v_mul_f32_e32 v149, 0x41800000, v153
	v_or_b32_e32 v178, v174, v158
	s_lshl_b32 s0, s0, 7
	v_mov_b32_e32 v2, v133
	v_mov_b32_e32 v3, v133
	v_mov_b32_e32 v182, 0
	v_mov_b64_e32 v[52:53], v[4:5]
	v_mov_b64_e32 v[16:17], v[4:5]
	v_mov_b64_e32 v[56:57], v[4:5]
	v_mov_b64_e32 v[28:29], v[4:5]
	v_mov_b64_e32 v[60:61], v[4:5]
	v_mov_b64_e32 v[32:33], v[4:5]
	v_mov_b64_e32 v[64:65], v[4:5]
	v_mov_b64_e32 v[36:37], v[4:5]
	v_mov_b64_e32 v[68:69], v[4:5]
	v_mov_b64_e32 v[40:41], v[4:5]
	v_mov_b64_e32 v[72:73], v[4:5]
	v_mov_b64_e32 v[44:45], v[4:5]
	v_mov_b64_e32 v[76:77], v[4:5]
	v_mov_b64_e32 v[48:49], v[4:5]
	v_mov_b64_e32 v[80:81], v[4:5]
	v_mul_f32_e32 v175, v153, v161
	v_fma_f32 v176, v153, v161, -v149
	v_or_b32_e32 v177, 31, v174
	v_or_b32_e32 v179, 16, v178
	v_add_u32_e32 v180, 14, v178
	v_add_u32_e32 v181, 13, v178
	s_sub_i32 s22, 0, s0
	s_mov_b64 s[66:67], -1
	v_mov_b64_e32 v[50:51], v[2:3]
	v_mov_b64_e32 v[14:15], v[2:3]
	v_mov_b64_e32 v[54:55], v[2:3]
	v_mov_b64_e32 v[26:27], v[2:3]
	v_mov_b64_e32 v[58:59], v[2:3]
	v_mov_b64_e32 v[30:31], v[2:3]
	v_mov_b64_e32 v[62:63], v[2:3]
	v_mov_b64_e32 v[34:35], v[2:3]
	v_mov_b64_e32 v[66:67], v[2:3]
	v_mov_b64_e32 v[38:39], v[2:3]
	v_mov_b64_e32 v[70:71], v[2:3]
	v_mov_b64_e32 v[42:43], v[2:3]
	v_mov_b64_e32 v[74:75], v[2:3]
	v_mov_b64_e32 v[46:47], v[2:3]
	v_mov_b64_e32 v[78:79], v[2:3]
	v_mov_b32_e32 v183, 0
	v_mov_b32_e32 v152, 0
	v_mov_b32_e32 v1, v182
	.p2align	6

; __device__ __forceinline__ void attn_phase(const bf16_t* __restrict__ Q, const bf16_t* __restrict__ Kb, const bf16_t* __restrict__ Vt, bf16_t* MIX, const float* subln, float lam, const unsigned* kmax2, unsigned* qctr, unsigned char* lds) {
;     ...
;                     const bool diag = (k0 + 63 > qw0);
; #pragma unroll
;                     for (int qb2 = 0; qb2 < 2; ++qb2) {
;                         if (diag) { const int qabs = qw0 + qb2 * 16 + fr;
; #pragma unroll
;                             for (int kb = 0; kb < 4; ++kb)
; #pragma unroll
;                                 for (int j = 0; j < 4; ++j) if (k0 + kb * 16 + 4 * fq + j > qabs) s[qb2][kb][j] = NEG_INF; }
.LBB0_354:
	s_andn2_saveexec_b64 s[94:95], s[94:95]
	s_cbranch_execnz .LBB0_369
	.p2align	6
.LBB0_355:
	s_or_b64 exec, exec, s[94:95]
	s_and_saveexec_b64 s[94:95], s[10:11]
	s_cbranch_execz .LBB0_357
	.p2align	6
.LBB0_356:
	v_mov_b32_e32 v196, s80
	v_cmp_gt_i32_e32 vcc, v194, v179
	s_nop 1
	v_cndmask_b32_e32 v195, v102, v196, vcc
	v_cmp_lt_i32_e32 vcc, v194, v179
	s_nop 1
	v_cndmask_b32_e32 v102, v195, v102, vcc
	v_cndmask_b32_e32 v103, v172, v103, vcc
	v_cmp_le_i32_e32 vcc, v194, v180
	s_nop 1
	v_cndmask_b32_e32 v104, v172, v104, vcc
	v_cmp_le_i32_e32 vcc, v194, v181
	s_nop 1
	v_cndmask_b32_e32 v105, v172, v105, vcc
	v_cmp_gt_i32_e32 vcc, v194, v178
	s_nop 1
	v_cndmask_b32_e32 v195, v118, v196, vcc
	v_cmp_lt_i32_e32 vcc, v194, v178
	s_nop 1
	v_cndmask_b32_e32 v118, v195, v118, vcc
	v_cndmask_b32_e32 v119, v172, v119, vcc
	v_cmp_le_i32_e32 vcc, v193, v178
	s_nop 1
	v_cndmask_b32_e32 v120, v172, v120, vcc
	v_cmp_le_i32_e32 vcc, v192, v178
	v_mov_b32_e32 v192, s80
	s_nop 0
	v_cndmask_b32_e32 v121, v172, v121, vcc
	v_cmp_gt_i32_e32 vcc, v191, v178
	s_nop 1
	v_cndmask_b32_e32 v98, v98, v192, vcc
	v_cmp_le_i32_e32 vcc, v190, v178
	s_nop 1
	v_cndmask_b32_e32 v99, v172, v99, vcc
	v_cmp_le_i32_e32 vcc, v189, v178
	s_nop 1
	v_cndmask_b32_e32 v100, v172, v100, vcc
	v_cmp_le_i32_e32 vcc, v188, v178
	v_mov_b32_e32 v188, s80
	s_nop 0
	v_cndmask_b32_e32 v101, v172, v101, vcc
	v_cmp_gt_i32_e32 vcc, v187, v178
	s_nop 1
	v_cndmask_b32_e32 v106, v106, v188, vcc
	v_cmp_le_i32_e32 vcc, v186, v178
	s_nop 1
	v_cndmask_b32_e32 v107, v172, v107, vcc
	v_cmp_le_i32_e32 vcc, v185, v178
	s_nop 1
	v_cndmask_b32_e32 v108, v172, v108, vcc
	v_cmp_le_i32_e32 vcc, v184, v178
	s_nop 1
	v_cndmask_b32_e32 v109, v172, v109, vcc
	.p2align	6

; #define PG8_STAGE(bufoff, gbase, voff) do { _Pragma("unroll") for (int _i = 0; _i < 2; ++_i) \
;         __builtin_amdgcn_global_load_lds((const unsigned*)((const char*)(gbase) + (voff)[_i]), (PG8_LAS unsigned*)(lds + (bufoff) + ldsw + _i * 8192), 16, 0, 0); } while (0)
; #define PG8_WAIT_V(n) asm volatile("s_waitcnt vmcnt(" #n ")" ::: "memory")
; #define PG8_BAR __builtin_amdgcn_s_barrier()
; template <class Epi, class Sched, bool ALIGN_EPI = false, bool SP2 = false>
; __device__ __forceinline__ void gemm_phase(PG8_LAS unsigned char* lds, const Gemm g, const Sched& S, const Epi& E) {
;     ...
;     for (int i = 0; i < 2; ++i) { int R, C; stage_rc(tid * 16 + i * 8192, R, C); const int Rb = Epi::PERM ? ((R & ~31) + perm32(R & 31)) : R;
;         voffA[i] = (unsigned)(R * K + C) * 2u; voffB[i] = (unsigned)(Rb * K + C) * 2u; }
;     const size_t kstep = (size_t)(BK * 2);
;     const size_t hstep = (size_t)HALF * K * 2;
;     const size_t tstep = 2 * hstep;
;     const unsigned ldsw = (unsigned)wid * 1024u;
;     const int aoff = lds_byte(wr * 64 + fr, fq * 8), boff = lds_byte(wc * 32 + fr, fq * 8);
;     ...
;         if (wr == 1) PG8_BAR;
;         PG8_WAIT_V(2); PG8_BAR;
;         PG8_STAGE(PG8_SB(1, 0), cB + kstep, voffB); PG8_STAGE(PG8_SA(1, 0), cA + kstep, voffA); PG8_STAGE(PG8_SB(1, 1), cB + hstep + kstep, voffB);
;         PG8_WAIT_V(6); PG8_BAR;
.LBB0_482:
	s_add_u32 s18, s6, 0xf500000
	s_mov_b64 s[20:21], 0x80
	s_addc_u32 s19, s7, 0
	s_add_i32 m0, s39, 0x18000
	v_lshl_add_u64 v[10:11], v[10:11], 0, s[20:21]
	s_waitcnt vmcnt(2)
	s_barrier
	global_load_lds_dwordx4 v[10:11], off
	v_lshl_add_u64 v[6:7], v[6:7], 0, s[20:21]
	s_add_i32 m0, s39, 0x1a000
	s_add_i32 s46, s39, 0x8000
	global_load_lds_dwordx4 v[6:7], off
	v_lshl_add_u64 v[6:7], v[8:9], 0, s[20:21]
	s_mov_b32 m0, s46
	s_add_i32 s47, s39, 0xa000
	global_load_lds_dwordx4 v[6:7], off
	v_lshl_add_u64 v[6:7], v[12:13], 0, s[20:21]
	s_mov_b32 m0, s47
	v_lshl_add_u64 v[4:5], v[4:5], 0, s[20:21]
	global_load_lds_dwordx4 v[6:7], off
	s_add_i32 m0, s39, 0x1c000
	v_lshl_add_u64 v[2:3], v[2:3], 0, s[20:21]
	global_load_lds_dwordx4 v[4:5], off
	s_add_i32 m0, s39, 0x1e000
	s_lshr_b32 s5, s5, 26
	global_load_lds_dwordx4 v[2:3], off
	v_and_b32_e32 v2, 15, v0
	s_add_i32 s5, s4, s5
	v_lshlrev_b32_e32 v3, 1, v18
	v_lshlrev_b32_e32 v4, 2, v0
	s_ashr_i32 s52, s5, 6
	v_lshl_or_b32 v1, s25, 6, v2
	v_lshl_or_b32 v2, v2, 6, v3
	s_lshl_b32 s5, s25, 13
	v_and_b32_e32 v4, 32, v4
	v_bitop3_b32 v5, v2, s5, v4 bitop3:0xde
	s_lshl_b32 s5, s23, 5
	s_and_b32 s5, s5, 0x60
	v_lshlrev_b32_e32 v2, 6, v0
	s_movk_i32 s6, 0x3c0
	v_and_or_b32 v2, v2, s6, v3
	s_lshl_b32 s6, s5, 7
	v_bitop3_b32 v150, s6, v2, v4 bitop3:0xf6
	v_add_u32_e32 v2, v19, v16
	v_mul_lo_u32 v2, s4, v2
	v_lshlrev_b32_e32 v2, 1, v2
	v_add3_u32 v2, v14, v2, v15
	v_mov_b32_e32 v3, v133
	s_cmp_gt_i32 s4, 63
	v_lshl_add_u64 v[138:139], s[12:13], 0, v[2:3]
	v_add_u32_e32 v2, v17, v16
	s_sext_i32_i8 s1, s22
	s_cselect_b64 s[22:23], -1, 0
	s_add_i32 s44, s52, -2
	v_mul_lo_u32 v2, s4, v2
	s_waitcnt vmcnt(6)
	s_cmpk_lt_u32 s24, 0x100
	v_lshlrev_b32_e32 v2, 1, v2
	s_cselect_b64 s[24:25], -1, 0
	v_add3_u32 v2, v14, v2, v15
	s_add_i32 s54, 0, 0x10000
	s_add_i32 s55, 0, 0x14000
	s_ashr_i32 s45, s82, 31
	s_mov_b32 s53, s82
	s_waitcnt vmcnt(0)
	v_or_b32_e32 v151, s5, v18
	v_lshl_add_u64 v[140:141], s[12:13], 0, v[2:3]
	v_mov_b64_e32 v[142:143], 0x100
	v_mov_b64_e32 v[144:145], 0xff
	v_add_u32_e32 v152, s54, v150
	v_add_u32_e32 v153, s55, v150
	v_add_u32_e32 v154, 0, v5
	s_barrier
	s_branch .LBB0_485
	.p2align	6

; #define PG8_BAR __builtin_amdgcn_s_barrier()
; template <class Epi, class Sched, bool ALIGN_EPI = false, bool SP2 = false>
; __device__ __forceinline__ void gemm_phase(PG8_LAS unsigned char* lds, const Gemm g, const Sched& S, const Epi& E) {
;     ...
; #pragma unroll
;         for (int a = 0; a < 2; ++a)
; #pragma unroll
;             for (int b = 0; b < 2; ++b)
; #pragma unroll
;                 for (int m = 0; m < 4; ++m)
; #pragma unroll
;                     for (int n = 0; n < 2; ++n) acc[a][b][m][n] = (f32x4){0.f, 0.f, 0.f, 0.f};
;         cur = nxt; cA = nA; cB = nB; ++ui;
;         if constexpr (ALIGN_EPI) { if (wr == 1) PG8_BAR; }
.LBB0_495:
	v_mov_b32_e32 v129, 0
	s_andn2_b64 vcc, exec, s[22:23]
	v_mov_b32_e32 v128, v129
	v_mov_b32_e32 v127, v129
	v_mov_b32_e32 v126, v129
	v_mov_b32_e32 v125, v129
	v_mov_b32_e32 v124, v129
	v_mov_b32_e32 v123, v129
	v_mov_b32_e32 v122, v129
	v_mov_b32_e32 v113, v129
	v_mov_b32_e32 v112, v129
	v_mov_b32_e32 v111, v129
	v_mov_b32_e32 v110, v129
	v_mov_b32_e32 v109, v129
	v_mov_b32_e32 v108, v129
	v_mov_b32_e32 v107, v129
	v_mov_b32_e32 v106, v129
	v_mov_b32_e32 v97, v129
	v_mov_b32_e32 v96, v129
	v_mov_b32_e32 v95, v129
	v_mov_b32_e32 v94, v129
	v_mov_b32_e32 v93, v129
	v_mov_b32_e32 v92, v129
	v_mov_b32_e32 v91, v129
	v_mov_b32_e32 v90, v129
	v_mov_b32_e32 v81, v129
	v_mov_b32_e32 v80, v129
	v_mov_b32_e32 v79, v129
	v_mov_b32_e32 v78, v129
	v_mov_b32_e32 v77, v129
	v_mov_b32_e32 v76, v129
	v_mov_b32_e32 v75, v129
	v_mov_b32_e32 v74, v129
	v_mov_b32_e32 v121, v129
	v_mov_b32_e32 v120, v129
	v_mov_b32_e32 v119, v129
	v_mov_b32_e32 v118, v129
	v_mov_b32_e32 v117, v129
	v_mov_b32_e32 v116, v129
	v_mov_b32_e32 v115, v129
	v_mov_b32_e32 v114, v129
	v_mov_b32_e32 v105, v129
	v_mov_b32_e32 v104, v129
	v_mov_b32_e32 v103, v129
	v_mov_b32_e32 v102, v129
	v_mov_b32_e32 v101, v129
	v_mov_b32_e32 v100, v129
	v_mov_b32_e32 v99, v129
	v_mov_b32_e32 v98, v129
	v_mov_b32_e32 v89, v129
	v_mov_b32_e32 v88, v129
	v_mov_b32_e32 v87, v129
	v_mov_b32_e32 v86, v129
	v_mov_b32_e32 v85, v129
	v_mov_b32_e32 v84, v129
	v_mov_b32_e32 v83, v129
	v_mov_b32_e32 v82, v129
	v_mov_b32_e32 v73, v129
	v_mov_b32_e32 v72, v129
	v_mov_b32_e32 v71, v129
	v_mov_b32_e32 v70, v129
	v_mov_b32_e32 v69, v129
	v_mov_b32_e32 v68, v129
	v_mov_b32_e32 v67, v129
	v_mov_b32_e32 v66, v129
	v_mov_b32_e32 v65, v129
	v_mov_b32_e32 v64, v129
	v_mov_b32_e32 v63, v129
	v_mov_b32_e32 v62, v129
	v_mov_b32_e32 v61, v129
	v_mov_b32_e32 v60, v129
	v_mov_b32_e32 v59, v129
	v_mov_b32_e32 v58, v129
	v_mov_b32_e32 v49, v129
	v_mov_b32_e32 v48, v129
	v_mov_b32_e32 v47, v129
	v_mov_b32_e32 v46, v129
	v_mov_b32_e32 v45, v129
	v_mov_b32_e32 v44, v129
	v_mov_b32_e32 v43, v129
	v_mov_b32_e32 v42, v129
	v_mov_b32_e32 v33, v129
	v_mov_b32_e32 v32, v129
	v_mov_b32_e32 v31, v129
	v_mov_b32_e32 v30, v129
	v_mov_b32_e32 v29, v129
	v_mov_b32_e32 v28, v129
	v_mov_b32_e32 v27, v129
	v_mov_b32_e32 v26, v129
	v_mov_b32_e32 v17, v129
	v_mov_b32_e32 v16, v129
	v_mov_b32_e32 v15, v129
	v_mov_b32_e32 v14, v129
	v_mov_b32_e32 v13, v129
	v_mov_b32_e32 v12, v129
	v_mov_b32_e32 v11, v129
	v_mov_b32_e32 v10, v129
	v_mov_b32_e32 v57, v129
	v_mov_b32_e32 v56, v129
	v_mov_b32_e32 v55, v129
	v_mov_b32_e32 v54, v129
	v_mov_b32_e32 v53, v129
	v_mov_b32_e32 v52, v129
	v_mov_b32_e32 v51, v129
	v_mov_b32_e32 v50, v129
	v_mov_b32_e32 v41, v129
	v_mov_b32_e32 v40, v129
	v_mov_b32_e32 v39, v129
	v_mov_b32_e32 v38, v129
	v_mov_b32_e32 v37, v129
	v_mov_b32_e32 v36, v129
	v_mov_b32_e32 v35, v129
	v_mov_b32_e32 v34, v129
	v_mov_b32_e32 v25, v129
	v_mov_b32_e32 v24, v129
	v_mov_b32_e32 v23, v129
	v_mov_b32_e32 v22, v129
	v_mov_b32_e32 v21, v129
	v_mov_b32_e32 v20, v129
	v_mov_b32_e32 v19, v129
	v_mov_b32_e32 v18, v129
	v_mov_b32_e32 v9, v129
	v_mov_b32_e32 v8, v129
	v_mov_b32_e32 v7, v129
	v_mov_b32_e32 v6, v129
	v_mov_b32_e32 v5, v129
	v_mov_b32_e32 v4, v129
	v_mov_b32_e32 v3, v129
	v_mov_b32_e32 v2, v129
	s_cbranch_vccnz .LBB0_498
	s_add_u32 s58, s30, 0x100
	s_addc_u32 s59, s31, 0
	s_add_u32 s30, s34, 0x80
	v_mov_b32_e32 v2, 0
	s_addc_u32 s31, s35, 0
	s_mov_b32 s34, 0
	v_mov_b32_e32 v3, v2
	v_mov_b32_e32 v4, v2
	v_mov_b32_e32 v5, v2
	v_mov_b32_e32 v6, v2
	v_mov_b32_e32 v7, v2
	v_mov_b32_e32 v8, v2
	v_mov_b32_e32 v9, v2
	v_mov_b32_e32 v18, v2
	v_mov_b32_e32 v19, v2
	v_mov_b32_e32 v20, v2
	v_mov_b32_e32 v21, v2
	v_mov_b32_e32 v22, v2
	v_mov_b32_e32 v23, v2
	v_mov_b32_e32 v24, v2
	v_mov_b32_e32 v25, v2
	v_mov_b32_e32 v34, v2
	v_mov_b32_e32 v35, v2
	v_mov_b32_e32 v36, v2
	v_mov_b32_e32 v37, v2
	v_mov_b32_e32 v38, v2
	v_mov_b32_e32 v39, v2
	v_mov_b32_e32 v40, v2
	v_mov_b32_e32 v41, v2
	v_mov_b32_e32 v50, v2
	v_mov_b32_e32 v51, v2
	v_mov_b32_e32 v52, v2
	v_mov_b32_e32 v53, v2
	v_mov_b32_e32 v54, v2
	v_mov_b32_e32 v55, v2
	v_mov_b32_e32 v56, v2
	v_mov_b32_e32 v57, v2
	v_mov_b32_e32 v10, v2
	v_mov_b32_e32 v11, v2
	v_mov_b32_e32 v12, v2
	v_mov_b32_e32 v13, v2
	v_mov_b32_e32 v14, v2
	v_mov_b32_e32 v15, v2
	v_mov_b32_e32 v16, v2
	v_mov_b32_e32 v17, v2
	v_mov_b32_e32 v26, v2
	v_mov_b32_e32 v27, v2
	v_mov_b32_e32 v28, v2
	v_mov_b32_e32 v29, v2
	v_mov_b32_e32 v30, v2
	v_mov_b32_e32 v31, v2
	v_mov_b32_e32 v32, v2
	v_mov_b32_e32 v33, v2
	v_mov_b32_e32 v42, v2
	v_mov_b32_e32 v43, v2
	v_mov_b32_e32 v44, v2
	v_mov_b32_e32 v45, v2
	v_mov_b32_e32 v46, v2
	v_mov_b32_e32 v47, v2
	v_mov_b32_e32 v48, v2
	v_mov_b32_e32 v49, v2
	v_mov_b32_e32 v58, v2
	v_mov_b32_e32 v59, v2
	v_mov_b32_e32 v60, v2
	v_mov_b32_e32 v61, v2
	v_mov_b32_e32 v62, v2
	v_mov_b32_e32 v63, v2
	v_mov_b32_e32 v64, v2
	v_mov_b32_e32 v65, v2
	v_mov_b32_e32 v66, v2
	v_mov_b32_e32 v67, v2
	v_mov_b32_e32 v68, v2
	v_mov_b32_e32 v69, v2
	v_mov_b32_e32 v70, v2
	v_mov_b32_e32 v71, v2
	v_mov_b32_e32 v72, v2
	v_mov_b32_e32 v73, v2
	v_mov_b32_e32 v82, v2
	v_mov_b32_e32 v83, v2
	v_mov_b32_e32 v84, v2
	v_mov_b32_e32 v85, v2
	v_mov_b32_e32 v86, v2
	v_mov_b32_e32 v87, v2
	v_mov_b32_e32 v88, v2
	v_mov_b32_e32 v89, v2
	v_mov_b32_e32 v98, v2
	v_mov_b32_e32 v99, v2
	v_mov_b32_e32 v100, v2
	v_mov_b32_e32 v101, v2
	v_mov_b32_e32 v102, v2
	v_mov_b32_e32 v103, v2
	v_mov_b32_e32 v104, v2
	v_mov_b32_e32 v105, v2
	v_mov_b32_e32 v114, v2
	v_mov_b32_e32 v115, v2
	v_mov_b32_e32 v116, v2
	v_mov_b32_e32 v117, v2
	v_mov_b32_e32 v118, v2
	v_mov_b32_e32 v119, v2
	v_mov_b32_e32 v120, v2
	v_mov_b32_e32 v121, v2
	v_mov_b32_e32 v74, v2
	v_mov_b32_e32 v75, v2
	v_mov_b32_e32 v76, v2
	v_mov_b32_e32 v77, v2
	v_mov_b32_e32 v78, v2
	v_mov_b32_e32 v79, v2
	v_mov_b32_e32 v80, v2
	v_mov_b32_e32 v81, v2
	v_mov_b32_e32 v90, v2
	v_mov_b32_e32 v91, v2
	v_mov_b32_e32 v92, v2
	v_mov_b32_e32 v93, v2
	v_mov_b32_e32 v94, v2
	v_mov_b32_e32 v95, v2
	v_mov_b32_e32 v96, v2
	v_mov_b32_e32 v97, v2
	v_mov_b32_e32 v106, v2
	v_mov_b32_e32 v107, v2
	v_mov_b32_e32 v108, v2
	v_mov_b32_e32 v109, v2
	v_mov_b32_e32 v110, v2
	v_mov_b32_e32 v111, v2
	v_mov_b32_e32 v112, v2
	v_mov_b32_e32 v113, v2
	v_mov_b32_e32 v122, v2
	v_mov_b32_e32 v123, v2
	v_mov_b32_e32 v124, v2
	v_mov_b32_e32 v125, v2
	v_mov_b32_e32 v126, v2
	v_mov_b32_e32 v127, v2
	v_mov_b32_e32 v128, v2
	v_mov_b32_e32 v129, v2
	.p2align	6

; #define PG8_STAGE(bufoff, gbase, voff) do { _Pragma("unroll") for (int _i = 0; _i < 2; ++_i) \
;         __builtin_amdgcn_global_load_lds((const unsigned*)((const char*)(gbase) + (voff)[_i]), (PG8_LAS unsigned*)(lds + (bufoff) + ldsw + _i * 8192), 16, 0, 0); } while (0)
; #define PG8_WAIT_V(n) asm volatile("s_waitcnt vmcnt(" #n ")" ::: "memory")
; #define PG8_BAR __builtin_amdgcn_s_barrier()
; template <class Epi, class Sched, bool ALIGN_EPI = false, bool SP2 = false>
; __device__ __forceinline__ void gemm_phase(PG8_LAS unsigned char* lds, const Gemm g, const Sched& S, const Epi& E) {
;     ...
;     for (int i = 0; i < 2; ++i) { int R, C; stage_rc(tid * 16 + i * 8192, R, C); const int Rb = Epi::PERM ? ((R & ~31) + perm32(R & 31)) : R;
;         voffA[i] = (unsigned)(R * K + C) * 2u; voffB[i] = (unsigned)(Rb * K + C) * 2u; }
;     const size_t kstep = (size_t)(BK * 2);
;     const size_t hstep = (size_t)HALF * K * 2;
;     const size_t tstep = 2 * hstep;
;     const unsigned ldsw = (unsigned)wid * 1024u;
;     const int aoff = lds_byte(wr * 64 + fr, fq * 8), boff = lds_byte(wc * 32 + fr, fq * 8);
;     ...
;         if (wr == 1) PG8_BAR;
;         PG8_WAIT_V(2); PG8_BAR;
;         PG8_STAGE(PG8_SB(1, 0), cB + kstep, voffB); PG8_STAGE(PG8_SA(1, 0), cA + kstep, voffA); PG8_STAGE(PG8_SB(1, 1), cB + hstep + kstep, voffB);
;         PG8_WAIT_V(6); PG8_BAR;
.LBB0_567:
	s_add_u32 s16, s6, 0x17500000
	s_mov_b64 s[18:19], 0x80
	s_addc_u32 s17, s7, 0
	s_add_i32 m0, s0, 0x18000
	v_lshl_add_u64 v[10:11], v[10:11], 0, s[18:19]
	s_waitcnt vmcnt(2)
	s_barrier
	global_load_lds_dwordx4 v[10:11], off
	v_lshl_add_u64 v[6:7], v[6:7], 0, s[18:19]
	s_add_i32 m0, s0, 0x1a000
	s_add_i32 s42, s0, 0x8000
	global_load_lds_dwordx4 v[6:7], off
	v_lshl_add_u64 v[6:7], v[8:9], 0, s[18:19]
	s_mov_b32 m0, s42
	s_add_i32 s43, s0, 0xa000
	global_load_lds_dwordx4 v[6:7], off
	v_lshl_add_u64 v[6:7], v[12:13], 0, s[18:19]
	s_mov_b32 m0, s43
	v_lshl_add_u64 v[4:5], v[4:5], 0, s[18:19]
	global_load_lds_dwordx4 v[6:7], off
	s_add_i32 m0, s0, 0x1c000
	v_lshl_add_u64 v[2:3], v[2:3], 0, s[18:19]
	global_load_lds_dwordx4 v[4:5], off
	s_add_i32 m0, s0, 0x1e000
	s_lshr_b32 s5, s5, 26
	global_load_lds_dwordx4 v[2:3], off
	v_and_b32_e32 v2, 15, v0
	s_add_i32 s5, s4, s5
	v_lshlrev_b32_e32 v3, 1, v18
	v_lshlrev_b32_e32 v4, 2, v0
	s_ashr_i32 s44, s5, 6
	v_lshl_or_b32 v1, s23, 6, v2
	v_lshl_or_b32 v2, v2, 6, v3
	s_lshl_b32 s5, s23, 13
	v_and_b32_e32 v4, 32, v4
	v_bitop3_b32 v5, v2, s5, v4 bitop3:0xde
	s_lshl_b32 s5, s21, 5
	s_and_b32 s5, s5, 0x60
	v_lshlrev_b32_e32 v2, 6, v0
	s_movk_i32 s6, 0x3c0
	v_and_or_b32 v2, v2, s6, v3
	s_lshl_b32 s6, s5, 7
	v_bitop3_b32 v146, s6, v2, v4 bitop3:0xf6
	v_add_u32_e32 v2, v19, v16
	v_mul_lo_u32 v2, s4, v2
	v_lshlrev_b32_e32 v2, 1, v2
	v_add3_u32 v2, v14, v2, v15
	v_mov_b32_e32 v3, v133
	s_cmp_gt_i32 s4, 63
	v_lshl_add_u64 v[138:139], s[10:11], 0, v[2:3]
	v_add_u32_e32 v2, v17, v16
	s_sext_i32_i8 s57, s20
	s_cselect_b64 s[20:21], -1, 0
	s_add_i32 s45, s44, -2
	v_mul_lo_u32 v2, s4, v2
	s_waitcnt vmcnt(6)
	s_cmpk_lt_u32 s22, 0x100
	v_lshlrev_b32_e32 v2, 1, v2
	s_cselect_b64 s[22:23], -1, 0
	v_add3_u32 v2, v14, v2, v15
	s_add_i32 s52, 0, 0x10000
	s_add_i32 s53, 0, 0x14000
	s_ashr_i32 s46, s82, 31
	s_mov_b32 s47, s82
	v_or_b32_e32 v147, s5, v18
	v_lshl_add_u64 v[140:141], s[10:11], 0, v[2:3]
	v_mov_b64_e32 v[142:143], 0x200
	v_mov_b64_e32 v[144:145], 0x1ff
	v_add_u32_e32 v148, s52, v146
	v_add_u32_e32 v149, s53, v146
	v_add_u32_e32 v150, 0, v5
	s_barrier
	s_waitcnt vmcnt(0)
	s_branch .LBB0_570
	.p2align	6

; #define PG8_BAR __builtin_amdgcn_s_barrier()
; template <class Epi, class Sched, bool ALIGN_EPI = false, bool SP2 = false>
; __device__ __forceinline__ void gemm_phase(PG8_LAS unsigned char* lds, const Gemm g, const Sched& S, const Epi& E) {
;     ...
; #pragma unroll
;         for (int a = 0; a < 2; ++a)
; #pragma unroll
;             for (int b = 0; b < 2; ++b)
; #pragma unroll
;                 for (int m = 0; m < 4; ++m)
; #pragma unroll
;                     for (int n = 0; n < 2; ++n) acc[a][b][m][n] = (f32x4){0.f, 0.f, 0.f, 0.f};
;         cur = nxt; cA = nA; cB = nB; ++ui;
;         if constexpr (ALIGN_EPI) { if (wr == 1) PG8_BAR; }
.LBB0_580:
	v_mov_b32_e32 v125, 0
	s_andn2_b64 vcc, exec, s[20:21]
	v_mov_b32_e32 v124, v125
	v_mov_b32_e32 v123, v125
	v_mov_b32_e32 v122, v125
	v_mov_b32_e32 v129, v125
	v_mov_b32_e32 v128, v125
	v_mov_b32_e32 v127, v125
	v_mov_b32_e32 v126, v125
	v_mov_b32_e32 v113, v125
	v_mov_b32_e32 v112, v125
	v_mov_b32_e32 v111, v125
	v_mov_b32_e32 v110, v125
	v_mov_b32_e32 v109, v125
	v_mov_b32_e32 v108, v125
	v_mov_b32_e32 v107, v125
	v_mov_b32_e32 v106, v125
	v_mov_b32_e32 v97, v125
	v_mov_b32_e32 v96, v125
	v_mov_b32_e32 v95, v125
	v_mov_b32_e32 v94, v125
	v_mov_b32_e32 v93, v125
	v_mov_b32_e32 v92, v125
	v_mov_b32_e32 v91, v125
	v_mov_b32_e32 v90, v125
	v_mov_b32_e32 v81, v125
	v_mov_b32_e32 v80, v125
	v_mov_b32_e32 v79, v125
	v_mov_b32_e32 v78, v125
	v_mov_b32_e32 v77, v125
	v_mov_b32_e32 v76, v125
	v_mov_b32_e32 v75, v125
	v_mov_b32_e32 v74, v125
	v_mov_b32_e32 v121, v125
	v_mov_b32_e32 v120, v125
	v_mov_b32_e32 v119, v125
	v_mov_b32_e32 v118, v125
	v_mov_b32_e32 v117, v125
	v_mov_b32_e32 v116, v125
	v_mov_b32_e32 v115, v125
	v_mov_b32_e32 v114, v125
	v_mov_b32_e32 v105, v125
	v_mov_b32_e32 v104, v125
	v_mov_b32_e32 v103, v125
	v_mov_b32_e32 v102, v125
	v_mov_b32_e32 v101, v125
	v_mov_b32_e32 v100, v125
	v_mov_b32_e32 v99, v125
	v_mov_b32_e32 v98, v125
	v_mov_b32_e32 v89, v125
	v_mov_b32_e32 v88, v125
	v_mov_b32_e32 v87, v125
	v_mov_b32_e32 v86, v125
	v_mov_b32_e32 v85, v125
	v_mov_b32_e32 v84, v125
	v_mov_b32_e32 v83, v125
	v_mov_b32_e32 v82, v125
	v_mov_b32_e32 v73, v125
	v_mov_b32_e32 v72, v125
	v_mov_b32_e32 v71, v125
	v_mov_b32_e32 v70, v125
	v_mov_b32_e32 v69, v125
	v_mov_b32_e32 v68, v125
	v_mov_b32_e32 v67, v125
	v_mov_b32_e32 v66, v125
	v_mov_b32_e32 v65, v125
	v_mov_b32_e32 v64, v125
	v_mov_b32_e32 v63, v125
	v_mov_b32_e32 v62, v125
	v_mov_b32_e32 v61, v125
	v_mov_b32_e32 v60, v125
	v_mov_b32_e32 v59, v125
	v_mov_b32_e32 v58, v125
	v_mov_b32_e32 v49, v125
	v_mov_b32_e32 v48, v125
	v_mov_b32_e32 v47, v125
	v_mov_b32_e32 v46, v125
	v_mov_b32_e32 v45, v125
	v_mov_b32_e32 v44, v125
	v_mov_b32_e32 v43, v125
	v_mov_b32_e32 v42, v125
	v_mov_b32_e32 v33, v125
	v_mov_b32_e32 v32, v125
	v_mov_b32_e32 v31, v125
	v_mov_b32_e32 v30, v125
	v_mov_b32_e32 v29, v125
	v_mov_b32_e32 v28, v125
	v_mov_b32_e32 v27, v125
	v_mov_b32_e32 v26, v125
	v_mov_b32_e32 v17, v125
	v_mov_b32_e32 v16, v125
	v_mov_b32_e32 v15, v125
	v_mov_b32_e32 v14, v125
	v_mov_b32_e32 v13, v125
	v_mov_b32_e32 v12, v125
	v_mov_b32_e32 v11, v125
	v_mov_b32_e32 v10, v125
	v_mov_b32_e32 v57, v125
	v_mov_b32_e32 v56, v125
	v_mov_b32_e32 v55, v125
	v_mov_b32_e32 v54, v125
	v_mov_b32_e32 v53, v125
	v_mov_b32_e32 v52, v125
	v_mov_b32_e32 v51, v125
	v_mov_b32_e32 v50, v125
	v_mov_b32_e32 v41, v125
	v_mov_b32_e32 v40, v125
	v_mov_b32_e32 v39, v125
	v_mov_b32_e32 v38, v125
	v_mov_b32_e32 v37, v125
	v_mov_b32_e32 v36, v125
	v_mov_b32_e32 v35, v125
	v_mov_b32_e32 v34, v125
	v_mov_b32_e32 v25, v125
	v_mov_b32_e32 v24, v125
	v_mov_b32_e32 v23, v125
	v_mov_b32_e32 v22, v125
	v_mov_b32_e32 v21, v125
	v_mov_b32_e32 v20, v125
	v_mov_b32_e32 v19, v125
	v_mov_b32_e32 v18, v125
	v_mov_b32_e32 v9, v125
	v_mov_b32_e32 v8, v125
	v_mov_b32_e32 v7, v125
	v_mov_b32_e32 v6, v125
	v_mov_b32_e32 v5, v125
	v_mov_b32_e32 v4, v125
	v_mov_b32_e32 v3, v125
	v_mov_b32_e32 v2, v125
	s_cbranch_vccnz .LBB0_583
	s_add_u32 s58, s28, 0x100
	s_addc_u32 s59, s29, 0
	s_add_u32 s28, s30, 0x80
	v_mov_b32_e32 v2, 0
	s_addc_u32 s29, s31, 0
	s_mov_b32 s30, 0
	v_mov_b32_e32 v3, v2
	v_mov_b32_e32 v4, v2
	v_mov_b32_e32 v5, v2
	v_mov_b32_e32 v6, v2
	v_mov_b32_e32 v7, v2
	v_mov_b32_e32 v8, v2
	v_mov_b32_e32 v9, v2
	v_mov_b32_e32 v18, v2
	v_mov_b32_e32 v19, v2
	v_mov_b32_e32 v20, v2
	v_mov_b32_e32 v21, v2
	v_mov_b32_e32 v22, v2
	v_mov_b32_e32 v23, v2
	v_mov_b32_e32 v24, v2
	v_mov_b32_e32 v25, v2
	v_mov_b32_e32 v34, v2
	v_mov_b32_e32 v35, v2
	v_mov_b32_e32 v36, v2
	v_mov_b32_e32 v37, v2
	v_mov_b32_e32 v38, v2
	v_mov_b32_e32 v39, v2
	v_mov_b32_e32 v40, v2
	v_mov_b32_e32 v41, v2
	v_mov_b32_e32 v50, v2
	v_mov_b32_e32 v51, v2
	v_mov_b32_e32 v52, v2
	v_mov_b32_e32 v53, v2
	v_mov_b32_e32 v54, v2
	v_mov_b32_e32 v55, v2
	v_mov_b32_e32 v56, v2
	v_mov_b32_e32 v57, v2
	v_mov_b32_e32 v10, v2
	v_mov_b32_e32 v11, v2
	v_mov_b32_e32 v12, v2
	v_mov_b32_e32 v13, v2
	v_mov_b32_e32 v14, v2
	v_mov_b32_e32 v15, v2
	v_mov_b32_e32 v16, v2
	v_mov_b32_e32 v17, v2
	v_mov_b32_e32 v26, v2
	v_mov_b32_e32 v27, v2
	v_mov_b32_e32 v28, v2
	v_mov_b32_e32 v29, v2
	v_mov_b32_e32 v30, v2
	v_mov_b32_e32 v31, v2
	v_mov_b32_e32 v32, v2
	v_mov_b32_e32 v33, v2
	v_mov_b32_e32 v42, v2
	v_mov_b32_e32 v43, v2
	v_mov_b32_e32 v44, v2
	v_mov_b32_e32 v45, v2
	v_mov_b32_e32 v46, v2
	v_mov_b32_e32 v47, v2
	v_mov_b32_e32 v48, v2
	v_mov_b32_e32 v49, v2
	v_mov_b32_e32 v58, v2
	v_mov_b32_e32 v59, v2
	v_mov_b32_e32 v60, v2
	v_mov_b32_e32 v61, v2
	v_mov_b32_e32 v62, v2
	v_mov_b32_e32 v63, v2
	v_mov_b32_e32 v64, v2
	v_mov_b32_e32 v65, v2
	v_mov_b32_e32 v66, v2
	v_mov_b32_e32 v67, v2
	v_mov_b32_e32 v68, v2
	v_mov_b32_e32 v69, v2
	v_mov_b32_e32 v70, v2
	v_mov_b32_e32 v71, v2
	v_mov_b32_e32 v72, v2
	v_mov_b32_e32 v73, v2
	v_mov_b32_e32 v82, v2
	v_mov_b32_e32 v83, v2
	v_mov_b32_e32 v84, v2
	v_mov_b32_e32 v85, v2
	v_mov_b32_e32 v86, v2
	v_mov_b32_e32 v87, v2
	v_mov_b32_e32 v88, v2
	v_mov_b32_e32 v89, v2
	v_mov_b32_e32 v98, v2
	v_mov_b32_e32 v99, v2
	v_mov_b32_e32 v100, v2
	v_mov_b32_e32 v101, v2
	v_mov_b32_e32 v102, v2
	v_mov_b32_e32 v103, v2
	v_mov_b32_e32 v104, v2
	v_mov_b32_e32 v105, v2
	v_mov_b32_e32 v114, v2
	v_mov_b32_e32 v115, v2
	v_mov_b32_e32 v116, v2
	v_mov_b32_e32 v117, v2
	v_mov_b32_e32 v118, v2
	v_mov_b32_e32 v119, v2
	v_mov_b32_e32 v120, v2
	v_mov_b32_e32 v121, v2
	v_mov_b32_e32 v74, v2
	v_mov_b32_e32 v75, v2
	v_mov_b32_e32 v76, v2
	v_mov_b32_e32 v77, v2
	v_mov_b32_e32 v78, v2
	v_mov_b32_e32 v79, v2
	v_mov_b32_e32 v80, v2
	v_mov_b32_e32 v81, v2
	v_mov_b32_e32 v90, v2
	v_mov_b32_e32 v91, v2
	v_mov_b32_e32 v92, v2
	v_mov_b32_e32 v93, v2
	v_mov_b32_e32 v94, v2
	v_mov_b32_e32 v95, v2
	v_mov_b32_e32 v96, v2
	v_mov_b32_e32 v97, v2
	v_mov_b32_e32 v106, v2
	v_mov_b32_e32 v107, v2
	v_mov_b32_e32 v108, v2
	v_mov_b32_e32 v109, v2
	v_mov_b32_e32 v110, v2
	v_mov_b32_e32 v111, v2
	v_mov_b32_e32 v112, v2
	v_mov_b32_e32 v113, v2
	v_mov_b32_e32 v126, v2
	v_mov_b32_e32 v127, v2
	v_mov_b32_e32 v128, v2
	v_mov_b32_e32 v129, v2
	v_mov_b32_e32 v122, v2
	v_mov_b32_e32 v123, v2
	v_mov_b32_e32 v124, v2
	v_mov_b32_e32 v125, v2
	.p2align	6

; #define PG8_STAGE(bufoff, gbase, voff) do { _Pragma("unroll") for (int _i = 0; _i < 2; ++_i) \
;         __builtin_amdgcn_global_load_lds((const unsigned*)((const char*)(gbase) + (voff)[_i]), (PG8_LAS unsigned*)(lds + (bufoff) + ldsw + _i * 8192), 16, 0, 0); } while (0)
; #define PG8_WAIT_V(n) asm volatile("s_waitcnt vmcnt(" #n ")" ::: "memory")
; #define PG8_BAR __builtin_amdgcn_s_barrier()
; template <class Epi, class Sched, bool ALIGN_EPI = false, bool SP2 = false>
; __device__ __forceinline__ void gemm_phase(PG8_LAS unsigned char* lds, const Gemm g, const Sched& S, const Epi& E) {
;     ...
;     for (int i = 0; i < 2; ++i) { int R, C; stage_rc(tid * 16 + i * 8192, R, C); const int Rb = Epi::PERM ? ((R & ~31) + perm32(R & 31)) : R;
;         voffA[i] = (unsigned)(R * K + C) * 2u; voffB[i] = (unsigned)(Rb * K + C) * 2u; }
;     const size_t kstep = (size_t)(BK * 2);
;     const size_t hstep = (size_t)HALF * K * 2;
;     const size_t tstep = 2 * hstep;
;     const unsigned ldsw = (unsigned)wid * 1024u;
;     const int aoff = lds_byte(wr * 64 + fr, fq * 8), boff = lds_byte(wc * 32 + fr, fq * 8);
;     ...
;         if (wr == 1) PG8_BAR;
;         PG8_WAIT_V(2); PG8_BAR;
;         PG8_STAGE(PG8_SB(1, 0), cB + kstep, voffB); PG8_STAGE(PG8_SA(1, 0), cA + kstep, voffA); PG8_STAGE(PG8_SB(1, 1), cB + hstep + kstep, voffB);
;         PG8_WAIT_V(6); PG8_BAR;
.LBB0_738:
	s_add_u32 s16, s6, 0xc500000
	s_mov_b64 s[18:19], 0x80
	s_addc_u32 s17, s7, 0
	s_add_i32 m0, s40, 0x18000
	v_lshl_add_u64 v[10:11], v[10:11], 0, s[18:19]
	s_waitcnt vmcnt(2)
	s_barrier
	global_load_lds_dwordx4 v[10:11], off
	v_lshl_add_u64 v[6:7], v[6:7], 0, s[18:19]
	s_add_i32 m0, s40, 0x1a000
	s_add_i32 s45, s40, 0x8000
	global_load_lds_dwordx4 v[6:7], off
	v_lshl_add_u64 v[6:7], v[8:9], 0, s[18:19]
	s_mov_b32 m0, s45
	s_add_i32 s46, s40, 0xa000
	global_load_lds_dwordx4 v[6:7], off
	v_lshl_add_u64 v[6:7], v[12:13], 0, s[18:19]
	s_mov_b32 m0, s46
	v_lshl_add_u64 v[4:5], v[4:5], 0, s[18:19]
	global_load_lds_dwordx4 v[6:7], off
	s_add_i32 m0, s40, 0x1c000
	v_lshl_add_u64 v[2:3], v[2:3], 0, s[18:19]
	global_load_lds_dwordx4 v[4:5], off
	s_add_i32 m0, s40, 0x1e000
	s_lshr_b32 s5, s5, 26
	global_load_lds_dwordx4 v[2:3], off
	v_and_b32_e32 v2, 15, v0
	s_add_i32 s5, s4, s5
	v_lshlrev_b32_e32 v3, 1, v16
	v_lshlrev_b32_e32 v4, 2, v0
	s_ashr_i32 s47, s5, 6
	v_lshl_or_b32 v1, s23, 6, v2
	v_lshl_or_b32 v2, v2, 6, v3
	s_lshl_b32 s5, s23, 13
	v_and_b32_e32 v4, 32, v4
	v_bitop3_b32 v5, v2, s5, v4 bitop3:0xde
	s_lshl_b32 s5, s21, 5
	s_and_b32 s5, s5, 0x60
	v_lshlrev_b32_e32 v2, 6, v0
	s_movk_i32 s6, 0x3c0
	v_and_or_b32 v2, v2, s6, v3
	s_lshl_b32 s6, s5, 7
	v_bitop3_b32 v146, s6, v2, v4 bitop3:0xf6
	v_add_u32_e32 v2, v18, v17
	v_mul_lo_u32 v2, s4, v2
	v_lshlrev_b32_e32 v2, 1, v2
	v_add3_u32 v2, v14, v2, v15
	v_mov_b32_e32 v3, v135
	s_cmp_gt_i32 s4, 63
	v_lshl_add_u64 v[138:139], s[10:11], 0, v[2:3]
	v_add_u32_e32 v2, v19, v17
	s_sext_i32_i16 s1, s20
	s_cselect_b64 s[20:21], -1, 0
	s_add_i32 s48, s47, -2
	v_mul_lo_u32 v2, s4, v2
	s_waitcnt vmcnt(6)
	s_cmpk_lt_u32 s22, 0x100
	v_lshlrev_b32_e32 v2, 1, v2
	s_cselect_b64 s[22:23], -1, 0
	v_add3_u32 v2, v14, v2, v15
	s_add_i32 s53, 0, 0x10000
	s_add_i32 s54, 0, 0x14000
	s_ashr_i32 s49, s82, 31
	s_mov_b32 s52, s82
	v_or_b32_e32 v147, s5, v16
	v_lshl_add_u64 v[140:141], s[10:11], 0, v[2:3]
	v_mov_b64_e32 v[142:143], 0xb00
	v_mov_b64_e32 v[144:145], 0xaff
	v_add_u32_e32 v148, s53, v146
	v_add_u32_e32 v149, s54, v146
	v_add_u32_e32 v150, 0, v5
	s_movk_i32 s55, 0x2c00
	s_barrier
	s_waitcnt vmcnt(0)
	s_branch .LBB0_741
	.p2align	6

; #define PG8_BAR __builtin_amdgcn_s_barrier()
; template <class Epi, class Sched, bool ALIGN_EPI = false, bool SP2 = false>
; __device__ __forceinline__ void gemm_phase(PG8_LAS unsigned char* lds, const Gemm g, const Sched& S, const Epi& E) {
;     ...
; #pragma unroll
;         for (int a = 0; a < 2; ++a)
; #pragma unroll
;             for (int b = 0; b < 2; ++b)
; #pragma unroll
;                 for (int m = 0; m < 4; ++m)
; #pragma unroll
;                     for (int n = 0; n < 2; ++n) acc[a][b][m][n] = (f32x4){0.f, 0.f, 0.f, 0.f};
;         cur = nxt; cA = nA; cB = nB; ++ui;
;         if constexpr (ALIGN_EPI) { if (wr == 1) PG8_BAR; }
.LBB0_747:
	v_mov_b32_e32 v125, 0
	s_andn2_b64 vcc, exec, s[20:21]
	v_mov_b32_e32 v124, v125
	v_mov_b32_e32 v123, v125
	v_mov_b32_e32 v122, v125
	v_mov_b32_e32 v121, v125
	v_mov_b32_e32 v120, v125
	v_mov_b32_e32 v119, v125
	v_mov_b32_e32 v118, v125
	v_mov_b32_e32 v113, v125
	v_mov_b32_e32 v112, v125
	v_mov_b32_e32 v111, v125
	v_mov_b32_e32 v110, v125
	v_mov_b32_e32 v105, v125
	v_mov_b32_e32 v104, v125
	v_mov_b32_e32 v103, v125
	v_mov_b32_e32 v102, v125
	v_mov_b32_e32 v97, v125
	v_mov_b32_e32 v96, v125
	v_mov_b32_e32 v95, v125
	v_mov_b32_e32 v94, v125
	v_mov_b32_e32 v89, v125
	v_mov_b32_e32 v88, v125
	v_mov_b32_e32 v87, v125
	v_mov_b32_e32 v86, v125
	v_mov_b32_e32 v81, v125
	v_mov_b32_e32 v80, v125
	v_mov_b32_e32 v79, v125
	v_mov_b32_e32 v78, v125
	v_mov_b32_e32 v73, v125
	v_mov_b32_e32 v72, v125
	v_mov_b32_e32 v71, v125
	v_mov_b32_e32 v70, v125
	v_mov_b32_e32 v129, v125
	v_mov_b32_e32 v128, v125
	v_mov_b32_e32 v127, v125
	v_mov_b32_e32 v126, v125
	v_mov_b32_e32 v117, v125
	v_mov_b32_e32 v116, v125
	v_mov_b32_e32 v115, v125
	v_mov_b32_e32 v114, v125
	v_mov_b32_e32 v109, v125
	v_mov_b32_e32 v108, v125
	v_mov_b32_e32 v107, v125
	v_mov_b32_e32 v106, v125
	v_mov_b32_e32 v101, v125
	v_mov_b32_e32 v100, v125
	v_mov_b32_e32 v99, v125
	v_mov_b32_e32 v98, v125
	v_mov_b32_e32 v93, v125
	v_mov_b32_e32 v92, v125
	v_mov_b32_e32 v91, v125
	v_mov_b32_e32 v90, v125
	v_mov_b32_e32 v85, v125
	v_mov_b32_e32 v84, v125
	v_mov_b32_e32 v83, v125
	v_mov_b32_e32 v82, v125
	v_mov_b32_e32 v77, v125
	v_mov_b32_e32 v76, v125
	v_mov_b32_e32 v75, v125
	v_mov_b32_e32 v74, v125
	v_mov_b32_e32 v69, v125
	v_mov_b32_e32 v68, v125
	v_mov_b32_e32 v67, v125
	v_mov_b32_e32 v66, v125
	v_mov_b32_e32 v65, v125
	v_mov_b32_e32 v64, v125
	v_mov_b32_e32 v63, v125
	v_mov_b32_e32 v62, v125
	v_mov_b32_e32 v57, v125
	v_mov_b32_e32 v56, v125
	v_mov_b32_e32 v55, v125
	v_mov_b32_e32 v54, v125
	v_mov_b32_e32 v49, v125
	v_mov_b32_e32 v48, v125
	v_mov_b32_e32 v47, v125
	v_mov_b32_e32 v46, v125
	v_mov_b32_e32 v41, v125
	v_mov_b32_e32 v40, v125
	v_mov_b32_e32 v39, v125
	v_mov_b32_e32 v38, v125
	v_mov_b32_e32 v33, v125
	v_mov_b32_e32 v32, v125
	v_mov_b32_e32 v31, v125
	v_mov_b32_e32 v30, v125
	v_mov_b32_e32 v25, v125
	v_mov_b32_e32 v24, v125
	v_mov_b32_e32 v23, v125
	v_mov_b32_e32 v22, v125
	v_mov_b32_e32 v17, v125
	v_mov_b32_e32 v16, v125
	v_mov_b32_e32 v15, v125
	v_mov_b32_e32 v14, v125
	v_mov_b32_e32 v9, v125
	v_mov_b32_e32 v8, v125
	v_mov_b32_e32 v7, v125
	v_mov_b32_e32 v6, v125
	v_mov_b32_e32 v61, v125
	v_mov_b32_e32 v60, v125
	v_mov_b32_e32 v59, v125
	v_mov_b32_e32 v58, v125
	v_mov_b32_e32 v53, v125
	v_mov_b32_e32 v52, v125
	v_mov_b32_e32 v51, v125
	v_mov_b32_e32 v50, v125
	v_mov_b32_e32 v45, v125
	v_mov_b32_e32 v44, v125
	v_mov_b32_e32 v43, v125
	v_mov_b32_e32 v42, v125
	v_mov_b32_e32 v37, v125
	v_mov_b32_e32 v36, v125
	v_mov_b32_e32 v35, v125
	v_mov_b32_e32 v34, v125
	v_mov_b32_e32 v29, v125
	v_mov_b32_e32 v28, v125
	v_mov_b32_e32 v27, v125
	v_mov_b32_e32 v26, v125
	v_mov_b32_e32 v21, v125
	v_mov_b32_e32 v20, v125
	v_mov_b32_e32 v19, v125
	v_mov_b32_e32 v18, v125
	v_mov_b32_e32 v13, v125
	v_mov_b32_e32 v12, v125
	v_mov_b32_e32 v11, v125
	v_mov_b32_e32 v10, v125
	v_mov_b32_e32 v5, v125
	v_mov_b32_e32 v4, v125
	v_mov_b32_e32 v3, v125
	v_mov_b32_e32 v2, v125
	s_cbranch_vccnz .LBB0_750
	s_add_u32 s58, s28, 0x100
	s_addc_u32 s59, s29, 0
	s_add_u32 s28, s30, 0x80
	v_mov_b32_e32 v2, 0
	s_addc_u32 s29, s31, 0
	s_mov_b32 s30, 0
	v_mov_b32_e32 v3, v2
	v_mov_b32_e32 v4, v2
	v_mov_b32_e32 v5, v2
	v_mov_b32_e32 v10, v2
	v_mov_b32_e32 v11, v2
	v_mov_b32_e32 v12, v2
	v_mov_b32_e32 v13, v2
	v_mov_b32_e32 v18, v2
	v_mov_b32_e32 v19, v2
	v_mov_b32_e32 v20, v2
	v_mov_b32_e32 v21, v2
	v_mov_b32_e32 v26, v2
	v_mov_b32_e32 v27, v2
	v_mov_b32_e32 v28, v2
	v_mov_b32_e32 v29, v2
	v_mov_b32_e32 v34, v2
	v_mov_b32_e32 v35, v2
	v_mov_b32_e32 v36, v2
	v_mov_b32_e32 v37, v2
	v_mov_b32_e32 v42, v2
	v_mov_b32_e32 v43, v2
	v_mov_b32_e32 v44, v2
	v_mov_b32_e32 v45, v2
	v_mov_b32_e32 v50, v2
	v_mov_b32_e32 v51, v2
	v_mov_b32_e32 v52, v2
	v_mov_b32_e32 v53, v2
	v_mov_b32_e32 v58, v2
	v_mov_b32_e32 v59, v2
	v_mov_b32_e32 v60, v2
	v_mov_b32_e32 v61, v2
	v_mov_b32_e32 v6, v2
	v_mov_b32_e32 v7, v2
	v_mov_b32_e32 v8, v2
	v_mov_b32_e32 v9, v2
	v_mov_b32_e32 v14, v2
	v_mov_b32_e32 v15, v2
	v_mov_b32_e32 v16, v2
	v_mov_b32_e32 v17, v2
	v_mov_b32_e32 v22, v2
	v_mov_b32_e32 v23, v2
	v_mov_b32_e32 v24, v2
	v_mov_b32_e32 v25, v2
	v_mov_b32_e32 v30, v2
	v_mov_b32_e32 v31, v2
	v_mov_b32_e32 v32, v2
	v_mov_b32_e32 v33, v2
	v_mov_b32_e32 v38, v2
	v_mov_b32_e32 v39, v2
	v_mov_b32_e32 v40, v2
	v_mov_b32_e32 v41, v2
	v_mov_b32_e32 v46, v2
	v_mov_b32_e32 v47, v2
	v_mov_b32_e32 v48, v2
	v_mov_b32_e32 v49, v2
	v_mov_b32_e32 v54, v2
	v_mov_b32_e32 v55, v2
	v_mov_b32_e32 v56, v2
	v_mov_b32_e32 v57, v2
	v_mov_b32_e32 v62, v2
	v_mov_b32_e32 v63, v2
	v_mov_b32_e32 v64, v2
	v_mov_b32_e32 v65, v2
	v_mov_b32_e32 v66, v2
	v_mov_b32_e32 v67, v2
	v_mov_b32_e32 v68, v2
	v_mov_b32_e32 v69, v2
	v_mov_b32_e32 v74, v2
	v_mov_b32_e32 v75, v2
	v_mov_b32_e32 v76, v2
	v_mov_b32_e32 v77, v2
	v_mov_b32_e32 v82, v2
	v_mov_b32_e32 v83, v2
	v_mov_b32_e32 v84, v2
	v_mov_b32_e32 v85, v2
	v_mov_b32_e32 v90, v2
	v_mov_b32_e32 v91, v2
	v_mov_b32_e32 v92, v2
	v_mov_b32_e32 v93, v2
	v_mov_b32_e32 v98, v2
	v_mov_b32_e32 v99, v2
	v_mov_b32_e32 v100, v2
	v_mov_b32_e32 v101, v2
	v_mov_b32_e32 v106, v2
	v_mov_b32_e32 v107, v2
	v_mov_b32_e32 v108, v2
	v_mov_b32_e32 v109, v2
	v_mov_b32_e32 v114, v2
	v_mov_b32_e32 v115, v2
	v_mov_b32_e32 v116, v2
	v_mov_b32_e32 v117, v2
	v_mov_b32_e32 v126, v2
	v_mov_b32_e32 v127, v2
	v_mov_b32_e32 v128, v2
	v_mov_b32_e32 v129, v2
	v_mov_b32_e32 v70, v2
	v_mov_b32_e32 v71, v2
	v_mov_b32_e32 v72, v2
	v_mov_b32_e32 v73, v2
	v_mov_b32_e32 v78, v2
	v_mov_b32_e32 v79, v2
	v_mov_b32_e32 v80, v2
	v_mov_b32_e32 v81, v2
	v_mov_b32_e32 v86, v2
	v_mov_b32_e32 v87, v2
	v_mov_b32_e32 v88, v2
	v_mov_b32_e32 v89, v2
	v_mov_b32_e32 v94, v2
	v_mov_b32_e32 v95, v2
	v_mov_b32_e32 v96, v2
	v_mov_b32_e32 v97, v2
	v_mov_b32_e32 v102, v2
	v_mov_b32_e32 v103, v2
	v_mov_b32_e32 v104, v2
	v_mov_b32_e32 v105, v2
	v_mov_b32_e32 v110, v2
	v_mov_b32_e32 v111, v2
	v_mov_b32_e32 v112, v2
	v_mov_b32_e32 v113, v2
	v_mov_b32_e32 v118, v2
	v_mov_b32_e32 v119, v2
	v_mov_b32_e32 v120, v2
	v_mov_b32_e32 v121, v2
	v_mov_b32_e32 v122, v2
	v_mov_b32_e32 v123, v2
	v_mov_b32_e32 v124, v2
	v_mov_b32_e32 v125, v2
	.p2align	6

; #define PG8_STAGE(bufoff, gbase, voff) do { _Pragma("unroll") for (int _i = 0; _i < 2; ++_i) \
;         __builtin_amdgcn_global_load_lds((const unsigned*)((const char*)(gbase) + (voff)[_i]), (PG8_LAS unsigned*)(lds + (bufoff) + ldsw + _i * 8192), 16, 0, 0); } while (0)
; #define PG8_WAIT_V(n) asm volatile("s_waitcnt vmcnt(" #n ")" ::: "memory")
; #define PG8_BAR __builtin_amdgcn_s_barrier()
; template <class Epi, class Sched, bool ALIGN_EPI = false, bool SP2 = false>
; __device__ __forceinline__ void gemm_phase(PG8_LAS unsigned char* lds, const Gemm g, const Sched& S, const Epi& E) {
;     ...
;     for (int i = 0; i < 2; ++i) { int R, C; stage_rc(tid * 16 + i * 8192, R, C); const int Rb = Epi::PERM ? ((R & ~31) + perm32(R & 31)) : R;
;         voffA[i] = (unsigned)(R * K + C) * 2u; voffB[i] = (unsigned)(Rb * K + C) * 2u; }
;     const size_t kstep = (size_t)(BK * 2);
;     const size_t hstep = (size_t)HALF * K * 2;
;     const size_t tstep = 2 * hstep;
;     const unsigned ldsw = (unsigned)wid * 1024u;
;     const int aoff = lds_byte(wr * 64 + fr, fq * 8), boff = lds_byte(wc * 32 + fr, fq * 8);
;     ...
;         if (wr == 1) PG8_BAR;
;         PG8_WAIT_V(2); PG8_BAR;
;         PG8_STAGE(PG8_SB(1, 0), cB + kstep, voffB); PG8_STAGE(PG8_SA(1, 0), cA + kstep, voffA); PG8_STAGE(PG8_SB(1, 1), cB + hstep + kstep, voffB);
;         PG8_WAIT_V(6); PG8_BAR;
.LBB0_819:
	s_add_u32 s16, s6, 0x17500000
	s_mov_b64 s[18:19], 0x80
	s_addc_u32 s17, s7, 0
	s_add_i32 m0, s0, 0x18000
	v_lshl_add_u64 v[10:11], v[10:11], 0, s[18:19]
	s_waitcnt vmcnt(2)
	s_barrier
	global_load_lds_dwordx4 v[10:11], off
	v_lshl_add_u64 v[6:7], v[6:7], 0, s[18:19]
	s_add_i32 m0, s0, 0x1a000
	s_add_i32 s42, s0, 0x8000
	global_load_lds_dwordx4 v[6:7], off
	v_lshl_add_u64 v[6:7], v[8:9], 0, s[18:19]
	s_mov_b32 m0, s42
	s_add_i32 s43, s0, 0xa000
	global_load_lds_dwordx4 v[6:7], off
	v_lshl_add_u64 v[6:7], v[12:13], 0, s[18:19]
	s_mov_b32 m0, s43
	v_lshl_add_u64 v[4:5], v[4:5], 0, s[18:19]
	global_load_lds_dwordx4 v[6:7], off
	s_add_i32 m0, s0, 0x1c000
	v_lshl_add_u64 v[2:3], v[2:3], 0, s[18:19]
	global_load_lds_dwordx4 v[4:5], off
	s_add_i32 m0, s0, 0x1e000
	s_lshr_b32 s5, s5, 26
	global_load_lds_dwordx4 v[2:3], off
	v_and_b32_e32 v2, 15, v0
	s_add_i32 s5, s4, s5
	v_lshlrev_b32_e32 v3, 1, v18
	v_lshlrev_b32_e32 v4, 2, v0
	s_ashr_i32 s44, s5, 6
	v_lshl_or_b32 v1, s23, 6, v2
	v_lshl_or_b32 v2, v2, 6, v3
	s_lshl_b32 s5, s23, 13
	v_and_b32_e32 v4, 32, v4
	v_bitop3_b32 v5, v2, s5, v4 bitop3:0xde
	s_lshl_b32 s5, s21, 5
	s_and_b32 s5, s5, 0x60
	v_lshlrev_b32_e32 v2, 6, v0
	s_movk_i32 s6, 0x3c0
	v_and_or_b32 v2, v2, s6, v3
	s_lshl_b32 s6, s5, 7
	v_bitop3_b32 v146, s6, v2, v4 bitop3:0xf6
	v_add_u32_e32 v2, v19, v16
	v_mul_lo_u32 v2, s4, v2
	v_lshlrev_b32_e32 v2, 1, v2
	v_add3_u32 v2, v14, v2, v15
	v_mov_b32_e32 v3, v133
	s_cmp_gt_i32 s4, 63
	v_lshl_add_u64 v[138:139], s[10:11], 0, v[2:3]
	v_add_u32_e32 v2, v17, v16
	s_sext_i32_i8 s55, s20
	s_cselect_b64 s[20:21], -1, 0
	s_add_i32 s45, s44, -2
	v_mul_lo_u32 v2, s4, v2
	s_waitcnt vmcnt(6)
	s_cmpk_lt_u32 s22, 0x100
	v_lshlrev_b32_e32 v2, 1, v2
	s_cselect_b64 s[22:23], -1, 0
	v_add3_u32 v2, v14, v2, v15
	s_add_i32 s48, 0, 0x10000
	s_add_i32 s49, 0, 0x14000
	s_ashr_i32 s46, s82, 31
	s_mov_b32 s47, s82
	v_or_b32_e32 v147, s5, v18
	v_lshl_add_u64 v[140:141], s[10:11], 0, v[2:3]
	v_mov_b64_e32 v[142:143], 0x200
	v_mov_b64_e32 v[144:145], 0x1ff
	v_add_u32_e32 v148, s48, v146
	v_add_u32_e32 v149, s49, v146
	v_add_u32_e32 v150, 0, v5
	s_barrier
	s_waitcnt vmcnt(0)
	s_branch .LBB0_822
	.p2align	6

; #define PG8_BAR __builtin_amdgcn_s_barrier()
; template <class Epi, class Sched, bool ALIGN_EPI = false, bool SP2 = false>
; __device__ __forceinline__ void gemm_phase(PG8_LAS unsigned char* lds, const Gemm g, const Sched& S, const Epi& E) {
;     ...
; #pragma unroll
;         for (int a = 0; a < 2; ++a)
; #pragma unroll
;             for (int b = 0; b < 2; ++b)
; #pragma unroll
;                 for (int m = 0; m < 4; ++m)
; #pragma unroll
;                     for (int n = 0; n < 2; ++n) acc[a][b][m][n] = (f32x4){0.f, 0.f, 0.f, 0.f};
;         cur = nxt; cA = nA; cB = nB; ++ui;
;         if constexpr (ALIGN_EPI) { if (wr == 1) PG8_BAR; }
.LBB0_832:
	v_mov_b32_e32 v125, 0
	s_andn2_b64 vcc, exec, s[20:21]
	v_mov_b32_e32 v124, v125
	v_mov_b32_e32 v123, v125
	v_mov_b32_e32 v122, v125
	v_mov_b32_e32 v129, v125
	v_mov_b32_e32 v128, v125
	v_mov_b32_e32 v127, v125
	v_mov_b32_e32 v126, v125
	v_mov_b32_e32 v113, v125
	v_mov_b32_e32 v112, v125
	v_mov_b32_e32 v111, v125
	v_mov_b32_e32 v110, v125
	v_mov_b32_e32 v109, v125
	v_mov_b32_e32 v108, v125
	v_mov_b32_e32 v107, v125
	v_mov_b32_e32 v106, v125
	v_mov_b32_e32 v97, v125
	v_mov_b32_e32 v96, v125
	v_mov_b32_e32 v95, v125
	v_mov_b32_e32 v94, v125
	v_mov_b32_e32 v93, v125
	v_mov_b32_e32 v92, v125
	v_mov_b32_e32 v91, v125
	v_mov_b32_e32 v90, v125
	v_mov_b32_e32 v81, v125
	v_mov_b32_e32 v80, v125
	v_mov_b32_e32 v79, v125
	v_mov_b32_e32 v78, v125
	v_mov_b32_e32 v77, v125
	v_mov_b32_e32 v76, v125
	v_mov_b32_e32 v75, v125
	v_mov_b32_e32 v74, v125
	v_mov_b32_e32 v121, v125
	v_mov_b32_e32 v120, v125
	v_mov_b32_e32 v119, v125
	v_mov_b32_e32 v118, v125
	v_mov_b32_e32 v117, v125
	v_mov_b32_e32 v116, v125
	v_mov_b32_e32 v115, v125
	v_mov_b32_e32 v114, v125
	v_mov_b32_e32 v105, v125
	v_mov_b32_e32 v104, v125
	v_mov_b32_e32 v103, v125
	v_mov_b32_e32 v102, v125
	v_mov_b32_e32 v101, v125
	v_mov_b32_e32 v100, v125
	v_mov_b32_e32 v99, v125
	v_mov_b32_e32 v98, v125
	v_mov_b32_e32 v89, v125
	v_mov_b32_e32 v88, v125
	v_mov_b32_e32 v87, v125
	v_mov_b32_e32 v86, v125
	v_mov_b32_e32 v85, v125
	v_mov_b32_e32 v84, v125
	v_mov_b32_e32 v83, v125
	v_mov_b32_e32 v82, v125
	v_mov_b32_e32 v73, v125
	v_mov_b32_e32 v72, v125
	v_mov_b32_e32 v71, v125
	v_mov_b32_e32 v70, v125
	v_mov_b32_e32 v69, v125
	v_mov_b32_e32 v68, v125
	v_mov_b32_e32 v67, v125
	v_mov_b32_e32 v66, v125
	v_mov_b32_e32 v65, v125
	v_mov_b32_e32 v64, v125
	v_mov_b32_e32 v63, v125
	v_mov_b32_e32 v62, v125
	v_mov_b32_e32 v61, v125
	v_mov_b32_e32 v60, v125
	v_mov_b32_e32 v59, v125
	v_mov_b32_e32 v58, v125
	v_mov_b32_e32 v49, v125
	v_mov_b32_e32 v48, v125
	v_mov_b32_e32 v47, v125
	v_mov_b32_e32 v46, v125
	v_mov_b32_e32 v45, v125
	v_mov_b32_e32 v44, v125
	v_mov_b32_e32 v43, v125
	v_mov_b32_e32 v42, v125
	v_mov_b32_e32 v33, v125
	v_mov_b32_e32 v32, v125
	v_mov_b32_e32 v31, v125
	v_mov_b32_e32 v30, v125
	v_mov_b32_e32 v29, v125
	v_mov_b32_e32 v28, v125
	v_mov_b32_e32 v27, v125
	v_mov_b32_e32 v26, v125
	v_mov_b32_e32 v17, v125
	v_mov_b32_e32 v16, v125
	v_mov_b32_e32 v15, v125
	v_mov_b32_e32 v14, v125
	v_mov_b32_e32 v13, v125
	v_mov_b32_e32 v12, v125
	v_mov_b32_e32 v11, v125
	v_mov_b32_e32 v10, v125
	v_mov_b32_e32 v57, v125
	v_mov_b32_e32 v56, v125
	v_mov_b32_e32 v55, v125
	v_mov_b32_e32 v54, v125
	v_mov_b32_e32 v53, v125
	v_mov_b32_e32 v52, v125
	v_mov_b32_e32 v51, v125
	v_mov_b32_e32 v50, v125
	v_mov_b32_e32 v41, v125
	v_mov_b32_e32 v40, v125
	v_mov_b32_e32 v39, v125
	v_mov_b32_e32 v38, v125
	v_mov_b32_e32 v37, v125
	v_mov_b32_e32 v36, v125
	v_mov_b32_e32 v35, v125
	v_mov_b32_e32 v34, v125
	v_mov_b32_e32 v25, v125
	v_mov_b32_e32 v24, v125
	v_mov_b32_e32 v23, v125
	v_mov_b32_e32 v22, v125
	v_mov_b32_e32 v21, v125
	v_mov_b32_e32 v20, v125
	v_mov_b32_e32 v19, v125
	v_mov_b32_e32 v18, v125
	v_mov_b32_e32 v9, v125
	v_mov_b32_e32 v8, v125
	v_mov_b32_e32 v7, v125
	v_mov_b32_e32 v6, v125
	v_mov_b32_e32 v5, v125
	v_mov_b32_e32 v4, v125
	v_mov_b32_e32 v3, v125
	v_mov_b32_e32 v2, v125
	s_cbranch_vccnz .LBB0_835
	s_add_u32 s56, s28, 0x100
	s_addc_u32 s57, s29, 0
	s_add_u32 s28, s30, 0x80
	v_mov_b32_e32 v2, 0
	s_addc_u32 s29, s31, 0
	s_mov_b32 s30, 0
	v_mov_b32_e32 v3, v2
	v_mov_b32_e32 v4, v2
	v_mov_b32_e32 v5, v2
	v_mov_b32_e32 v6, v2
	v_mov_b32_e32 v7, v2
	v_mov_b32_e32 v8, v2
	v_mov_b32_e32 v9, v2
	v_mov_b32_e32 v18, v2
	v_mov_b32_e32 v19, v2
	v_mov_b32_e32 v20, v2
	v_mov_b32_e32 v21, v2
	v_mov_b32_e32 v22, v2
	v_mov_b32_e32 v23, v2
	v_mov_b32_e32 v24, v2
	v_mov_b32_e32 v25, v2
	v_mov_b32_e32 v34, v2
	v_mov_b32_e32 v35, v2
	v_mov_b32_e32 v36, v2
	v_mov_b32_e32 v37, v2
	v_mov_b32_e32 v38, v2
	v_mov_b32_e32 v39, v2
	v_mov_b32_e32 v40, v2
	v_mov_b32_e32 v41, v2
	v_mov_b32_e32 v50, v2
	v_mov_b32_e32 v51, v2
	v_mov_b32_e32 v52, v2
	v_mov_b32_e32 v53, v2
	v_mov_b32_e32 v54, v2
	v_mov_b32_e32 v55, v2
	v_mov_b32_e32 v56, v2
	v_mov_b32_e32 v57, v2
	v_mov_b32_e32 v10, v2
	v_mov_b32_e32 v11, v2
	v_mov_b32_e32 v12, v2
	v_mov_b32_e32 v13, v2
	v_mov_b32_e32 v14, v2
	v_mov_b32_e32 v15, v2
	v_mov_b32_e32 v16, v2
	v_mov_b32_e32 v17, v2
	v_mov_b32_e32 v26, v2
	v_mov_b32_e32 v27, v2
	v_mov_b32_e32 v28, v2
	v_mov_b32_e32 v29, v2
	v_mov_b32_e32 v30, v2
	v_mov_b32_e32 v31, v2
	v_mov_b32_e32 v32, v2
	v_mov_b32_e32 v33, v2
	v_mov_b32_e32 v42, v2
	v_mov_b32_e32 v43, v2
	v_mov_b32_e32 v44, v2
	v_mov_b32_e32 v45, v2
	v_mov_b32_e32 v46, v2
	v_mov_b32_e32 v47, v2
	v_mov_b32_e32 v48, v2
	v_mov_b32_e32 v49, v2
	v_mov_b32_e32 v58, v2
	v_mov_b32_e32 v59, v2
	v_mov_b32_e32 v60, v2
	v_mov_b32_e32 v61, v2
	v_mov_b32_e32 v62, v2
	v_mov_b32_e32 v63, v2
	v_mov_b32_e32 v64, v2
	v_mov_b32_e32 v65, v2
	v_mov_b32_e32 v66, v2
	v_mov_b32_e32 v67, v2
	v_mov_b32_e32 v68, v2
	v_mov_b32_e32 v69, v2
	v_mov_b32_e32 v70, v2
	v_mov_b32_e32 v71, v2
	v_mov_b32_e32 v72, v2
	v_mov_b32_e32 v73, v2
	v_mov_b32_e32 v82, v2
	v_mov_b32_e32 v83, v2
	v_mov_b32_e32 v84, v2
	v_mov_b32_e32 v85, v2
	v_mov_b32_e32 v86, v2
	v_mov_b32_e32 v87, v2
	v_mov_b32_e32 v88, v2
	v_mov_b32_e32 v89, v2
	v_mov_b32_e32 v98, v2
	v_mov_b32_e32 v99, v2
	v_mov_b32_e32 v100, v2
	v_mov_b32_e32 v101, v2
	v_mov_b32_e32 v102, v2
	v_mov_b32_e32 v103, v2
	v_mov_b32_e32 v104, v2
	v_mov_b32_e32 v105, v2
	v_mov_b32_e32 v114, v2
	v_mov_b32_e32 v115, v2
	v_mov_b32_e32 v116, v2
	v_mov_b32_e32 v117, v2
	v_mov_b32_e32 v118, v2
	v_mov_b32_e32 v119, v2
	v_mov_b32_e32 v120, v2
	v_mov_b32_e32 v121, v2
	v_mov_b32_e32 v74, v2
	v_mov_b32_e32 v75, v2
	v_mov_b32_e32 v76, v2
	v_mov_b32_e32 v77, v2
	v_mov_b32_e32 v78, v2
	v_mov_b32_e32 v79, v2
	v_mov_b32_e32 v80, v2
	v_mov_b32_e32 v81, v2
	v_mov_b32_e32 v90, v2
	v_mov_b32_e32 v91, v2
	v_mov_b32_e32 v92, v2
	v_mov_b32_e32 v93, v2
	v_mov_b32_e32 v94, v2
	v_mov_b32_e32 v95, v2
	v_mov_b32_e32 v96, v2
	v_mov_b32_e32 v97, v2
	v_mov_b32_e32 v106, v2
	v_mov_b32_e32 v107, v2
	v_mov_b32_e32 v108, v2
	v_mov_b32_e32 v109, v2
	v_mov_b32_e32 v110, v2
	v_mov_b32_e32 v111, v2
	v_mov_b32_e32 v112, v2
	v_mov_b32_e32 v113, v2
	v_mov_b32_e32 v126, v2
	v_mov_b32_e32 v127, v2
	v_mov_b32_e32 v128, v2
	v_mov_b32_e32 v129, v2
	v_mov_b32_e32 v122, v2
	v_mov_b32_e32 v123, v2
	v_mov_b32_e32 v124, v2
	v_mov_b32_e32 v125, v2
	.p2align	6

; #define PG8_STAGE(bufoff, gbase, voff) do { _Pragma("unroll") for (int _i = 0; _i < 2; ++_i) \
;         __builtin_amdgcn_global_load_lds((const unsigned*)((const char*)(gbase) + (voff)[_i]), (PG8_LAS unsigned*)(lds + (bufoff) + ldsw + _i * 8192), 16, 0, 0); } while (0)
; #define PG8_WAIT_V(n) asm volatile("s_waitcnt vmcnt(" #n ")" ::: "memory")
; #define PG8_BAR __builtin_amdgcn_s_barrier()
; template <class Epi, class Sched, bool ALIGN_EPI = false, bool SP2 = false>
; __device__ __forceinline__ void gemm_phase(PG8_LAS unsigned char* lds, const Gemm g, const Sched& S, const Epi& E) {
;     ...
;     for (int i = 0; i < 2; ++i) { int R, C; stage_rc(tid * 16 + i * 8192, R, C); const int Rb = Epi::PERM ? ((R & ~31) + perm32(R & 31)) : R;
;         voffA[i] = (unsigned)(R * K + C) * 2u; voffB[i] = (unsigned)(Rb * K + C) * 2u; }
;     const size_t kstep = (size_t)(BK * 2);
;     const size_t hstep = (size_t)HALF * K * 2;
;     const size_t tstep = 2 * hstep;
;     const unsigned ldsw = (unsigned)wid * 1024u;
;     const int aoff = lds_byte(wr * 64 + fr, fq * 8), boff = lds_byte(wc * 32 + fr, fq * 8);
;     ...
;         if (wr == 1) PG8_BAR;
;         PG8_WAIT_V(2); PG8_BAR;
;         PG8_STAGE(PG8_SB(1, 0), cB + kstep, voffB); PG8_STAGE(PG8_SA(1, 0), cA + kstep, voffA); PG8_STAGE(PG8_SB(1, 1), cB + hstep + kstep, voffB);
;         PG8_WAIT_V(6); PG8_BAR;
.LBB0_1143:
	s_add_u32 s18, s4, 0x17500000
	s_addc_u32 s19, s5, 0
	s_add_u32 s20, s4, 0x17d00000
	s_addc_u32 s21, s5, 0
	s_add_u32 s22, s4, 0x18500000
	s_mov_b64 s[24:25], 0x80
	s_addc_u32 s23, s5, 0
	s_add_i32 m0, s42, 0x18000
	v_lshl_add_u64 v[10:11], v[10:11], 0, s[24:25]
	s_waitcnt vmcnt(2)
	s_barrier
	global_load_lds_dwordx4 v[10:11], off
	v_lshl_add_u64 v[6:7], v[6:7], 0, s[24:25]
	s_add_i32 m0, s42, 0x1a000
	s_add_i32 s52, s42, 0x8000
	global_load_lds_dwordx4 v[6:7], off
	v_lshl_add_u64 v[6:7], v[8:9], 0, s[24:25]
	s_mov_b32 m0, s52
	s_add_i32 s53, s42, 0xa000
	global_load_lds_dwordx4 v[6:7], off
	v_lshl_add_u64 v[6:7], v[12:13], 0, s[24:25]
	s_mov_b32 m0, s53
	v_lshl_add_u64 v[4:5], v[4:5], 0, s[24:25]
	global_load_lds_dwordx4 v[6:7], off
	s_add_i32 m0, s42, 0x1c000
	v_lshl_add_u64 v[2:3], v[2:3], 0, s[24:25]
	global_load_lds_dwordx4 v[4:5], off
	s_add_i32 m0, s42, 0x1e000
	s_lshr_b32 s1, s1, 26
	global_load_lds_dwordx4 v[2:3], off
	v_and_b32_e32 v2, 15, v0
	s_add_i32 s1, s0, s1
	v_lshlrev_b32_e32 v3, 1, v18
	v_lshlrev_b32_e32 v4, 2, v0
	s_ashr_i32 s54, s1, 6
	v_lshl_or_b32 v1, s27, 6, v2
	v_lshl_or_b32 v2, v2, 6, v3
	s_lshl_b32 s1, s27, 13
	v_and_b32_e32 v4, 32, v4
	v_bitop3_b32 v2, v2, s1, v4 bitop3:0xde
	s_lshl_b32 s1, s26, 5
	s_and_b32 s1, s1, 0x60
	v_lshlrev_b32_e32 v5, 6, v0
	s_movk_i32 s4, 0x3c0
	v_and_or_b32 v3, v5, s4, v3
	s_lshl_b32 s4, s1, 7
	v_bitop3_b32 v149, s4, v3, v4 bitop3:0xf6
	v_add_u32_e32 v3, v19, v16
	v_mul_lo_u32 v3, s0, v3
	v_lshlrev_b32_e32 v3, 1, v3
	s_cmp_gt_i32 s0, 63
	v_add3_u32 v146, v14, v3, v15
	v_add_u32_e32 v3, v17, v16
	s_cselect_b64 s[26:27], -1, 0
	s_add_i32 s55, s54, -2
	v_mul_lo_u32 v3, s0, v3
	s_waitcnt vmcnt(6)
	s_cmpk_lt_u32 s28, 0x100
	v_lshlrev_b32_e32 v3, 1, v3
	s_cselect_b64 s[28:29], -1, 0
	s_waitcnt vmcnt(0)
	v_lshl_add_u64 v[150:151], s[8:9], 0, v[146:147]
	v_add3_u32 v146, v14, v3, v15
	s_add_i32 s69, 0, 0x10000
	s_add_i32 s86, 0, 0x14000
	v_or_b32_e32 v148, s1, v18
	s_ashr_i32 s56, s82, 31
	s_mov_b32 s57, s82
	s_ashr_i32 s68, s2, 31
	v_lshl_add_u64 v[152:153], s[8:9], 0, v[146:147]
	v_mov_b64_e32 v[154:155], 0xc0
	v_mov_b64_e32 v[156:157], 0xbf
	v_add_u32_e32 v160, s69, v149
	v_add_u32_e32 v161, s86, v149
	v_add_u32_e32 v162, 0, v2
	s_barrier
	s_branch .LBB0_1146
	.p2align	6
.LBB0_1144:
	s_mov_b64 s[0:1], 0
	.p2align	6

; #define PG8_BAR __builtin_amdgcn_s_barrier()
; template <class Epi, class Sched, bool ALIGN_EPI = false, bool SP2 = false>
; __device__ __forceinline__ void gemm_phase(PG8_LAS unsigned char* lds, const Gemm g, const Sched& S, const Epi& E) {
;     ...
; #pragma unroll
;         for (int a = 0; a < 2; ++a)
; #pragma unroll
;             for (int b = 0; b < 2; ++b)
; #pragma unroll
;                 for (int m = 0; m < 4; ++m)
; #pragma unroll
;                     for (int n = 0; n < 2; ++n) acc[a][b][m][n] = (f32x4){0.f, 0.f, 0.f, 0.f};
;         cur = nxt; cA = nA; cB = nB; ++ui;
;         if constexpr (ALIGN_EPI) { if (wr == 1) PG8_BAR; }
.LBB0_1152:
	v_mov_b32_e32 v129, 0
	s_andn2_b64 vcc, exec, s[26:27]
	v_mov_b32_e32 v128, v129
	v_mov_b32_e32 v127, v129
	v_mov_b32_e32 v126, v129
	v_mov_b32_e32 v125, v129
	v_mov_b32_e32 v124, v129
	v_mov_b32_e32 v123, v129
	v_mov_b32_e32 v122, v129
	v_mov_b32_e32 v113, v129
	v_mov_b32_e32 v112, v129
	v_mov_b32_e32 v111, v129
	v_mov_b32_e32 v110, v129
	v_mov_b32_e32 v109, v129
	v_mov_b32_e32 v108, v129
	v_mov_b32_e32 v107, v129
	v_mov_b32_e32 v106, v129
	v_mov_b32_e32 v97, v129
	v_mov_b32_e32 v96, v129
	v_mov_b32_e32 v95, v129
	v_mov_b32_e32 v94, v129
	v_mov_b32_e32 v93, v129
	v_mov_b32_e32 v92, v129
	v_mov_b32_e32 v91, v129
	v_mov_b32_e32 v90, v129
	v_mov_b32_e32 v81, v129
	v_mov_b32_e32 v80, v129
	v_mov_b32_e32 v79, v129
	v_mov_b32_e32 v78, v129
	v_mov_b32_e32 v77, v129
	v_mov_b32_e32 v76, v129
	v_mov_b32_e32 v75, v129
	v_mov_b32_e32 v74, v129
	v_mov_b32_e32 v121, v129
	v_mov_b32_e32 v120, v129
	v_mov_b32_e32 v119, v129
	v_mov_b32_e32 v118, v129
	v_mov_b32_e32 v117, v129
	v_mov_b32_e32 v116, v129
	v_mov_b32_e32 v115, v129
	v_mov_b32_e32 v114, v129
	v_mov_b32_e32 v105, v129
	v_mov_b32_e32 v104, v129
	v_mov_b32_e32 v103, v129
	v_mov_b32_e32 v102, v129
	v_mov_b32_e32 v101, v129
	v_mov_b32_e32 v100, v129
	v_mov_b32_e32 v99, v129
	v_mov_b32_e32 v98, v129
	v_mov_b32_e32 v89, v129
	v_mov_b32_e32 v88, v129
	v_mov_b32_e32 v87, v129
	v_mov_b32_e32 v86, v129
	v_mov_b32_e32 v85, v129
	v_mov_b32_e32 v84, v129
	v_mov_b32_e32 v83, v129
	v_mov_b32_e32 v82, v129
	v_mov_b32_e32 v73, v129
	v_mov_b32_e32 v72, v129
	v_mov_b32_e32 v71, v129
	v_mov_b32_e32 v70, v129
	v_mov_b32_e32 v69, v129
	v_mov_b32_e32 v68, v129
	v_mov_b32_e32 v67, v129
	v_mov_b32_e32 v66, v129
	v_mov_b32_e32 v65, v129
	v_mov_b32_e32 v64, v129
	v_mov_b32_e32 v63, v129
	v_mov_b32_e32 v62, v129
	v_mov_b32_e32 v61, v129
	v_mov_b32_e32 v60, v129
	v_mov_b32_e32 v59, v129
	v_mov_b32_e32 v58, v129
	v_mov_b32_e32 v49, v129
	v_mov_b32_e32 v48, v129
	v_mov_b32_e32 v47, v129
	v_mov_b32_e32 v46, v129
	v_mov_b32_e32 v45, v129
	v_mov_b32_e32 v44, v129
	v_mov_b32_e32 v43, v129
	v_mov_b32_e32 v42, v129
	v_mov_b32_e32 v33, v129
	v_mov_b32_e32 v32, v129
	v_mov_b32_e32 v31, v129
	v_mov_b32_e32 v30, v129
	v_mov_b32_e32 v29, v129
	v_mov_b32_e32 v28, v129
	v_mov_b32_e32 v27, v129
	v_mov_b32_e32 v26, v129
	v_mov_b32_e32 v17, v129
	v_mov_b32_e32 v16, v129
	v_mov_b32_e32 v15, v129
	v_mov_b32_e32 v14, v129
	v_mov_b32_e32 v13, v129
	v_mov_b32_e32 v12, v129
	v_mov_b32_e32 v11, v129
	v_mov_b32_e32 v10, v129
	v_mov_b32_e32 v57, v129
	v_mov_b32_e32 v56, v129
	v_mov_b32_e32 v55, v129
	v_mov_b32_e32 v54, v129
	v_mov_b32_e32 v53, v129
	v_mov_b32_e32 v52, v129
	v_mov_b32_e32 v51, v129
	v_mov_b32_e32 v50, v129
	v_mov_b32_e32 v41, v129
	v_mov_b32_e32 v40, v129
	v_mov_b32_e32 v39, v129
	v_mov_b32_e32 v38, v129
	v_mov_b32_e32 v37, v129
	v_mov_b32_e32 v36, v129
	v_mov_b32_e32 v35, v129
	v_mov_b32_e32 v34, v129
	v_mov_b32_e32 v25, v129
	v_mov_b32_e32 v24, v129
	v_mov_b32_e32 v23, v129
	v_mov_b32_e32 v22, v129
	v_mov_b32_e32 v21, v129
	v_mov_b32_e32 v20, v129
	v_mov_b32_e32 v19, v129
	v_mov_b32_e32 v18, v129
	v_mov_b32_e32 v9, v129
	v_mov_b32_e32 v8, v129
	v_mov_b32_e32 v7, v129
	v_mov_b32_e32 v6, v129
	v_mov_b32_e32 v5, v129
	v_mov_b32_e32 v4, v129
	v_mov_b32_e32 v3, v129
	v_mov_b32_e32 v2, v129
	s_cbranch_vccnz .LBB0_1155
	s_add_u32 s45, s34, 0x100
	s_addc_u32 s80, s35, 0
	s_add_u32 s34, s36, 0x80
	v_mov_b32_e32 v2, 0
	s_addc_u32 s35, s37, 0
	s_mov_b32 s36, 0
	v_mov_b32_e32 v3, v2
	v_mov_b32_e32 v4, v2
	v_mov_b32_e32 v5, v2
	v_mov_b32_e32 v6, v2
	v_mov_b32_e32 v7, v2
	v_mov_b32_e32 v8, v2
	v_mov_b32_e32 v9, v2
	v_mov_b32_e32 v18, v2
	v_mov_b32_e32 v19, v2
	v_mov_b32_e32 v20, v2
	v_mov_b32_e32 v21, v2
	v_mov_b32_e32 v22, v2
	v_mov_b32_e32 v23, v2
	v_mov_b32_e32 v24, v2
	v_mov_b32_e32 v25, v2
	v_mov_b32_e32 v34, v2
	v_mov_b32_e32 v35, v2
	v_mov_b32_e32 v36, v2
	v_mov_b32_e32 v37, v2
	v_mov_b32_e32 v38, v2
	v_mov_b32_e32 v39, v2
	v_mov_b32_e32 v40, v2
	v_mov_b32_e32 v41, v2
	v_mov_b32_e32 v50, v2
	v_mov_b32_e32 v51, v2
	v_mov_b32_e32 v52, v2
	v_mov_b32_e32 v53, v2
	v_mov_b32_e32 v54, v2
	v_mov_b32_e32 v55, v2
	v_mov_b32_e32 v56, v2
	v_mov_b32_e32 v57, v2
	v_mov_b32_e32 v10, v2
	v_mov_b32_e32 v11, v2
	v_mov_b32_e32 v12, v2
	v_mov_b32_e32 v13, v2
	v_mov_b32_e32 v14, v2
	v_mov_b32_e32 v15, v2
	v_mov_b32_e32 v16, v2
	v_mov_b32_e32 v17, v2
	v_mov_b32_e32 v26, v2
	v_mov_b32_e32 v27, v2
	v_mov_b32_e32 v28, v2
	v_mov_b32_e32 v29, v2
	v_mov_b32_e32 v30, v2
	v_mov_b32_e32 v31, v2
	v_mov_b32_e32 v32, v2
	v_mov_b32_e32 v33, v2
	v_mov_b32_e32 v42, v2
	v_mov_b32_e32 v43, v2
	v_mov_b32_e32 v44, v2
	v_mov_b32_e32 v45, v2
	v_mov_b32_e32 v46, v2
	v_mov_b32_e32 v47, v2
	v_mov_b32_e32 v48, v2
	v_mov_b32_e32 v49, v2
	v_mov_b32_e32 v58, v2
	v_mov_b32_e32 v59, v2
	v_mov_b32_e32 v60, v2
	v_mov_b32_e32 v61, v2
	v_mov_b32_e32 v62, v2
	v_mov_b32_e32 v63, v2
	v_mov_b32_e32 v64, v2
	v_mov_b32_e32 v65, v2
	v_mov_b32_e32 v66, v2
	v_mov_b32_e32 v67, v2
	v_mov_b32_e32 v68, v2
	v_mov_b32_e32 v69, v2
	v_mov_b32_e32 v70, v2
	v_mov_b32_e32 v71, v2
	v_mov_b32_e32 v72, v2
	v_mov_b32_e32 v73, v2
	v_mov_b32_e32 v82, v2
	v_mov_b32_e32 v83, v2
	v_mov_b32_e32 v84, v2
	v_mov_b32_e32 v85, v2
	v_mov_b32_e32 v86, v2
	v_mov_b32_e32 v87, v2
	v_mov_b32_e32 v88, v2
	v_mov_b32_e32 v89, v2
	v_mov_b32_e32 v98, v2
	v_mov_b32_e32 v99, v2
	v_mov_b32_e32 v100, v2
	v_mov_b32_e32 v101, v2
	v_mov_b32_e32 v102, v2
	v_mov_b32_e32 v103, v2
	v_mov_b32_e32 v104, v2
	v_mov_b32_e32 v105, v2
	v_mov_b32_e32 v114, v2
	v_mov_b32_e32 v115, v2
	v_mov_b32_e32 v116, v2
	v_mov_b32_e32 v117, v2
	v_mov_b32_e32 v118, v2
	v_mov_b32_e32 v119, v2
	v_mov_b32_e32 v120, v2
	v_mov_b32_e32 v121, v2
	v_mov_b32_e32 v74, v2
	v_mov_b32_e32 v75, v2
	v_mov_b32_e32 v76, v2
	v_mov_b32_e32 v77, v2
	v_mov_b32_e32 v78, v2
	v_mov_b32_e32 v79, v2
	v_mov_b32_e32 v80, v2
	v_mov_b32_e32 v81, v2
	v_mov_b32_e32 v90, v2
	v_mov_b32_e32 v91, v2
	v_mov_b32_e32 v92, v2
	v_mov_b32_e32 v93, v2
	v_mov_b32_e32 v94, v2
	v_mov_b32_e32 v95, v2
	v_mov_b32_e32 v96, v2
	v_mov_b32_e32 v97, v2
	v_mov_b32_e32 v106, v2
	v_mov_b32_e32 v107, v2
	v_mov_b32_e32 v108, v2
	v_mov_b32_e32 v109, v2
	v_mov_b32_e32 v110, v2
	v_mov_b32_e32 v111, v2
	v_mov_b32_e32 v112, v2
	v_mov_b32_e32 v113, v2
	v_mov_b32_e32 v122, v2
	v_mov_b32_e32 v123, v2
	v_mov_b32_e32 v124, v2
	v_mov_b32_e32 v125, v2
	v_mov_b32_e32 v126, v2
	v_mov_b32_e32 v127, v2
	v_mov_b32_e32 v128, v2
	v_mov_b32_e32 v129, v2
	.p2align	6

; #define PG8_STAGE(bufoff, gbase, voff) do { _Pragma("unroll") for (int _i = 0; _i < 2; ++_i) \
;         __builtin_amdgcn_global_load_lds((const unsigned*)((const char*)(gbase) + (voff)[_i]), (PG8_LAS unsigned*)(lds + (bufoff) + ldsw + _i * 8192), 16, 0, 0); } while (0)
; #define PG8_WAIT_V(n) asm volatile("s_waitcnt vmcnt(" #n ")" ::: "memory")
; #define PG8_BAR __builtin_amdgcn_s_barrier()
; template <class Epi, class Sched, bool ALIGN_EPI = false, bool SP2 = false>
; __device__ __forceinline__ void gemm_phase(PG8_LAS unsigned char* lds, const Gemm g, const Sched& S, const Epi& E) {
;     ...
;     for (int i = 0; i < 2; ++i) { int R, C; stage_rc(tid * 16 + i * 8192, R, C); const int Rb = Epi::PERM ? ((R & ~31) + perm32(R & 31)) : R;
;         voffA[i] = (unsigned)(R * K + C) * 2u; voffB[i] = (unsigned)(Rb * K + C) * 2u; }
;     const size_t kstep = (size_t)(BK * 2);
;     const size_t hstep = (size_t)HALF * K * 2;
;     const size_t tstep = 2 * hstep;
;     const unsigned ldsw = (unsigned)wid * 1024u;
;     const int aoff = lds_byte(wr * 64 + fr, fq * 8), boff = lds_byte(wc * 32 + fr, fq * 8);
;     ...
;         if (wr == 1) PG8_BAR;
;         PG8_WAIT_V(2); PG8_BAR;
;         PG8_STAGE(PG8_SB(1, 0), cB + kstep, voffB); PG8_STAGE(PG8_SA(1, 0), cA + kstep, voffA); PG8_STAGE(PG8_SB(1, 1), cB + hstep + kstep, voffB);
;         PG8_WAIT_V(6); PG8_BAR;
.LBB0_1360:
	s_add_u32 s22, s4, 0x3500000
	s_mov_b64 s[24:25], 0x80
	s_addc_u32 s23, s5, 0
	s_add_i32 m0, s42, 0x18000
	v_lshl_add_u64 v[10:11], v[10:11], 0, s[24:25]
	s_waitcnt vmcnt(2)
	s_barrier
	global_load_lds_dwordx4 v[10:11], off
	v_lshl_add_u64 v[6:7], v[6:7], 0, s[24:25]
	s_add_i32 m0, s42, 0x1a000
	s_add_i32 s47, s42, 0x8000
	global_load_lds_dwordx4 v[6:7], off
	v_lshl_add_u64 v[6:7], v[8:9], 0, s[24:25]
	s_mov_b32 m0, s47
	s_add_i32 s48, s42, 0xa000
	global_load_lds_dwordx4 v[6:7], off
	v_lshl_add_u64 v[6:7], v[12:13], 0, s[24:25]
	s_mov_b32 m0, s48
	v_lshl_add_u64 v[4:5], v[4:5], 0, s[24:25]
	global_load_lds_dwordx4 v[6:7], off
	s_add_i32 m0, s42, 0x1c000
	v_lshl_add_u64 v[2:3], v[2:3], 0, s[24:25]
	global_load_lds_dwordx4 v[4:5], off
	s_add_i32 m0, s42, 0x1e000
	s_lshr_b32 s1, s1, 26
	global_load_lds_dwordx4 v[2:3], off
	s_add_i32 s1, s0, s1
	v_lshlrev_b32_e32 v3, 2, v150
	s_ashr_i32 s49, s1, 6
	v_lshl_or_b32 v2, v150, 6, v152
	s_lshl_b32 s1, s29, 13
	v_and_b32_e32 v3, 32, v3
	v_bitop3_b32 v4, v2, s1, v3 bitop3:0xde
	v_add_u32_e32 v2, v151, v147
	v_mul_lo_u32 v2, s0, v2
	s_lshl_b32 s1, s27, 5
	v_lshlrev_b32_e32 v2, 1, v2
	s_and_b32 s1, s1, 0x60
	v_add3_u32 v2, v1, v2, v146
	v_mov_b32_e32 v3, v133
	s_cmp_gt_i32 s0, 63
	v_lshl_add_u64 v[138:139], s[14:15], 0, v[2:3]
	v_add_u32_e32 v2, v148, v147
	s_sext_i32_i8 s80, s26
	s_cselect_b64 s[26:27], -1, 0
	s_add_i32 s52, s49, -2
	v_mul_lo_u32 v2, s0, v2
	s_waitcnt vmcnt(6)
	s_cmpk_lt_u32 s28, 0x100
	v_lshlrev_b32_e32 v2, 1, v2
	v_lshl_or_b32 v159, s29, 6, v150
	v_lshl_or_b32 v160, s1, 7, v153
	s_cselect_b64 s[28:29], -1, 0
	v_add3_u32 v2, v1, v2, v146
	s_add_i32 s55, 0, 0x10000
	s_add_i32 s56, 0, 0x14000
	s_ashr_i32 s53, s82, 31
	s_mov_b32 s54, s82
	v_or_b32_e32 v161, s1, v149
	v_lshl_add_u64 v[140:141], s[14:15], 0, v[2:3]
	v_mov_b64_e32 v[142:143], 0x200
	v_mov_b64_e32 v[144:145], 0x1ff
	v_add_u32_e32 v162, s55, v160
	v_add_u32_e32 v163, s56, v160
	v_add_u32_e32 v164, 0, v4
	s_barrier
	s_branch .LBB0_1363
	.p2align	6

; #define PG8_BAR __builtin_amdgcn_s_barrier()
; template <class Epi, class Sched, bool ALIGN_EPI = false, bool SP2 = false>
; __device__ __forceinline__ void gemm_phase(PG8_LAS unsigned char* lds, const Gemm g, const Sched& S, const Epi& E) {
;     ...
; #pragma unroll
;         for (int a = 0; a < 2; ++a)
; #pragma unroll
;             for (int b = 0; b < 2; ++b)
; #pragma unroll
;                 for (int m = 0; m < 4; ++m)
; #pragma unroll
;                     for (int n = 0; n < 2; ++n) acc[a][b][m][n] = (f32x4){0.f, 0.f, 0.f, 0.f};
;         cur = nxt; cA = nA; cB = nB; ++ui;
;         if constexpr (ALIGN_EPI) { if (wr == 1) PG8_BAR; }
.LBB0_1373:
	v_mov_b32_e32 v125, 0
	s_andn2_b64 vcc, exec, s[26:27]
	v_mov_b32_e32 v124, v125
	v_mov_b32_e32 v123, v125
	v_mov_b32_e32 v122, v125
	v_mov_b32_e32 v129, v125
	v_mov_b32_e32 v128, v125
	v_mov_b32_e32 v127, v125
	v_mov_b32_e32 v126, v125
	v_mov_b32_e32 v113, v125
	v_mov_b32_e32 v112, v125
	v_mov_b32_e32 v111, v125
	v_mov_b32_e32 v110, v125
	v_mov_b32_e32 v109, v125
	v_mov_b32_e32 v108, v125
	v_mov_b32_e32 v107, v125
	v_mov_b32_e32 v106, v125
	v_mov_b32_e32 v97, v125
	v_mov_b32_e32 v96, v125
	v_mov_b32_e32 v95, v125
	v_mov_b32_e32 v94, v125
	v_mov_b32_e32 v93, v125
	v_mov_b32_e32 v92, v125
	v_mov_b32_e32 v91, v125
	v_mov_b32_e32 v90, v125
	v_mov_b32_e32 v81, v125
	v_mov_b32_e32 v80, v125
	v_mov_b32_e32 v79, v125
	v_mov_b32_e32 v78, v125
	v_mov_b32_e32 v77, v125
	v_mov_b32_e32 v76, v125
	v_mov_b32_e32 v75, v125
	v_mov_b32_e32 v74, v125
	v_mov_b32_e32 v121, v125
	v_mov_b32_e32 v120, v125
	v_mov_b32_e32 v119, v125
	v_mov_b32_e32 v118, v125
	v_mov_b32_e32 v117, v125
	v_mov_b32_e32 v116, v125
	v_mov_b32_e32 v115, v125
	v_mov_b32_e32 v114, v125
	v_mov_b32_e32 v105, v125
	v_mov_b32_e32 v104, v125
	v_mov_b32_e32 v103, v125
	v_mov_b32_e32 v102, v125
	v_mov_b32_e32 v101, v125
	v_mov_b32_e32 v100, v125
	v_mov_b32_e32 v99, v125
	v_mov_b32_e32 v98, v125
	v_mov_b32_e32 v89, v125
	v_mov_b32_e32 v88, v125
	v_mov_b32_e32 v87, v125
	v_mov_b32_e32 v86, v125
	v_mov_b32_e32 v85, v125
	v_mov_b32_e32 v84, v125
	v_mov_b32_e32 v83, v125
	v_mov_b32_e32 v82, v125
	v_mov_b32_e32 v73, v125
	v_mov_b32_e32 v72, v125
	v_mov_b32_e32 v71, v125
	v_mov_b32_e32 v70, v125
	v_mov_b32_e32 v69, v125
	v_mov_b32_e32 v68, v125
	v_mov_b32_e32 v67, v125
	v_mov_b32_e32 v66, v125
	v_mov_b32_e32 v65, v125
	v_mov_b32_e32 v64, v125
	v_mov_b32_e32 v63, v125
	v_mov_b32_e32 v62, v125
	v_mov_b32_e32 v61, v125
	v_mov_b32_e32 v60, v125
	v_mov_b32_e32 v59, v125
	v_mov_b32_e32 v58, v125
	v_mov_b32_e32 v49, v125
	v_mov_b32_e32 v48, v125
	v_mov_b32_e32 v47, v125
	v_mov_b32_e32 v46, v125
	v_mov_b32_e32 v45, v125
	v_mov_b32_e32 v44, v125
	v_mov_b32_e32 v43, v125
	v_mov_b32_e32 v42, v125
	v_mov_b32_e32 v33, v125
	v_mov_b32_e32 v32, v125
	v_mov_b32_e32 v31, v125
	v_mov_b32_e32 v30, v125
	v_mov_b32_e32 v29, v125
	v_mov_b32_e32 v28, v125
	v_mov_b32_e32 v27, v125
	v_mov_b32_e32 v26, v125
	v_mov_b32_e32 v17, v125
	v_mov_b32_e32 v16, v125
	v_mov_b32_e32 v15, v125
	v_mov_b32_e32 v14, v125
	v_mov_b32_e32 v13, v125
	v_mov_b32_e32 v12, v125
	v_mov_b32_e32 v11, v125
	v_mov_b32_e32 v10, v125
	v_mov_b32_e32 v57, v125
	v_mov_b32_e32 v56, v125
	v_mov_b32_e32 v55, v125
	v_mov_b32_e32 v54, v125
	v_mov_b32_e32 v53, v125
	v_mov_b32_e32 v52, v125
	v_mov_b32_e32 v51, v125
	v_mov_b32_e32 v50, v125
	v_mov_b32_e32 v41, v125
	v_mov_b32_e32 v40, v125
	v_mov_b32_e32 v39, v125
	v_mov_b32_e32 v38, v125
	v_mov_b32_e32 v37, v125
	v_mov_b32_e32 v36, v125
	v_mov_b32_e32 v35, v125
	v_mov_b32_e32 v34, v125
	v_mov_b32_e32 v25, v125
	v_mov_b32_e32 v24, v125
	v_mov_b32_e32 v23, v125
	v_mov_b32_e32 v22, v125
	v_mov_b32_e32 v21, v125
	v_mov_b32_e32 v20, v125
	v_mov_b32_e32 v19, v125
	v_mov_b32_e32 v18, v125
	v_mov_b32_e32 v9, v125
	v_mov_b32_e32 v8, v125
	v_mov_b32_e32 v7, v125
	v_mov_b32_e32 v6, v125
	v_mov_b32_e32 v5, v125
	v_mov_b32_e32 v4, v125
	v_mov_b32_e32 v3, v125
	v_mov_b32_e32 v2, v125
	s_cbranch_vccnz .LBB0_1376
	s_add_u32 s81, s34, 0x100
	s_addc_u32 s86, s35, 0
	s_add_u32 s34, s36, 0x80
	v_mov_b32_e32 v2, 0
	s_addc_u32 s35, s37, 0
	s_mov_b32 s36, 0
	v_mov_b32_e32 v3, v2
	v_mov_b32_e32 v4, v2
	v_mov_b32_e32 v5, v2
	v_mov_b32_e32 v6, v2
	v_mov_b32_e32 v7, v2
	v_mov_b32_e32 v8, v2
	v_mov_b32_e32 v9, v2
	v_mov_b32_e32 v18, v2
	v_mov_b32_e32 v19, v2
	v_mov_b32_e32 v20, v2
	v_mov_b32_e32 v21, v2
	v_mov_b32_e32 v22, v2
	v_mov_b32_e32 v23, v2
	v_mov_b32_e32 v24, v2
	v_mov_b32_e32 v25, v2
	v_mov_b32_e32 v34, v2
	v_mov_b32_e32 v35, v2
	v_mov_b32_e32 v36, v2
	v_mov_b32_e32 v37, v2
	v_mov_b32_e32 v38, v2
	v_mov_b32_e32 v39, v2
	v_mov_b32_e32 v40, v2
	v_mov_b32_e32 v41, v2
	v_mov_b32_e32 v50, v2
	v_mov_b32_e32 v51, v2
	v_mov_b32_e32 v52, v2
	v_mov_b32_e32 v53, v2
	v_mov_b32_e32 v54, v2
	v_mov_b32_e32 v55, v2
	v_mov_b32_e32 v56, v2
	v_mov_b32_e32 v57, v2
	v_mov_b32_e32 v10, v2
	v_mov_b32_e32 v11, v2
	v_mov_b32_e32 v12, v2
	v_mov_b32_e32 v13, v2
	v_mov_b32_e32 v14, v2
	v_mov_b32_e32 v15, v2
	v_mov_b32_e32 v16, v2
	v_mov_b32_e32 v17, v2
	v_mov_b32_e32 v26, v2
	v_mov_b32_e32 v27, v2
	v_mov_b32_e32 v28, v2
	v_mov_b32_e32 v29, v2
	v_mov_b32_e32 v30, v2
	v_mov_b32_e32 v31, v2
	v_mov_b32_e32 v32, v2
	v_mov_b32_e32 v33, v2
	v_mov_b32_e32 v42, v2
	v_mov_b32_e32 v43, v2
	v_mov_b32_e32 v44, v2
	v_mov_b32_e32 v45, v2
	v_mov_b32_e32 v46, v2
	v_mov_b32_e32 v47, v2
	v_mov_b32_e32 v48, v2
	v_mov_b32_e32 v49, v2
	v_mov_b32_e32 v58, v2
	v_mov_b32_e32 v59, v2
	v_mov_b32_e32 v60, v2
	v_mov_b32_e32 v61, v2
	v_mov_b32_e32 v62, v2
	v_mov_b32_e32 v63, v2
	v_mov_b32_e32 v64, v2
	v_mov_b32_e32 v65, v2
	v_mov_b32_e32 v66, v2
	v_mov_b32_e32 v67, v2
	v_mov_b32_e32 v68, v2
	v_mov_b32_e32 v69, v2
	v_mov_b32_e32 v70, v2
	v_mov_b32_e32 v71, v2
	v_mov_b32_e32 v72, v2
	v_mov_b32_e32 v73, v2
	v_mov_b32_e32 v82, v2
	v_mov_b32_e32 v83, v2
	v_mov_b32_e32 v84, v2
	v_mov_b32_e32 v85, v2
	v_mov_b32_e32 v86, v2
	v_mov_b32_e32 v87, v2
	v_mov_b32_e32 v88, v2
	v_mov_b32_e32 v89, v2
	v_mov_b32_e32 v98, v2
	v_mov_b32_e32 v99, v2
	v_mov_b32_e32 v100, v2
	v_mov_b32_e32 v101, v2
	v_mov_b32_e32 v102, v2
	v_mov_b32_e32 v103, v2
	v_mov_b32_e32 v104, v2
	v_mov_b32_e32 v105, v2
	v_mov_b32_e32 v114, v2
	v_mov_b32_e32 v115, v2
	v_mov_b32_e32 v116, v2
	v_mov_b32_e32 v117, v2
	v_mov_b32_e32 v118, v2
	v_mov_b32_e32 v119, v2
	v_mov_b32_e32 v120, v2
	v_mov_b32_e32 v121, v2
	v_mov_b32_e32 v74, v2
	v_mov_b32_e32 v75, v2
	v_mov_b32_e32 v76, v2
	v_mov_b32_e32 v77, v2
	v_mov_b32_e32 v78, v2
	v_mov_b32_e32 v79, v2
	v_mov_b32_e32 v80, v2
	v_mov_b32_e32 v81, v2
	v_mov_b32_e32 v90, v2
	v_mov_b32_e32 v91, v2
	v_mov_b32_e32 v92, v2
	v_mov_b32_e32 v93, v2
	v_mov_b32_e32 v94, v2
	v_mov_b32_e32 v95, v2
	v_mov_b32_e32 v96, v2
	v_mov_b32_e32 v97, v2
	v_mov_b32_e32 v106, v2
	v_mov_b32_e32 v107, v2
	v_mov_b32_e32 v108, v2
	v_mov_b32_e32 v109, v2
	v_mov_b32_e32 v110, v2
	v_mov_b32_e32 v111, v2
	v_mov_b32_e32 v112, v2
	v_mov_b32_e32 v113, v2
	v_mov_b32_e32 v126, v2
	v_mov_b32_e32 v127, v2
	v_mov_b32_e32 v128, v2
	v_mov_b32_e32 v129, v2
	v_mov_b32_e32 v122, v2
	v_mov_b32_e32 v123, v2
	v_mov_b32_e32 v124, v2
	v_mov_b32_e32 v125, v2
	.p2align	6

; #define PG8_STAGE(bufoff, gbase, voff) do { _Pragma("unroll") for (int _i = 0; _i < 2; ++_i) \
;         __builtin_amdgcn_global_load_lds((const unsigned*)((const char*)(gbase) + (voff)[_i]), (PG8_LAS unsigned*)(lds + (bufoff) + ldsw + _i * 8192), 16, 0, 0); } while (0)
; #define PG8_WAIT_V(n) asm volatile("s_waitcnt vmcnt(" #n ")" ::: "memory")
; #define PG8_BAR __builtin_amdgcn_s_barrier()
; template <class Epi, class Sched, bool ALIGN_EPI = false, bool SP2 = false>
; __device__ __forceinline__ void gemm_phase(PG8_LAS unsigned char* lds, const Gemm g, const Sched& S, const Epi& E) {
;     ...
;     for (int i = 0; i < 2; ++i) { int R, C; stage_rc(tid * 16 + i * 8192, R, C); const int Rb = Epi::PERM ? ((R & ~31) + perm32(R & 31)) : R;
;         voffA[i] = (unsigned)(R * K + C) * 2u; voffB[i] = (unsigned)(Rb * K + C) * 2u; }
;     const size_t kstep = (size_t)(BK * 2);
;     const size_t hstep = (size_t)HALF * K * 2;
;     const size_t tstep = 2 * hstep;
;     const unsigned ldsw = (unsigned)wid * 1024u;
;     const int aoff = lds_byte(wr * 64 + fr, fq * 8), boff = lds_byte(wc * 32 + fr, fq * 8);
;     ...
;         if (wr == 1) PG8_BAR;
;         PG8_WAIT_V(2); PG8_BAR;
;         PG8_STAGE(PG8_SB(1, 0), cB + kstep, voffB); PG8_STAGE(PG8_SA(1, 0), cA + kstep, voffA); PG8_STAGE(PG8_SB(1, 1), cB + hstep + kstep, voffB);
;         PG8_WAIT_V(6); PG8_BAR;
.LBB0_1389:
	s_add_u32 s20, s4, 0x7500000
	s_mov_b64 s[22:23], 0x80
	s_addc_u32 s21, s5, 0
	s_add_i32 m0, s41, 0x18000
	v_lshl_add_u64 v[10:11], v[10:11], 0, s[22:23]
	s_waitcnt vmcnt(2)
	s_barrier
	global_load_lds_dwordx4 v[10:11], off
	v_lshl_add_u64 v[6:7], v[6:7], 0, s[22:23]
	s_add_i32 m0, s41, 0x1a000
	s_add_i32 s46, s41, 0x8000
	global_load_lds_dwordx4 v[6:7], off
	v_lshl_add_u64 v[6:7], v[8:9], 0, s[22:23]
	s_mov_b32 m0, s46
	s_add_i32 s47, s41, 0xa000
	global_load_lds_dwordx4 v[6:7], off
	v_lshl_add_u64 v[6:7], v[12:13], 0, s[22:23]
	s_mov_b32 m0, s47
	v_lshl_add_u64 v[4:5], v[4:5], 0, s[22:23]
	global_load_lds_dwordx4 v[6:7], off
	s_add_i32 m0, s41, 0x1c000
	v_lshl_add_u64 v[2:3], v[2:3], 0, s[22:23]
	global_load_lds_dwordx4 v[4:5], off
	s_add_i32 m0, s41, 0x1e000
	s_lshr_b32 s4, s7, 26
	global_load_lds_dwordx4 v[2:3], off
	s_add_i32 s4, s6, s4
	v_lshlrev_b32_e32 v3, 2, v150
	s_ashr_i32 s48, s4, 6
	v_lshl_or_b32 v2, v150, 6, v152
	s_lshl_b32 s4, s27, 13
	v_and_b32_e32 v3, 32, v3
	v_bitop3_b32 v4, v2, s4, v3 bitop3:0xde
	v_add_u32_e32 v2, v151, v147
	v_mul_lo_u32 v2, s6, v2
	s_lshl_b32 s4, s25, 5
	v_lshlrev_b32_e32 v2, 1, v2
	s_and_b32 s4, s4, 0x60
	v_add3_u32 v2, v1, v2, v146
	v_mov_b32_e32 v3, v133
	s_cmp_gt_i32 s6, 63
	v_lshl_add_u64 v[138:139], s[12:13], 0, v[2:3]
	v_add_u32_e32 v2, v148, v147
	s_sext_i32_i8 s69, s24
	s_cselect_b64 s[24:25], -1, 0
	s_add_i32 s49, s48, -2
	v_mul_lo_u32 v2, s6, v2
	s_waitcnt vmcnt(6)
	s_cmpk_lt_u32 s26, 0x100
	v_lshlrev_b32_e32 v2, 1, v2
	v_lshl_or_b32 v159, s27, 6, v150
	v_lshl_or_b32 v160, s4, 7, v153
	s_cselect_b64 s[26:27], -1, 0
	v_add3_u32 v2, v1, v2, v146
	s_add_i32 s54, 0, 0x10000
	s_add_i32 s55, 0, 0x14000
	s_ashr_i32 s52, s82, 31
	s_mov_b32 s53, s82
	v_or_b32_e32 v161, s4, v149
	v_lshl_add_u64 v[140:141], s[12:13], 0, v[2:3]
	v_mov_b64_e32 v[142:143], 0x200
	v_mov_b64_e32 v[144:145], 0x1ff
	v_add_u32_e32 v162, s54, v160
	v_add_u32_e32 v163, s55, v160
	v_add_u32_e32 v164, 0, v4
	s_barrier
	s_branch .LBB0_1392
	.p2align	6

; #define PG8_BAR __builtin_amdgcn_s_barrier()
; template <class Epi, class Sched, bool ALIGN_EPI = false, bool SP2 = false>
; __device__ __forceinline__ void gemm_phase(PG8_LAS unsigned char* lds, const Gemm g, const Sched& S, const Epi& E) {
;     ...
; #pragma unroll
;         for (int a = 0; a < 2; ++a)
; #pragma unroll
;             for (int b = 0; b < 2; ++b)
; #pragma unroll
;                 for (int m = 0; m < 4; ++m)
; #pragma unroll
;                     for (int n = 0; n < 2; ++n) acc[a][b][m][n] = (f32x4){0.f, 0.f, 0.f, 0.f};
;         cur = nxt; cA = nA; cB = nB; ++ui;
;         if constexpr (ALIGN_EPI) { if (wr == 1) PG8_BAR; }
.LBB0_1402:
	v_mov_b32_e32 v125, 0
	s_andn2_b64 vcc, exec, s[24:25]
	v_mov_b32_e32 v124, v125
	v_mov_b32_e32 v123, v125
	v_mov_b32_e32 v122, v125
	v_mov_b32_e32 v129, v125
	v_mov_b32_e32 v128, v125
	v_mov_b32_e32 v127, v125
	v_mov_b32_e32 v126, v125
	v_mov_b32_e32 v113, v125
	v_mov_b32_e32 v112, v125
	v_mov_b32_e32 v111, v125
	v_mov_b32_e32 v110, v125
	v_mov_b32_e32 v109, v125
	v_mov_b32_e32 v108, v125
	v_mov_b32_e32 v107, v125
	v_mov_b32_e32 v106, v125
	v_mov_b32_e32 v97, v125
	v_mov_b32_e32 v96, v125
	v_mov_b32_e32 v95, v125
	v_mov_b32_e32 v94, v125
	v_mov_b32_e32 v93, v125
	v_mov_b32_e32 v92, v125
	v_mov_b32_e32 v91, v125
	v_mov_b32_e32 v90, v125
	v_mov_b32_e32 v81, v125
	v_mov_b32_e32 v80, v125
	v_mov_b32_e32 v79, v125
	v_mov_b32_e32 v78, v125
	v_mov_b32_e32 v77, v125
	v_mov_b32_e32 v76, v125
	v_mov_b32_e32 v75, v125
	v_mov_b32_e32 v74, v125
	v_mov_b32_e32 v121, v125
	v_mov_b32_e32 v120, v125
	v_mov_b32_e32 v119, v125
	v_mov_b32_e32 v118, v125
	v_mov_b32_e32 v117, v125
	v_mov_b32_e32 v116, v125
	v_mov_b32_e32 v115, v125
	v_mov_b32_e32 v114, v125
	v_mov_b32_e32 v105, v125
	v_mov_b32_e32 v104, v125
	v_mov_b32_e32 v103, v125
	v_mov_b32_e32 v102, v125
	v_mov_b32_e32 v101, v125
	v_mov_b32_e32 v100, v125
	v_mov_b32_e32 v99, v125
	v_mov_b32_e32 v98, v125
	v_mov_b32_e32 v89, v125
	v_mov_b32_e32 v88, v125
	v_mov_b32_e32 v87, v125
	v_mov_b32_e32 v86, v125
	v_mov_b32_e32 v85, v125
	v_mov_b32_e32 v84, v125
	v_mov_b32_e32 v83, v125
	v_mov_b32_e32 v82, v125
	v_mov_b32_e32 v73, v125
	v_mov_b32_e32 v72, v125
	v_mov_b32_e32 v71, v125
	v_mov_b32_e32 v70, v125
	v_mov_b32_e32 v69, v125
	v_mov_b32_e32 v68, v125
	v_mov_b32_e32 v67, v125
	v_mov_b32_e32 v66, v125
	v_mov_b32_e32 v65, v125
	v_mov_b32_e32 v64, v125
	v_mov_b32_e32 v63, v125
	v_mov_b32_e32 v62, v125
	v_mov_b32_e32 v61, v125
	v_mov_b32_e32 v60, v125
	v_mov_b32_e32 v59, v125
	v_mov_b32_e32 v58, v125
	v_mov_b32_e32 v49, v125
	v_mov_b32_e32 v48, v125
	v_mov_b32_e32 v47, v125
	v_mov_b32_e32 v46, v125
	v_mov_b32_e32 v45, v125
	v_mov_b32_e32 v44, v125
	v_mov_b32_e32 v43, v125
	v_mov_b32_e32 v42, v125
	v_mov_b32_e32 v33, v125
	v_mov_b32_e32 v32, v125
	v_mov_b32_e32 v31, v125
	v_mov_b32_e32 v30, v125
	v_mov_b32_e32 v29, v125
	v_mov_b32_e32 v28, v125
	v_mov_b32_e32 v27, v125
	v_mov_b32_e32 v26, v125
	v_mov_b32_e32 v17, v125
	v_mov_b32_e32 v16, v125
	v_mov_b32_e32 v15, v125
	v_mov_b32_e32 v14, v125
	v_mov_b32_e32 v13, v125
	v_mov_b32_e32 v12, v125
	v_mov_b32_e32 v11, v125
	v_mov_b32_e32 v10, v125
	v_mov_b32_e32 v57, v125
	v_mov_b32_e32 v56, v125
	v_mov_b32_e32 v55, v125
	v_mov_b32_e32 v54, v125
	v_mov_b32_e32 v53, v125
	v_mov_b32_e32 v52, v125
	v_mov_b32_e32 v51, v125
	v_mov_b32_e32 v50, v125
	v_mov_b32_e32 v41, v125
	v_mov_b32_e32 v40, v125
	v_mov_b32_e32 v39, v125
	v_mov_b32_e32 v38, v125
	v_mov_b32_e32 v37, v125
	v_mov_b32_e32 v36, v125
	v_mov_b32_e32 v35, v125
	v_mov_b32_e32 v34, v125
	v_mov_b32_e32 v25, v125
	v_mov_b32_e32 v24, v125
	v_mov_b32_e32 v23, v125
	v_mov_b32_e32 v22, v125
	v_mov_b32_e32 v21, v125
	v_mov_b32_e32 v20, v125
	v_mov_b32_e32 v19, v125
	v_mov_b32_e32 v18, v125
	v_mov_b32_e32 v9, v125
	v_mov_b32_e32 v8, v125
	v_mov_b32_e32 v7, v125
	v_mov_b32_e32 v6, v125
	v_mov_b32_e32 v5, v125
	v_mov_b32_e32 v4, v125
	v_mov_b32_e32 v3, v125
	v_mov_b32_e32 v2, v125
	s_cbranch_vccnz .LBB0_1405
	s_add_u32 s80, s30, 0x100
	s_addc_u32 s81, s31, 0
	s_add_u32 s30, s34, 0x80
	v_mov_b32_e32 v2, 0
	s_addc_u32 s31, s35, 0
	s_mov_b32 s34, 0
	v_mov_b32_e32 v3, v2
	v_mov_b32_e32 v4, v2
	v_mov_b32_e32 v5, v2
	v_mov_b32_e32 v6, v2
	v_mov_b32_e32 v7, v2
	v_mov_b32_e32 v8, v2
	v_mov_b32_e32 v9, v2
	v_mov_b32_e32 v18, v2
	v_mov_b32_e32 v19, v2
	v_mov_b32_e32 v20, v2
	v_mov_b32_e32 v21, v2
	v_mov_b32_e32 v22, v2
	v_mov_b32_e32 v23, v2
	v_mov_b32_e32 v24, v2
	v_mov_b32_e32 v25, v2
	v_mov_b32_e32 v34, v2
	v_mov_b32_e32 v35, v2
	v_mov_b32_e32 v36, v2
	v_mov_b32_e32 v37, v2
	v_mov_b32_e32 v38, v2
	v_mov_b32_e32 v39, v2
	v_mov_b32_e32 v40, v2
	v_mov_b32_e32 v41, v2
	v_mov_b32_e32 v50, v2
	v_mov_b32_e32 v51, v2
	v_mov_b32_e32 v52, v2
	v_mov_b32_e32 v53, v2
	v_mov_b32_e32 v54, v2
	v_mov_b32_e32 v55, v2
	v_mov_b32_e32 v56, v2
	v_mov_b32_e32 v57, v2
	v_mov_b32_e32 v10, v2
	v_mov_b32_e32 v11, v2
	v_mov_b32_e32 v12, v2
	v_mov_b32_e32 v13, v2
	v_mov_b32_e32 v14, v2
	v_mov_b32_e32 v15, v2
	v_mov_b32_e32 v16, v2
	v_mov_b32_e32 v17, v2
	v_mov_b32_e32 v26, v2
	v_mov_b32_e32 v27, v2
	v_mov_b32_e32 v28, v2
	v_mov_b32_e32 v29, v2
	v_mov_b32_e32 v30, v2
	v_mov_b32_e32 v31, v2
	v_mov_b32_e32 v32, v2
	v_mov_b32_e32 v33, v2
	v_mov_b32_e32 v42, v2
	v_mov_b32_e32 v43, v2
	v_mov_b32_e32 v44, v2
	v_mov_b32_e32 v45, v2
	v_mov_b32_e32 v46, v2
	v_mov_b32_e32 v47, v2
	v_mov_b32_e32 v48, v2
	v_mov_b32_e32 v49, v2
	v_mov_b32_e32 v58, v2
	v_mov_b32_e32 v59, v2
	v_mov_b32_e32 v60, v2
	v_mov_b32_e32 v61, v2
	v_mov_b32_e32 v62, v2
	v_mov_b32_e32 v63, v2
	v_mov_b32_e32 v64, v2
	v_mov_b32_e32 v65, v2
	v_mov_b32_e32 v66, v2
	v_mov_b32_e32 v67, v2
	v_mov_b32_e32 v68, v2
	v_mov_b32_e32 v69, v2
	v_mov_b32_e32 v70, v2
	v_mov_b32_e32 v71, v2
	v_mov_b32_e32 v72, v2
	v_mov_b32_e32 v73, v2
	v_mov_b32_e32 v82, v2
	v_mov_b32_e32 v83, v2
	v_mov_b32_e32 v84, v2
	v_mov_b32_e32 v85, v2
	v_mov_b32_e32 v86, v2
	v_mov_b32_e32 v87, v2
	v_mov_b32_e32 v88, v2
	v_mov_b32_e32 v89, v2
	v_mov_b32_e32 v98, v2
	v_mov_b32_e32 v99, v2
	v_mov_b32_e32 v100, v2
	v_mov_b32_e32 v101, v2
	v_mov_b32_e32 v102, v2
	v_mov_b32_e32 v103, v2
	v_mov_b32_e32 v104, v2
	v_mov_b32_e32 v105, v2
	v_mov_b32_e32 v114, v2
	v_mov_b32_e32 v115, v2
	v_mov_b32_e32 v116, v2
	v_mov_b32_e32 v117, v2
	v_mov_b32_e32 v118, v2
	v_mov_b32_e32 v119, v2
	v_mov_b32_e32 v120, v2
	v_mov_b32_e32 v121, v2
	v_mov_b32_e32 v74, v2
	v_mov_b32_e32 v75, v2
	v_mov_b32_e32 v76, v2
	v_mov_b32_e32 v77, v2
	v_mov_b32_e32 v78, v2
	v_mov_b32_e32 v79, v2
	v_mov_b32_e32 v80, v2
	v_mov_b32_e32 v81, v2
	v_mov_b32_e32 v90, v2
	v_mov_b32_e32 v91, v2
	v_mov_b32_e32 v92, v2
	v_mov_b32_e32 v93, v2
	v_mov_b32_e32 v94, v2
	v_mov_b32_e32 v95, v2
	v_mov_b32_e32 v96, v2
	v_mov_b32_e32 v97, v2
	v_mov_b32_e32 v106, v2
	v_mov_b32_e32 v107, v2
	v_mov_b32_e32 v108, v2
	v_mov_b32_e32 v109, v2
	v_mov_b32_e32 v110, v2
	v_mov_b32_e32 v111, v2
	v_mov_b32_e32 v112, v2
	v_mov_b32_e32 v113, v2
	v_mov_b32_e32 v126, v2
	v_mov_b32_e32 v127, v2
	v_mov_b32_e32 v128, v2
	v_mov_b32_e32 v129, v2
	v_mov_b32_e32 v122, v2
	v_mov_b32_e32 v123, v2
	v_mov_b32_e32 v124, v2
	v_mov_b32_e32 v125, v2
	.p2align	6

; #define PG8_STAGE(bufoff, gbase, voff) do { _Pragma("unroll") for (int _i = 0; _i < 2; ++_i) \
;         __builtin_amdgcn_global_load_lds((const unsigned*)((const char*)(gbase) + (voff)[_i]), (PG8_LAS unsigned*)(lds + (bufoff) + ldsw + _i * 8192), 16, 0, 0); } while (0)
; #define PG8_WAIT_V(n) asm volatile("s_waitcnt vmcnt(" #n ")" ::: "memory")
; #define PG8_BAR __builtin_amdgcn_s_barrier()
; template <class Epi, class Sched, bool ALIGN_EPI = false, bool SP2 = false>
; __device__ __forceinline__ void gemm_phase(PG8_LAS unsigned char* lds, const Gemm g, const Sched& S, const Epi& E) {
;     ...
;     for (int i = 0; i < 2; ++i) { int R, C; stage_rc(tid * 16 + i * 8192, R, C); const int Rb = Epi::PERM ? ((R & ~31) + perm32(R & 31)) : R;
;         voffA[i] = (unsigned)(R * K + C) * 2u; voffB[i] = (unsigned)(Rb * K + C) * 2u; }
;     const size_t kstep = (size_t)(BK * 2);
;     const size_t hstep = (size_t)HALF * K * 2;
;     const size_t tstep = 2 * hstep;
;     const unsigned ldsw = (unsigned)wid * 1024u;
;     const int aoff = lds_byte(wr * 64 + fr, fq * 8), boff = lds_byte(wc * 32 + fr, fq * 8);
;     ...
;         if (wr == 1) PG8_BAR;
;         PG8_WAIT_V(2); PG8_BAR;
;         PG8_STAGE(PG8_SB(1, 0), cB + kstep, voffB); PG8_STAGE(PG8_SA(1, 0), cA + kstep, voffA); PG8_STAGE(PG8_SB(1, 1), cB + hstep + kstep, voffB);
;         PG8_WAIT_V(6); PG8_BAR;
.LBB0_1418:
	s_add_u32 s18, s18, 0x19500000
	s_mov_b64 s[20:21], 0x80
	s_addc_u32 s19, s19, 0
	s_add_i32 m0, s39, 0x18000
	v_lshl_add_u64 v[10:11], v[10:11], 0, s[20:21]
	s_waitcnt vmcnt(2)
	s_barrier
	global_load_lds_dwordx4 v[10:11], off
	v_lshl_add_u64 v[6:7], v[6:7], 0, s[20:21]
	s_add_i32 m0, s39, 0x1a000
	s_add_i32 s44, s39, 0x8000
	global_load_lds_dwordx4 v[6:7], off
	v_lshl_add_u64 v[6:7], v[8:9], 0, s[20:21]
	s_mov_b32 m0, s44
	s_add_i32 s45, s39, 0xa000
	global_load_lds_dwordx4 v[6:7], off
	v_lshl_add_u64 v[6:7], v[12:13], 0, s[20:21]
	s_mov_b32 m0, s45
	v_lshl_add_u64 v[4:5], v[4:5], 0, s[20:21]
	global_load_lds_dwordx4 v[6:7], off
	s_add_i32 m0, s39, 0x1c000
	v_lshl_add_u64 v[2:3], v[2:3], 0, s[20:21]
	global_load_lds_dwordx4 v[4:5], off
	s_add_i32 m0, s39, 0x1e000
	s_sext_i32_i8 s57, s0
	global_load_lds_dwordx4 v[2:3], off
	s_lshr_b32 s0, s5, 26
	s_add_i32 s0, s4, s0
	v_lshlrev_b32_e32 v3, 2, v150
	s_ashr_i32 s46, s0, 6
	v_lshl_or_b32 v2, v150, 6, v152
	s_lshl_b32 s0, s22, 13
	v_and_b32_e32 v3, 32, v3
	v_bitop3_b32 v4, v2, s0, v3 bitop3:0xde
	v_add_u32_e32 v2, v151, v147
	v_mul_lo_u32 v2, s4, v2
	s_lshl_b32 s0, s1, 5
	v_lshlrev_b32_e32 v2, 1, v2
	s_and_b32 s0, s0, 0x60
	v_add3_u32 v2, v1, v2, v146
	v_mov_b32_e32 v3, v133
	s_cmp_gt_i32 s4, 63
	v_lshl_add_u64 v[138:139], s[6:7], 0, v[2:3]
	v_add_u32_e32 v2, v148, v147
	v_lshl_or_b32 v154, s22, 6, v150
	s_cselect_b64 s[22:23], -1, 0
	s_add_i32 s47, s46, -2
	v_mul_lo_u32 v2, s4, v2
	s_waitcnt vmcnt(6)
	s_cmpk_lt_u32 s24, 0x100
	v_lshlrev_b32_e32 v2, 1, v2
	v_lshl_or_b32 v150, s0, 7, v153
	s_cselect_b64 s[24:25], -1, 0
	v_add3_u32 v2, v1, v2, v146
	s_add_i32 s52, 0, 0x10000
	s_add_i32 s53, 0, 0x14000
	s_ashr_i32 s48, s82, 31
	s_mov_b32 s49, s82
	v_or_b32_e32 v149, s0, v149
	v_lshl_add_u64 v[140:141], s[6:7], 0, v[2:3]
	v_mov_b64_e32 v[142:143], 0x200
	v_mov_b64_e32 v[144:145], 0x1ff
	v_add_u32_e32 v1, s52, v150
	v_add_u32_e32 v146, s53, v150
	v_add_u32_e32 v147, 0, v4
	s_barrier
	s_branch .LBB0_1421
	.p2align	6

; #define PG8_BAR __builtin_amdgcn_s_barrier()
; template <class Epi, class Sched, bool ALIGN_EPI = false, bool SP2 = false>
; __device__ __forceinline__ void gemm_phase(PG8_LAS unsigned char* lds, const Gemm g, const Sched& S, const Epi& E) {
;     ...
; #pragma unroll
;         for (int a = 0; a < 2; ++a)
; #pragma unroll
;             for (int b = 0; b < 2; ++b)
; #pragma unroll
;                 for (int m = 0; m < 4; ++m)
; #pragma unroll
;                     for (int n = 0; n < 2; ++n) acc[a][b][m][n] = (f32x4){0.f, 0.f, 0.f, 0.f};
;         cur = nxt; cA = nA; cB = nB; ++ui;
;         if constexpr (ALIGN_EPI) { if (wr == 1) PG8_BAR; }
.LBB0_1431:
	v_mov_b32_e32 v125, 0
	s_andn2_b64 vcc, exec, s[22:23]
	v_mov_b32_e32 v124, v125
	v_mov_b32_e32 v123, v125
	v_mov_b32_e32 v122, v125
	v_mov_b32_e32 v129, v125
	v_mov_b32_e32 v128, v125
	v_mov_b32_e32 v127, v125
	v_mov_b32_e32 v126, v125
	v_mov_b32_e32 v113, v125
	v_mov_b32_e32 v112, v125
	v_mov_b32_e32 v111, v125
	v_mov_b32_e32 v110, v125
	v_mov_b32_e32 v109, v125
	v_mov_b32_e32 v108, v125
	v_mov_b32_e32 v107, v125
	v_mov_b32_e32 v106, v125
	v_mov_b32_e32 v97, v125
	v_mov_b32_e32 v96, v125
	v_mov_b32_e32 v95, v125
	v_mov_b32_e32 v94, v125
	v_mov_b32_e32 v93, v125
	v_mov_b32_e32 v92, v125
	v_mov_b32_e32 v91, v125
	v_mov_b32_e32 v90, v125
	v_mov_b32_e32 v81, v125
	v_mov_b32_e32 v80, v125
	v_mov_b32_e32 v79, v125
	v_mov_b32_e32 v78, v125
	v_mov_b32_e32 v77, v125
	v_mov_b32_e32 v76, v125
	v_mov_b32_e32 v75, v125
	v_mov_b32_e32 v74, v125
	v_mov_b32_e32 v121, v125
	v_mov_b32_e32 v120, v125
	v_mov_b32_e32 v119, v125
	v_mov_b32_e32 v118, v125
	v_mov_b32_e32 v117, v125
	v_mov_b32_e32 v116, v125
	v_mov_b32_e32 v115, v125
	v_mov_b32_e32 v114, v125
	v_mov_b32_e32 v105, v125
	v_mov_b32_e32 v104, v125
	v_mov_b32_e32 v103, v125
	v_mov_b32_e32 v102, v125
	v_mov_b32_e32 v101, v125
	v_mov_b32_e32 v100, v125
	v_mov_b32_e32 v99, v125
	v_mov_b32_e32 v98, v125
	v_mov_b32_e32 v89, v125
	v_mov_b32_e32 v88, v125
	v_mov_b32_e32 v87, v125
	v_mov_b32_e32 v86, v125
	v_mov_b32_e32 v85, v125
	v_mov_b32_e32 v84, v125
	v_mov_b32_e32 v83, v125
	v_mov_b32_e32 v82, v125
	v_mov_b32_e32 v73, v125
	v_mov_b32_e32 v72, v125
	v_mov_b32_e32 v71, v125
	v_mov_b32_e32 v70, v125
	v_mov_b32_e32 v69, v125
	v_mov_b32_e32 v68, v125
	v_mov_b32_e32 v67, v125
	v_mov_b32_e32 v66, v125
	v_mov_b32_e32 v65, v125
	v_mov_b32_e32 v64, v125
	v_mov_b32_e32 v63, v125
	v_mov_b32_e32 v62, v125
	v_mov_b32_e32 v61, v125
	v_mov_b32_e32 v60, v125
	v_mov_b32_e32 v59, v125
	v_mov_b32_e32 v58, v125
	v_mov_b32_e32 v49, v125
	v_mov_b32_e32 v48, v125
	v_mov_b32_e32 v47, v125
	v_mov_b32_e32 v46, v125
	v_mov_b32_e32 v45, v125
	v_mov_b32_e32 v44, v125
	v_mov_b32_e32 v43, v125
	v_mov_b32_e32 v42, v125
	v_mov_b32_e32 v33, v125
	v_mov_b32_e32 v32, v125
	v_mov_b32_e32 v31, v125
	v_mov_b32_e32 v30, v125
	v_mov_b32_e32 v29, v125
	v_mov_b32_e32 v28, v125
	v_mov_b32_e32 v27, v125
	v_mov_b32_e32 v26, v125
	v_mov_b32_e32 v17, v125
	v_mov_b32_e32 v16, v125
	v_mov_b32_e32 v15, v125
	v_mov_b32_e32 v14, v125
	v_mov_b32_e32 v13, v125
	v_mov_b32_e32 v12, v125
	v_mov_b32_e32 v11, v125
	v_mov_b32_e32 v10, v125
	v_mov_b32_e32 v57, v125
	v_mov_b32_e32 v56, v125
	v_mov_b32_e32 v55, v125
	v_mov_b32_e32 v54, v125
	v_mov_b32_e32 v53, v125
	v_mov_b32_e32 v52, v125
	v_mov_b32_e32 v51, v125
	v_mov_b32_e32 v50, v125
	v_mov_b32_e32 v41, v125
	v_mov_b32_e32 v40, v125
	v_mov_b32_e32 v39, v125
	v_mov_b32_e32 v38, v125
	v_mov_b32_e32 v37, v125
	v_mov_b32_e32 v36, v125
	v_mov_b32_e32 v35, v125
	v_mov_b32_e32 v34, v125
	v_mov_b32_e32 v25, v125
	v_mov_b32_e32 v24, v125
	v_mov_b32_e32 v23, v125
	v_mov_b32_e32 v22, v125
	v_mov_b32_e32 v21, v125
	v_mov_b32_e32 v20, v125
	v_mov_b32_e32 v19, v125
	v_mov_b32_e32 v18, v125
	v_mov_b32_e32 v9, v125
	v_mov_b32_e32 v8, v125
	v_mov_b32_e32 v7, v125
	v_mov_b32_e32 v6, v125
	v_mov_b32_e32 v5, v125
	v_mov_b32_e32 v4, v125
	v_mov_b32_e32 v3, v125
	v_mov_b32_e32 v2, v125
	s_cbranch_vccnz .LBB0_1434
	s_add_u32 s68, s28, 0x100
	s_addc_u32 s69, s29, 0
	s_add_u32 s28, s30, 0x80
	v_mov_b32_e32 v2, 0
	s_addc_u32 s29, s31, 0
	s_mov_b32 s30, 0
	v_mov_b32_e32 v3, v2
	v_mov_b32_e32 v4, v2
	v_mov_b32_e32 v5, v2
	v_mov_b32_e32 v6, v2
	v_mov_b32_e32 v7, v2
	v_mov_b32_e32 v8, v2
	v_mov_b32_e32 v9, v2
	v_mov_b32_e32 v18, v2
	v_mov_b32_e32 v19, v2
	v_mov_b32_e32 v20, v2
	v_mov_b32_e32 v21, v2
	v_mov_b32_e32 v22, v2
	v_mov_b32_e32 v23, v2
	v_mov_b32_e32 v24, v2
	v_mov_b32_e32 v25, v2
	v_mov_b32_e32 v34, v2
	v_mov_b32_e32 v35, v2
	v_mov_b32_e32 v36, v2
	v_mov_b32_e32 v37, v2
	v_mov_b32_e32 v38, v2
	v_mov_b32_e32 v39, v2
	v_mov_b32_e32 v40, v2
	v_mov_b32_e32 v41, v2
	v_mov_b32_e32 v50, v2
	v_mov_b32_e32 v51, v2
	v_mov_b32_e32 v52, v2
	v_mov_b32_e32 v53, v2
	v_mov_b32_e32 v54, v2
	v_mov_b32_e32 v55, v2
	v_mov_b32_e32 v56, v2
	v_mov_b32_e32 v57, v2
	v_mov_b32_e32 v10, v2
	v_mov_b32_e32 v11, v2
	v_mov_b32_e32 v12, v2
	v_mov_b32_e32 v13, v2
	v_mov_b32_e32 v14, v2
	v_mov_b32_e32 v15, v2
	v_mov_b32_e32 v16, v2
	v_mov_b32_e32 v17, v2
	v_mov_b32_e32 v26, v2
	v_mov_b32_e32 v27, v2
	v_mov_b32_e32 v28, v2
	v_mov_b32_e32 v29, v2
	v_mov_b32_e32 v30, v2
	v_mov_b32_e32 v31, v2
	v_mov_b32_e32 v32, v2
	v_mov_b32_e32 v33, v2
	v_mov_b32_e32 v42, v2
	v_mov_b32_e32 v43, v2
	v_mov_b32_e32 v44, v2
	v_mov_b32_e32 v45, v2
	v_mov_b32_e32 v46, v2
	v_mov_b32_e32 v47, v2
	v_mov_b32_e32 v48, v2
	v_mov_b32_e32 v49, v2
	v_mov_b32_e32 v58, v2
	v_mov_b32_e32 v59, v2
	v_mov_b32_e32 v60, v2
	v_mov_b32_e32 v61, v2
	v_mov_b32_e32 v62, v2
	v_mov_b32_e32 v63, v2
	v_mov_b32_e32 v64, v2
	v_mov_b32_e32 v65, v2
	v_mov_b32_e32 v66, v2
	v_mov_b32_e32 v67, v2
	v_mov_b32_e32 v68, v2
	v_mov_b32_e32 v69, v2
	v_mov_b32_e32 v70, v2
	v_mov_b32_e32 v71, v2
	v_mov_b32_e32 v72, v2
	v_mov_b32_e32 v73, v2
	v_mov_b32_e32 v82, v2
	v_mov_b32_e32 v83, v2
	v_mov_b32_e32 v84, v2
	v_mov_b32_e32 v85, v2
	v_mov_b32_e32 v86, v2
	v_mov_b32_e32 v87, v2
	v_mov_b32_e32 v88, v2
	v_mov_b32_e32 v89, v2
	v_mov_b32_e32 v98, v2
	v_mov_b32_e32 v99, v2
	v_mov_b32_e32 v100, v2
	v_mov_b32_e32 v101, v2
	v_mov_b32_e32 v102, v2
	v_mov_b32_e32 v103, v2
	v_mov_b32_e32 v104, v2
	v_mov_b32_e32 v105, v2
	v_mov_b32_e32 v114, v2
	v_mov_b32_e32 v115, v2
	v_mov_b32_e32 v116, v2
	v_mov_b32_e32 v117, v2
	v_mov_b32_e32 v118, v2
	v_mov_b32_e32 v119, v2
	v_mov_b32_e32 v120, v2
	v_mov_b32_e32 v121, v2
	v_mov_b32_e32 v74, v2
	v_mov_b32_e32 v75, v2
	v_mov_b32_e32 v76, v2
	v_mov_b32_e32 v77, v2
	v_mov_b32_e32 v78, v2
	v_mov_b32_e32 v79, v2
	v_mov_b32_e32 v80, v2
	v_mov_b32_e32 v81, v2
	v_mov_b32_e32 v90, v2
	v_mov_b32_e32 v91, v2
	v_mov_b32_e32 v92, v2
	v_mov_b32_e32 v93, v2
	v_mov_b32_e32 v94, v2
	v_mov_b32_e32 v95, v2
	v_mov_b32_e32 v96, v2
	v_mov_b32_e32 v97, v2
	v_mov_b32_e32 v106, v2
	v_mov_b32_e32 v107, v2
	v_mov_b32_e32 v108, v2
	v_mov_b32_e32 v109, v2
	v_mov_b32_e32 v110, v2
	v_mov_b32_e32 v111, v2
	v_mov_b32_e32 v112, v2
	v_mov_b32_e32 v113, v2
	v_mov_b32_e32 v126, v2
	v_mov_b32_e32 v127, v2
	v_mov_b32_e32 v128, v2
	v_mov_b32_e32 v129, v2
	v_mov_b32_e32 v122, v2
	v_mov_b32_e32 v123, v2
	v_mov_b32_e32 v124, v2
	v_mov_b32_e32 v125, v2
	.p2align	6

; #define PG8_STAGE(bufoff, gbase, voff) do { _Pragma("unroll") for (int _i = 0; _i < 2; ++_i) \
;         __builtin_amdgcn_global_load_lds((const unsigned*)((const char*)(gbase) + (voff)[_i]), (PG8_LAS unsigned*)(lds + (bufoff) + ldsw + _i * 8192), 16, 0, 0); } while (0)
; #define PG8_WAIT_V(n) asm volatile("s_waitcnt vmcnt(" #n ")" ::: "memory")
; #define PG8_BAR __builtin_amdgcn_s_barrier()
; template <class Epi, class Sched, bool ALIGN_EPI = false, bool SP2 = false>
; __device__ __forceinline__ void gemm_phase(PG8_LAS unsigned char* lds, const Gemm g, const Sched& S, const Epi& E) {
;     ...
;     for (int i = 0; i < 2; ++i) { int R, C; stage_rc(tid * 16 + i * 8192, R, C); const int Rb = Epi::PERM ? ((R & ~31) + perm32(R & 31)) : R;
;         voffA[i] = (unsigned)(R * K + C) * 2u; voffB[i] = (unsigned)(Rb * K + C) * 2u; }
;     const size_t kstep = (size_t)(BK * 2);
;     const size_t hstep = (size_t)HALF * K * 2;
;     const size_t tstep = 2 * hstep;
;     const unsigned ldsw = (unsigned)wid * 1024u;
;     const int aoff = lds_byte(wr * 64 + fr, fq * 8), boff = lds_byte(wc * 32 + fr, fq * 8);
;     ...
;         if (wr == 1) PG8_BAR;
;         PG8_WAIT_V(2); PG8_BAR;
;         PG8_STAGE(PG8_SB(1, 0), cB + kstep, voffB); PG8_STAGE(PG8_SA(1, 0), cA + kstep, voffA); PG8_STAGE(PG8_SB(1, 1), cB + hstep + kstep, voffB);
;         PG8_WAIT_V(6); PG8_BAR;
.LBB0_1503:
	s_add_u32 s22, s4, 0xb500000
	s_mov_b64 s[24:25], 0x80
	s_addc_u32 s23, s5, 0
	s_add_i32 m0, s43, 0x18000
	v_lshl_add_u64 v[10:11], v[10:11], 0, s[24:25]
	s_waitcnt vmcnt(2)
	s_barrier
	global_load_lds_dwordx4 v[10:11], off
	v_lshl_add_u64 v[6:7], v[6:7], 0, s[24:25]
	s_add_i32 m0, s43, 0x1a000
	s_add_i32 s48, s43, 0x8000
	global_load_lds_dwordx4 v[6:7], off
	v_lshl_add_u64 v[6:7], v[8:9], 0, s[24:25]
	s_mov_b32 m0, s48
	s_add_i32 s49, s43, 0xa000
	global_load_lds_dwordx4 v[6:7], off
	v_lshl_add_u64 v[6:7], v[12:13], 0, s[24:25]
	s_mov_b32 m0, s49
	v_lshl_add_u64 v[4:5], v[4:5], 0, s[24:25]
	global_load_lds_dwordx4 v[6:7], off
	s_add_i32 m0, s43, 0x1c000
	v_lshl_add_u64 v[2:3], v[2:3], 0, s[24:25]
	global_load_lds_dwordx4 v[4:5], off
	s_add_i32 m0, s43, 0x1e000
	s_lshr_b32 s1, s1, 26
	global_load_lds_dwordx4 v[2:3], off
	s_add_i32 s1, s0, s1
	v_lshlrev_b32_e32 v3, 2, v156
	s_ashr_i32 s52, s1, 6
	v_lshl_or_b32 v2, v156, 6, v158
	s_lshl_b32 s1, s29, 13
	v_and_b32_e32 v3, 32, v3
	v_bitop3_b32 v4, v2, s1, v3 bitop3:0xde
	v_add_u32_e32 v2, v157, v153
	v_mul_lo_u32 v2, s0, v2
	s_lshl_b32 s1, s27, 5
	v_lshlrev_b32_e32 v2, 1, v2
	s_and_b32 s1, s1, 0x60
	v_add3_u32 v2, v1, v2, v152
	v_mov_b32_e32 v3, v133
	s_cmp_gt_i32 s0, 63
	v_lshl_add_u64 v[138:139], s[14:15], 0, v[2:3]
	v_add_u32_e32 v2, v154, v153
	s_sext_i32_i8 s81, s26
	s_cselect_b64 s[26:27], -1, 0
	s_add_i32 s53, s52, -2
	v_mul_lo_u32 v2, s0, v2
	s_waitcnt vmcnt(6)
	s_cmpk_lt_u32 s28, 0x100
	v_lshlrev_b32_e32 v2, 1, v2
	v_lshl_or_b32 v165, s29, 6, v156
	v_lshl_or_b32 v166, s1, 7, v159
	s_cselect_b64 s[28:29], -1, 0
	v_add3_u32 v2, v1, v2, v152
	s_add_i32 s56, 0, 0x10000
	s_add_i32 s57, 0, 0x14000
	s_ashr_i32 s54, s82, 31
	s_mov_b32 s55, s82
	v_or_b32_e32 v167, s1, v155
	v_lshl_add_u64 v[140:141], s[14:15], 0, v[2:3]
	v_mov_b64_e32 v[142:143], 0x200
	v_mov_b64_e32 v[144:145], 0x1ff
	v_add_u32_e32 v168, s56, v166
	v_add_u32_e32 v169, s57, v166
	v_add_u32_e32 v170, 0, v4
	s_mov_b32 s30, 0xbf1b4598
	s_barrier
	s_branch .LBB0_1506
	.p2align	6

; #define PG8_BAR __builtin_amdgcn_s_barrier()
; template <class Epi, class Sched, bool ALIGN_EPI = false, bool SP2 = false>
; __device__ __forceinline__ void gemm_phase(PG8_LAS unsigned char* lds, const Gemm g, const Sched& S, const Epi& E) {
;     ...
; #pragma unroll
;         for (int a = 0; a < 2; ++a)
; #pragma unroll
;             for (int b = 0; b < 2; ++b)
; #pragma unroll
;                 for (int m = 0; m < 4; ++m)
; #pragma unroll
;                     for (int n = 0; n < 2; ++n) acc[a][b][m][n] = (f32x4){0.f, 0.f, 0.f, 0.f};
;         cur = nxt; cA = nA; cB = nB; ++ui;
;         if constexpr (ALIGN_EPI) { if (wr == 1) PG8_BAR; }
.LBB0_1516:
	v_mov_b32_e32 v125, 0
	s_andn2_b64 vcc, exec, s[26:27]
	v_mov_b32_e32 v124, v125
	v_mov_b32_e32 v123, v125
	v_mov_b32_e32 v122, v125
	v_mov_b32_e32 v129, v125
	v_mov_b32_e32 v128, v125
	v_mov_b32_e32 v127, v125
	v_mov_b32_e32 v126, v125
	v_mov_b32_e32 v113, v125
	v_mov_b32_e32 v112, v125
	v_mov_b32_e32 v111, v125
	v_mov_b32_e32 v110, v125
	v_mov_b32_e32 v109, v125
	v_mov_b32_e32 v108, v125
	v_mov_b32_e32 v107, v125
	v_mov_b32_e32 v106, v125
	s_waitcnt vmcnt(0)
	v_mov_b32_e32 v97, v125
	v_mov_b32_e32 v96, v125
	v_mov_b32_e32 v95, v125
	v_mov_b32_e32 v94, v125
	v_mov_b32_e32 v93, v125
	v_mov_b32_e32 v92, v125
	v_mov_b32_e32 v91, v125
	v_mov_b32_e32 v90, v125
	v_mov_b32_e32 v81, v125
	v_mov_b32_e32 v80, v125
	v_mov_b32_e32 v79, v125
	v_mov_b32_e32 v78, v125
	v_mov_b32_e32 v77, v125
	v_mov_b32_e32 v76, v125
	v_mov_b32_e32 v75, v125
	v_mov_b32_e32 v74, v125
	v_mov_b32_e32 v121, v125
	v_mov_b32_e32 v120, v125
	v_mov_b32_e32 v119, v125
	v_mov_b32_e32 v118, v125
	v_mov_b32_e32 v117, v125
	v_mov_b32_e32 v116, v125
	v_mov_b32_e32 v115, v125
	v_mov_b32_e32 v114, v125
	v_mov_b32_e32 v105, v125
	v_mov_b32_e32 v104, v125
	v_mov_b32_e32 v103, v125
	v_mov_b32_e32 v102, v125
	v_mov_b32_e32 v101, v125
	v_mov_b32_e32 v100, v125
	v_mov_b32_e32 v99, v125
	v_mov_b32_e32 v98, v125
	v_mov_b32_e32 v89, v125
	v_mov_b32_e32 v88, v125
	v_mov_b32_e32 v87, v125
	v_mov_b32_e32 v86, v125
	v_mov_b32_e32 v85, v125
	v_mov_b32_e32 v84, v125
	v_mov_b32_e32 v83, v125
	v_mov_b32_e32 v82, v125
	v_mov_b32_e32 v73, v125
	v_mov_b32_e32 v72, v125
	v_mov_b32_e32 v71, v125
	v_mov_b32_e32 v70, v125
	v_mov_b32_e32 v69, v125
	v_mov_b32_e32 v68, v125
	v_mov_b32_e32 v67, v125
	v_mov_b32_e32 v66, v125
	v_mov_b32_e32 v65, v125
	v_mov_b32_e32 v64, v125
	v_mov_b32_e32 v63, v125
	v_mov_b32_e32 v62, v125
	v_mov_b32_e32 v61, v125
	v_mov_b32_e32 v60, v125
	v_mov_b32_e32 v59, v125
	v_mov_b32_e32 v58, v125
	v_mov_b32_e32 v49, v125
	v_mov_b32_e32 v48, v125
	v_mov_b32_e32 v47, v125
	v_mov_b32_e32 v46, v125
	v_mov_b32_e32 v45, v125
	v_mov_b32_e32 v44, v125
	v_mov_b32_e32 v43, v125
	v_mov_b32_e32 v42, v125
	v_mov_b32_e32 v33, v125
	v_mov_b32_e32 v32, v125
	v_mov_b32_e32 v31, v125
	v_mov_b32_e32 v30, v125
	v_mov_b32_e32 v29, v125
	v_mov_b32_e32 v28, v125
	v_mov_b32_e32 v27, v125
	v_mov_b32_e32 v26, v125
	v_mov_b32_e32 v17, v125
	v_mov_b32_e32 v16, v125
	v_mov_b32_e32 v15, v125
	v_mov_b32_e32 v14, v125
	v_mov_b32_e32 v13, v125
	v_mov_b32_e32 v12, v125
	v_mov_b32_e32 v11, v125
	v_mov_b32_e32 v10, v125
	v_mov_b32_e32 v57, v125
	v_mov_b32_e32 v56, v125
	v_mov_b32_e32 v55, v125
	v_mov_b32_e32 v54, v125
	v_mov_b32_e32 v53, v125
	v_mov_b32_e32 v52, v125
	v_mov_b32_e32 v51, v125
	v_mov_b32_e32 v50, v125
	v_mov_b32_e32 v41, v125
	v_mov_b32_e32 v40, v125
	v_mov_b32_e32 v39, v125
	v_mov_b32_e32 v38, v125
	v_mov_b32_e32 v37, v125
	v_mov_b32_e32 v36, v125
	v_mov_b32_e32 v35, v125
	v_mov_b32_e32 v34, v125
	v_mov_b32_e32 v25, v125
	v_mov_b32_e32 v24, v125
	v_mov_b32_e32 v23, v125
	v_mov_b32_e32 v22, v125
	v_mov_b32_e32 v21, v125
	v_mov_b32_e32 v20, v125
	v_mov_b32_e32 v19, v125
	v_mov_b32_e32 v18, v125
	v_mov_b32_e32 v9, v125
	v_mov_b32_e32 v8, v125
	v_mov_b32_e32 v7, v125
	v_mov_b32_e32 v6, v125
	v_mov_b32_e32 v5, v125
	v_mov_b32_e32 v4, v125
	v_mov_b32_e32 v3, v125
	v_mov_b32_e32 v2, v125
	s_cbranch_vccnz .LBB0_1520
	s_add_u32 s86, s36, 0x100
	s_addc_u32 s87, s37, 0
	s_add_u32 s36, s38, 0x80
	v_mov_b32_e32 v2, 0
	s_addc_u32 s37, s39, 0
	s_mov_b32 s38, 0
	v_mov_b32_e32 v3, v2
	v_mov_b32_e32 v4, v2
	v_mov_b32_e32 v5, v2
	v_mov_b32_e32 v6, v2
	v_mov_b32_e32 v7, v2
	v_mov_b32_e32 v8, v2
	v_mov_b32_e32 v9, v2
	v_mov_b32_e32 v18, v2
	v_mov_b32_e32 v19, v2
	v_mov_b32_e32 v20, v2
	v_mov_b32_e32 v21, v2
	v_mov_b32_e32 v22, v2
	v_mov_b32_e32 v23, v2
	v_mov_b32_e32 v24, v2
	v_mov_b32_e32 v25, v2
	v_mov_b32_e32 v34, v2
	v_mov_b32_e32 v35, v2
	v_mov_b32_e32 v36, v2
	v_mov_b32_e32 v37, v2
	v_mov_b32_e32 v38, v2
	v_mov_b32_e32 v39, v2
	v_mov_b32_e32 v40, v2
	v_mov_b32_e32 v41, v2
	v_mov_b32_e32 v50, v2
	v_mov_b32_e32 v51, v2
	v_mov_b32_e32 v52, v2
	v_mov_b32_e32 v53, v2
	v_mov_b32_e32 v54, v2
	v_mov_b32_e32 v55, v2
	v_mov_b32_e32 v56, v2
	v_mov_b32_e32 v57, v2
	v_mov_b32_e32 v10, v2
	v_mov_b32_e32 v11, v2
	v_mov_b32_e32 v12, v2
	v_mov_b32_e32 v13, v2
	v_mov_b32_e32 v14, v2
	v_mov_b32_e32 v15, v2
	v_mov_b32_e32 v16, v2
	v_mov_b32_e32 v17, v2
	v_mov_b32_e32 v26, v2
	v_mov_b32_e32 v27, v2
	v_mov_b32_e32 v28, v2
	v_mov_b32_e32 v29, v2
	v_mov_b32_e32 v30, v2
	v_mov_b32_e32 v31, v2
	v_mov_b32_e32 v32, v2
	v_mov_b32_e32 v33, v2
	v_mov_b32_e32 v42, v2
	v_mov_b32_e32 v43, v2
	v_mov_b32_e32 v44, v2
	v_mov_b32_e32 v45, v2
	v_mov_b32_e32 v46, v2
	v_mov_b32_e32 v47, v2
	v_mov_b32_e32 v48, v2
	v_mov_b32_e32 v49, v2
	v_mov_b32_e32 v58, v2
	v_mov_b32_e32 v59, v2
	v_mov_b32_e32 v60, v2
	v_mov_b32_e32 v61, v2
	v_mov_b32_e32 v62, v2
	v_mov_b32_e32 v63, v2
	v_mov_b32_e32 v64, v2
	v_mov_b32_e32 v65, v2
	v_mov_b32_e32 v66, v2
	v_mov_b32_e32 v67, v2
	v_mov_b32_e32 v68, v2
	v_mov_b32_e32 v69, v2
	v_mov_b32_e32 v70, v2
	v_mov_b32_e32 v71, v2
	v_mov_b32_e32 v72, v2
	v_mov_b32_e32 v73, v2
	v_mov_b32_e32 v82, v2
	v_mov_b32_e32 v83, v2
	v_mov_b32_e32 v84, v2
	v_mov_b32_e32 v85, v2
	v_mov_b32_e32 v86, v2
	v_mov_b32_e32 v87, v2
	v_mov_b32_e32 v88, v2
	v_mov_b32_e32 v89, v2
	v_mov_b32_e32 v98, v2
	v_mov_b32_e32 v99, v2
	v_mov_b32_e32 v100, v2
	v_mov_b32_e32 v101, v2
	v_mov_b32_e32 v102, v2
	v_mov_b32_e32 v103, v2
	v_mov_b32_e32 v104, v2
	v_mov_b32_e32 v105, v2
	v_mov_b32_e32 v114, v2
	v_mov_b32_e32 v115, v2
	v_mov_b32_e32 v116, v2
	v_mov_b32_e32 v117, v2
	v_mov_b32_e32 v118, v2
	v_mov_b32_e32 v119, v2
	v_mov_b32_e32 v120, v2
	v_mov_b32_e32 v121, v2
	v_mov_b32_e32 v74, v2
	v_mov_b32_e32 v75, v2
	v_mov_b32_e32 v76, v2
	v_mov_b32_e32 v77, v2
	v_mov_b32_e32 v78, v2
	v_mov_b32_e32 v79, v2
	v_mov_b32_e32 v80, v2
	v_mov_b32_e32 v81, v2
	v_mov_b32_e32 v90, v2
	v_mov_b32_e32 v91, v2
	v_mov_b32_e32 v92, v2
	v_mov_b32_e32 v93, v2
	v_mov_b32_e32 v94, v2
	v_mov_b32_e32 v95, v2
	v_mov_b32_e32 v96, v2
	v_mov_b32_e32 v97, v2
	v_mov_b32_e32 v106, v2
	v_mov_b32_e32 v107, v2
	v_mov_b32_e32 v108, v2
	v_mov_b32_e32 v109, v2
	v_mov_b32_e32 v110, v2
	v_mov_b32_e32 v111, v2
	v_mov_b32_e32 v112, v2
	v_mov_b32_e32 v113, v2
	v_mov_b32_e32 v126, v2
	v_mov_b32_e32 v127, v2
	v_mov_b32_e32 v128, v2
	v_mov_b32_e32 v129, v2
	v_mov_b32_e32 v122, v2
	v_mov_b32_e32 v123, v2
	v_mov_b32_e32 v124, v2
	v_mov_b32_e32 v125, v2
	.p2align	6

; #define PG8_STAGE(bufoff, gbase, voff) do { _Pragma("unroll") for (int _i = 0; _i < 2; ++_i) \
;         __builtin_amdgcn_global_load_lds((const unsigned*)((const char*)(gbase) + (voff)[_i]), (PG8_LAS unsigned*)(lds + (bufoff) + ldsw + _i * 8192), 16, 0, 0); } while (0)
; #define PG8_WAIT_V(n) asm volatile("s_waitcnt vmcnt(" #n ")" ::: "memory")
; #define PG8_BAR __builtin_amdgcn_s_barrier()
; template <class Epi, class Sched, bool ALIGN_EPI = false, bool SP2 = false>
; __device__ __forceinline__ void gemm_phase(PG8_LAS unsigned char* lds, const Gemm g, const Sched& S, const Epi& E) {
;     ...
;     for (int i = 0; i < 2; ++i) { int R, C; stage_rc(tid * 16 + i * 8192, R, C); const int Rb = Epi::PERM ? ((R & ~31) + perm32(R & 31)) : R;
;         voffA[i] = (unsigned)(R * K + C) * 2u; voffB[i] = (unsigned)(Rb * K + C) * 2u; }
;     const size_t kstep = (size_t)(BK * 2);
;     const size_t hstep = (size_t)HALF * K * 2;
;     const size_t tstep = 2 * hstep;
;     const unsigned ldsw = (unsigned)wid * 1024u;
;     const int aoff = lds_byte(wr * 64 + fr, fq * 8), boff = lds_byte(wc * 32 + fr, fq * 8);
;     ...
;         if (wr == 1) PG8_BAR;
;         PG8_WAIT_V(2); PG8_BAR;
;         PG8_STAGE(PG8_SB(1, 0), cB + kstep, voffB); PG8_STAGE(PG8_SA(1, 0), cA + kstep, voffA); PG8_STAGE(PG8_SB(1, 1), cB + hstep + kstep, voffB);
;         PG8_WAIT_V(6); PG8_BAR;
.LBB0_1533:
	s_add_u32 s18, s0, 0xf500000
	s_mov_b64 s[20:21], 0x80
	s_addc_u32 s19, s1, 0
	s_add_i32 m0, s37, 0x18000
	v_lshl_add_u64 v[10:11], v[10:11], 0, s[20:21]
	s_waitcnt vmcnt(2)
	s_barrier
	global_load_lds_dwordx4 v[10:11], off
	v_lshl_add_u64 v[6:7], v[6:7], 0, s[20:21]
	s_add_i32 m0, s37, 0x1a000
	s_add_i32 s42, s37, 0x8000
	global_load_lds_dwordx4 v[6:7], off
	v_lshl_add_u64 v[6:7], v[8:9], 0, s[20:21]
	s_mov_b32 m0, s42
	s_add_i32 s43, s37, 0xa000
	global_load_lds_dwordx4 v[6:7], off
	v_lshl_add_u64 v[6:7], v[12:13], 0, s[20:21]
	s_mov_b32 m0, s43
	v_lshl_add_u64 v[4:5], v[4:5], 0, s[20:21]
	global_load_lds_dwordx4 v[6:7], off
	s_add_i32 m0, s37, 0x1c000
	v_lshl_add_u64 v[2:3], v[2:3], 0, s[20:21]
	global_load_lds_dwordx4 v[4:5], off
	s_add_i32 m0, s37, 0x1e000
	s_lshr_b32 s0, s9, 26
	global_load_lds_dwordx4 v[2:3], off
	s_add_i32 s0, s8, s0
	v_lshlrev_b32_e32 v3, 2, v156
	s_ashr_i32 s44, s0, 6
	v_lshl_or_b32 v2, v156, 6, v158
	s_lshl_b32 s0, s22, 13
	v_and_b32_e32 v3, 32, v3
	v_bitop3_b32 v4, v2, s0, v3 bitop3:0xde
	v_add_u32_e32 v2, v157, v153
	v_mul_lo_u32 v2, s8, v2
	s_lshl_b32 s0, s5, 5
	v_lshlrev_b32_e32 v2, 1, v2
	s_and_b32 s0, s0, 0x60
	v_add3_u32 v2, v1, v2, v152
	v_mov_b32_e32 v3, v133
	s_cmp_gt_i32 s8, 63
	v_lshl_add_u64 v[138:139], s[10:11], 0, v[2:3]
	v_add_u32_e32 v2, v154, v153
	v_lshl_or_b32 v160, s22, 6, v156
	s_cselect_b64 s[22:23], -1, 0
	s_add_i32 s45, s44, -2
	v_mul_lo_u32 v2, s8, v2
	s_waitcnt vmcnt(6)
	s_cmpk_lt_u32 s24, 0x100
	v_lshlrev_b32_e32 v2, 1, v2
	v_lshl_or_b32 v156, s0, 7, v159
	s_cselect_b64 s[24:25], -1, 0
	v_add3_u32 v2, v1, v2, v152
	s_add_i32 s48, 0, 0x10000
	s_add_i32 s49, 0, 0x14000
	s_sext_i32_i8 s55, s4
	s_ashr_i32 s46, s82, 31
	s_mov_b32 s47, s82
	v_or_b32_e32 v155, s0, v155
	v_lshl_add_u64 v[140:141], s[10:11], 0, v[2:3]
	v_mov_b64_e32 v[142:143], 0x200
	v_mov_b64_e32 v[144:145], 0x1ff
	v_add_u32_e32 v1, s48, v156
	v_add_u32_e32 v152, s49, v156
	v_add_u32_e32 v153, 0, v4
	s_barrier
	s_branch .LBB0_1536
	.p2align	6

; template <class Epi, class Sched, bool ALIGN_EPI = false, bool SP2 = false>
; __device__ __forceinline__ void gemm_phase(PG8_LAS unsigned char* lds, const Gemm g, const Sched& S, const Epi& E) {
;     ...
;         if (!has_next) break;
; #pragma unroll
;         for (int a = 0; a < 2; ++a)
; #pragma unroll
;             for (int b = 0; b < 2; ++b)
; #pragma unroll
;                 for (int m = 0; m < 4; ++m)
; #pragma unroll
;                     for (int n = 0; n < 2; ++n) acc[a][b][m][n] = (f32x4){0.f, 0.f, 0.f, 0.f};
;         cur = nxt; cA = nA; cB = nB; ++ui;
.LBB0_1546:
	v_mov_b32_e32 v125, 0
	s_andn2_b64 vcc, exec, s[22:23]
	v_mov_b32_e32 v124, v125
	v_mov_b32_e32 v123, v125
	v_mov_b32_e32 v122, v125
	v_mov_b32_e32 v129, v125
	v_mov_b32_e32 v128, v125
	v_mov_b32_e32 v127, v125
	v_mov_b32_e32 v126, v125
	v_mov_b32_e32 v113, v125
	v_mov_b32_e32 v112, v125
	v_mov_b32_e32 v111, v125
	v_mov_b32_e32 v110, v125
	v_mov_b32_e32 v109, v125
	v_mov_b32_e32 v108, v125
	v_mov_b32_e32 v107, v125
	v_mov_b32_e32 v106, v125
	s_waitcnt vmcnt(0)
	v_mov_b32_e32 v97, v125
	v_mov_b32_e32 v96, v125
	v_mov_b32_e32 v95, v125
	v_mov_b32_e32 v94, v125
	v_mov_b32_e32 v93, v125
	v_mov_b32_e32 v92, v125
	v_mov_b32_e32 v91, v125
	v_mov_b32_e32 v90, v125
	v_mov_b32_e32 v81, v125
	v_mov_b32_e32 v80, v125
	v_mov_b32_e32 v79, v125
	v_mov_b32_e32 v78, v125
	v_mov_b32_e32 v77, v125
	v_mov_b32_e32 v76, v125
	v_mov_b32_e32 v75, v125
	v_mov_b32_e32 v74, v125
	v_mov_b32_e32 v121, v125
	v_mov_b32_e32 v120, v125
	v_mov_b32_e32 v119, v125
	v_mov_b32_e32 v118, v125
	v_mov_b32_e32 v117, v125
	v_mov_b32_e32 v116, v125
	v_mov_b32_e32 v115, v125
	v_mov_b32_e32 v114, v125
	v_mov_b32_e32 v105, v125
	v_mov_b32_e32 v104, v125
	v_mov_b32_e32 v103, v125
	v_mov_b32_e32 v102, v125
	v_mov_b32_e32 v101, v125
	v_mov_b32_e32 v100, v125
	v_mov_b32_e32 v99, v125
	v_mov_b32_e32 v98, v125
	v_mov_b32_e32 v89, v125
	v_mov_b32_e32 v88, v125
	v_mov_b32_e32 v87, v125
	v_mov_b32_e32 v86, v125
	v_mov_b32_e32 v85, v125
	v_mov_b32_e32 v84, v125
	v_mov_b32_e32 v83, v125
	v_mov_b32_e32 v82, v125
	v_mov_b32_e32 v73, v125
	v_mov_b32_e32 v72, v125
	v_mov_b32_e32 v71, v125
	v_mov_b32_e32 v70, v125
	v_mov_b32_e32 v69, v125
	v_mov_b32_e32 v68, v125
	v_mov_b32_e32 v67, v125
	v_mov_b32_e32 v66, v125
	v_mov_b32_e32 v65, v125
	v_mov_b32_e32 v64, v125
	v_mov_b32_e32 v63, v125
	v_mov_b32_e32 v62, v125
	v_mov_b32_e32 v61, v125
	v_mov_b32_e32 v60, v125
	v_mov_b32_e32 v59, v125
	v_mov_b32_e32 v58, v125
	v_mov_b32_e32 v49, v125
	v_mov_b32_e32 v48, v125
	v_mov_b32_e32 v47, v125
	v_mov_b32_e32 v46, v125
	v_mov_b32_e32 v45, v125
	v_mov_b32_e32 v44, v125
	v_mov_b32_e32 v43, v125
	v_mov_b32_e32 v42, v125
	v_mov_b32_e32 v33, v125
	v_mov_b32_e32 v32, v125
	v_mov_b32_e32 v31, v125
	v_mov_b32_e32 v30, v125
	v_mov_b32_e32 v29, v125
	v_mov_b32_e32 v28, v125
	v_mov_b32_e32 v27, v125
	v_mov_b32_e32 v26, v125
	v_mov_b32_e32 v17, v125
	v_mov_b32_e32 v16, v125
	v_mov_b32_e32 v15, v125
	v_mov_b32_e32 v14, v125
	v_mov_b32_e32 v13, v125
	v_mov_b32_e32 v12, v125
	v_mov_b32_e32 v11, v125
	v_mov_b32_e32 v10, v125
	v_mov_b32_e32 v57, v125
	v_mov_b32_e32 v56, v125
	v_mov_b32_e32 v55, v125
	v_mov_b32_e32 v54, v125
	v_mov_b32_e32 v53, v125
	v_mov_b32_e32 v52, v125
	v_mov_b32_e32 v51, v125
	v_mov_b32_e32 v50, v125
	v_mov_b32_e32 v41, v125
	v_mov_b32_e32 v40, v125
	v_mov_b32_e32 v39, v125
	v_mov_b32_e32 v38, v125
	v_mov_b32_e32 v37, v125
	v_mov_b32_e32 v36, v125
	v_mov_b32_e32 v35, v125
	v_mov_b32_e32 v34, v125
	v_mov_b32_e32 v25, v125
	v_mov_b32_e32 v24, v125
	v_mov_b32_e32 v23, v125
	v_mov_b32_e32 v22, v125
	v_mov_b32_e32 v21, v125
	v_mov_b32_e32 v20, v125
	v_mov_b32_e32 v19, v125
	v_mov_b32_e32 v18, v125
	v_mov_b32_e32 v9, v125
	v_mov_b32_e32 v8, v125
	v_mov_b32_e32 v7, v125
	v_mov_b32_e32 v6, v125
	v_mov_b32_e32 v5, v125
	v_mov_b32_e32 v4, v125
	v_mov_b32_e32 v3, v125
	v_mov_b32_e32 v2, v125
	s_cbranch_vccnz .LBB0_1549
	s_add_u32 s56, s26, 0x100
	s_addc_u32 s57, s27, 0
	s_add_u32 s26, s28, 0x80
	v_mov_b32_e32 v2, 0
	s_addc_u32 s27, s29, 0
	s_mov_b32 s28, 0
	v_mov_b32_e32 v3, v2
	v_mov_b32_e32 v4, v2
	v_mov_b32_e32 v5, v2
	v_mov_b32_e32 v6, v2
	v_mov_b32_e32 v7, v2
	v_mov_b32_e32 v8, v2
	v_mov_b32_e32 v9, v2
	v_mov_b32_e32 v18, v2
	v_mov_b32_e32 v19, v2
	v_mov_b32_e32 v20, v2
	v_mov_b32_e32 v21, v2
	v_mov_b32_e32 v22, v2
	v_mov_b32_e32 v23, v2
	v_mov_b32_e32 v24, v2
	v_mov_b32_e32 v25, v2
	v_mov_b32_e32 v34, v2
	v_mov_b32_e32 v35, v2
	v_mov_b32_e32 v36, v2
	v_mov_b32_e32 v37, v2
	v_mov_b32_e32 v38, v2
	v_mov_b32_e32 v39, v2
	v_mov_b32_e32 v40, v2
	v_mov_b32_e32 v41, v2
	v_mov_b32_e32 v50, v2
	v_mov_b32_e32 v51, v2
	v_mov_b32_e32 v52, v2
	v_mov_b32_e32 v53, v2
	v_mov_b32_e32 v54, v2
	v_mov_b32_e32 v55, v2
	v_mov_b32_e32 v56, v2
	v_mov_b32_e32 v57, v2
	v_mov_b32_e32 v10, v2
	v_mov_b32_e32 v11, v2
	v_mov_b32_e32 v12, v2
	v_mov_b32_e32 v13, v2
	v_mov_b32_e32 v14, v2
	v_mov_b32_e32 v15, v2
	v_mov_b32_e32 v16, v2
	v_mov_b32_e32 v17, v2
	v_mov_b32_e32 v26, v2
	v_mov_b32_e32 v27, v2
	v_mov_b32_e32 v28, v2
	v_mov_b32_e32 v29, v2
	v_mov_b32_e32 v30, v2
	v_mov_b32_e32 v31, v2
	v_mov_b32_e32 v32, v2
	v_mov_b32_e32 v33, v2
	v_mov_b32_e32 v42, v2
	v_mov_b32_e32 v43, v2
	v_mov_b32_e32 v44, v2
	v_mov_b32_e32 v45, v2
	v_mov_b32_e32 v46, v2
	v_mov_b32_e32 v47, v2
	v_mov_b32_e32 v48, v2
	v_mov_b32_e32 v49, v2
	v_mov_b32_e32 v58, v2
	v_mov_b32_e32 v59, v2
	v_mov_b32_e32 v60, v2
	v_mov_b32_e32 v61, v2
	v_mov_b32_e32 v62, v2
	v_mov_b32_e32 v63, v2
	v_mov_b32_e32 v64, v2
	v_mov_b32_e32 v65, v2
	v_mov_b32_e32 v66, v2
	v_mov_b32_e32 v67, v2
	v_mov_b32_e32 v68, v2
	v_mov_b32_e32 v69, v2
	v_mov_b32_e32 v70, v2
	v_mov_b32_e32 v71, v2
	v_mov_b32_e32 v72, v2
	v_mov_b32_e32 v73, v2
	v_mov_b32_e32 v82, v2
	v_mov_b32_e32 v83, v2
	v_mov_b32_e32 v84, v2
	v_mov_b32_e32 v85, v2
	v_mov_b32_e32 v86, v2
	v_mov_b32_e32 v87, v2
	v_mov_b32_e32 v88, v2
	v_mov_b32_e32 v89, v2
	v_mov_b32_e32 v98, v2
	v_mov_b32_e32 v99, v2
	v_mov_b32_e32 v100, v2
	v_mov_b32_e32 v101, v2
	v_mov_b32_e32 v102, v2
	v_mov_b32_e32 v103, v2
	v_mov_b32_e32 v104, v2
	v_mov_b32_e32 v105, v2
	v_mov_b32_e32 v114, v2
	v_mov_b32_e32 v115, v2
	v_mov_b32_e32 v116, v2
	v_mov_b32_e32 v117, v2
	v_mov_b32_e32 v118, v2
	v_mov_b32_e32 v119, v2
	v_mov_b32_e32 v120, v2
	v_mov_b32_e32 v121, v2
	v_mov_b32_e32 v74, v2
	v_mov_b32_e32 v75, v2
	v_mov_b32_e32 v76, v2
	v_mov_b32_e32 v77, v2
	v_mov_b32_e32 v78, v2
	v_mov_b32_e32 v79, v2
	v_mov_b32_e32 v80, v2
	v_mov_b32_e32 v81, v2
	v_mov_b32_e32 v90, v2
	v_mov_b32_e32 v91, v2
	v_mov_b32_e32 v92, v2
	v_mov_b32_e32 v93, v2
	v_mov_b32_e32 v94, v2
	v_mov_b32_e32 v95, v2
	v_mov_b32_e32 v96, v2
	v_mov_b32_e32 v97, v2
	v_mov_b32_e32 v106, v2
	v_mov_b32_e32 v107, v2
	v_mov_b32_e32 v108, v2
	v_mov_b32_e32 v109, v2
	v_mov_b32_e32 v110, v2
	v_mov_b32_e32 v111, v2
	v_mov_b32_e32 v112, v2
	v_mov_b32_e32 v113, v2
	v_mov_b32_e32 v126, v2
	v_mov_b32_e32 v127, v2
	v_mov_b32_e32 v128, v2
	v_mov_b32_e32 v129, v2
	v_mov_b32_e32 v122, v2
	v_mov_b32_e32 v123, v2
	v_mov_b32_e32 v124, v2
	v_mov_b32_e32 v125, v2
	.p2align	6

; #define PG8_STAGE(bufoff, gbase, voff) do { _Pragma("unroll") for (int _i = 0; _i < 2; ++_i) \
;         __builtin_amdgcn_global_load_lds((const unsigned*)((const char*)(gbase) + (voff)[_i]), (PG8_LAS unsigned*)(lds + (bufoff) + ldsw + _i * 8192), 16, 0, 0); } while (0)
; #define PG8_WAIT_V(n) asm volatile("s_waitcnt vmcnt(" #n ")" ::: "memory")
; #define PG8_BAR __builtin_amdgcn_s_barrier()
; template <class Epi, class Sched, bool ALIGN_EPI = false, bool SP2 = false>
; __device__ __forceinline__ void gemm_phase(PG8_LAS unsigned char* lds, const Gemm g, const Sched& S, const Epi& E) {
;     const int tid = threadIdx.x, wid = __builtin_amdgcn_readfirstlane(tid >> 6), lane = tid & 63, wr = wid >> 2, wc = wid & 3, fr = lane & 15, fq = lane >> 4;
;     const int K = g.K, nt = K / BK;
;     unsigned voffA[2], voffB[2];
; #pragma unroll
;     for (int i = 0; i < 2; ++i) { int R, C; stage_rc(tid * 16 + i * 8192, R, C); const int Rb = Epi::PERM ? ((R & ~31) + perm32(R & 31)) : R;
;         voffA[i] = (unsigned)(R * K + C) * 2u; voffB[i] = (unsigned)(Rb * K + C) * 2u; }
;     const size_t kstep = (size_t)(BK * 2);
;     const size_t hstep = (size_t)HALF * K * 2;
;     const size_t tstep = 2 * hstep;
;     const unsigned ldsw = (unsigned)wid * 1024u;
;     const int aoff = lds_byte(wr * 64 + fr, fq * 8), boff = lds_byte(wc * 32 + fr, fq * 8);
;     ...
;         PG8_STAGE(PG8_SB(0, 0), cB, voffB); PG8_STAGE(PG8_SB(0, 1), cB + hstep, voffB); PG8_STAGE(PG8_SA(0, 0), cA, voffA); PG8_STAGE(PG8_SA(0, 1), cA + hstep, voffA);
;         if (wr == 1) PG8_BAR;
;         PG8_WAIT_V(2); PG8_BAR;
;         PG8_STAGE(PG8_SB(1, 0), cB + kstep, voffB); PG8_STAGE(PG8_SA(1, 0), cA + kstep, voffA); PG8_STAGE(PG8_SB(1, 1), cB + hstep + kstep, voffB);
;         PG8_WAIT_V(6); PG8_BAR;
.LBB0_1709:
	s_add_u32 s14, s4, 0x3500000
	s_addc_u32 s15, s5, 0
	s_add_u32 s16, s4, 0x13500000
	s_addc_u32 s17, s5, 0
	s_add_u32 s18, s4, 0x19500000
	s_addc_u32 s19, s5, 0
	s_add_u32 s20, s4, 0x1d500000
	s_addc_u32 s21, s5, 0
	s_add_u32 s22, s4, 0x1e500000
	s_mov_b64 s[24:25], 0x80
	s_addc_u32 s23, s5, 0
	s_add_i32 m0, s48, 0x18000
	v_lshl_add_u64 v[10:11], v[10:11], 0, s[24:25]
	s_waitcnt vmcnt(2)
	s_barrier
	global_load_lds_dwordx4 v[10:11], off
	v_lshl_add_u64 v[6:7], v[6:7], 0, s[24:25]
	s_add_i32 m0, s48, 0x1a000
	s_add_i32 s55, s48, 0x8000
	global_load_lds_dwordx4 v[6:7], off
	v_lshl_add_u64 v[6:7], v[8:9], 0, s[24:25]
	s_mov_b32 m0, s55
	s_add_i32 s56, s48, 0xa000
	global_load_lds_dwordx4 v[6:7], off
	v_lshl_add_u64 v[6:7], v[12:13], 0, s[24:25]
	s_mov_b32 m0, s56
	v_lshl_add_u64 v[4:5], v[4:5], 0, s[24:25]
	global_load_lds_dwordx4 v[6:7], off
	s_add_i32 m0, s48, 0x1c000
	v_lshl_add_u64 v[2:3], v[2:3], 0, s[24:25]
	global_load_lds_dwordx4 v[4:5], off
	s_add_i32 m0, s48, 0x1e000
	s_lshr_b32 s1, s1, 26
	global_load_lds_dwordx4 v[2:3], off
	v_and_b32_e32 v2, 15, v0
	s_add_i32 s1, s0, s1
	v_lshlrev_b32_e32 v3, 1, v130
	v_lshlrev_b32_e32 v4, 2, v0
	s_ashr_i32 s57, s1, 6
	v_lshl_or_b32 v1, s29, 6, v2
	v_lshl_or_b32 v2, v2, 6, v3
	s_lshl_b32 s1, s29, 13
	v_and_b32_e32 v4, 32, v4
	v_bitop3_b32 v5, v2, s1, v4 bitop3:0xde
	s_lshl_b32 s1, s27, 5
	s_and_b32 s58, s1, 0x60
	v_lshlrev_b32_e32 v2, 6, v0
	s_movk_i32 s1, 0x3c0
	v_and_or_b32 v2, v2, s1, v3
	s_lshl_b32 s1, s58, 7
	v_bitop3_b32 v156, s1, v2, v4 bitop3:0xf6
	v_add_u32_e32 v2, v18, v16
	v_mul_lo_u32 v2, s0, v2
	v_lshlrev_b32_e32 v2, 1, v2
	v_add3_u32 v2, v14, v2, v15
	v_mov_b32_e32 v3, v135
	s_cmp_gt_i32 s0, 63
	v_lshl_add_u64 v[140:141], s[8:9], 0, v[2:3]
	v_add_u32_e32 v2, v17, v16
	s_sext_i32_i8 s41, s26
	s_cselect_b64 s[26:27], -1, 0
	s_add_i32 s59, s57, -2
	v_mul_lo_u32 v2, s0, v2
	s_waitcnt vmcnt(6)
	s_cmpk_lt_u32 s28, 0x100
	v_lshlrev_b32_e32 v2, 1, v2
	s_cselect_b64 s[28:29], -1, 0
	v_add3_u32 v2, v14, v2, v15
	s_add_i32 s62, 0, 0x10000
	s_add_i32 s63, 0, 0x14000
	s_ashr_i32 s60, s82, 31
	s_mov_b32 s61, s82
	v_mov_b32_e32 v131, v135
	v_lshl_add_u64 v[142:143], s[8:9], 0, v[2:3]
	v_mov_b64_e32 v[144:145], 0x200
	v_mov_b64_e32 v[146:147], 0x1ff
	v_add_u32_e32 v157, s62, v156
	v_add_u32_e32 v158, s63, v156
	v_add_u32_e32 v159, 0, v5
	s_mov_b32 s30, 0x3c800000
	s_mov_b32 s68, 0x800000
	s_barrier
	s_branch .LBB0_1712
	.p2align	6

; template <class Epi, class Sched, bool ALIGN_EPI = false, bool SP2 = false>
; __device__ __forceinline__ void gemm_phase(PG8_LAS unsigned char* lds, const Gemm g, const Sched& S, const Epi& E) {
;     ...
;         if (!has_next) break;
; #pragma unroll
;         for (int a = 0; a < 2; ++a)
; #pragma unroll
;             for (int b = 0; b < 2; ++b)
; #pragma unroll
;                 for (int m = 0; m < 4; ++m)
; #pragma unroll
;                     for (int n = 0; n < 2; ++n) acc[a][b][m][n] = (f32x4){0.f, 0.f, 0.f, 0.f};
;         cur = nxt; cA = nA; cB = nB; ++ui;
.LBB0_1722:
	v_mov_b32_e32 v125, 0
	s_andn2_b64 vcc, exec, s[26:27]
	v_mov_b32_e32 v124, v125
	v_mov_b32_e32 v123, v125
	v_mov_b32_e32 v122, v125
	v_mov_b32_e32 v129, v125
	v_mov_b32_e32 v128, v125
	v_mov_b32_e32 v127, v125
	v_mov_b32_e32 v126, v125
	v_mov_b32_e32 v113, v125
	v_mov_b32_e32 v112, v125
	v_mov_b32_e32 v111, v125
	v_mov_b32_e32 v110, v125
	v_mov_b32_e32 v109, v125
	v_mov_b32_e32 v108, v125
	v_mov_b32_e32 v107, v125
	v_mov_b32_e32 v106, v125
	s_waitcnt vmcnt(0)
	v_mov_b32_e32 v97, v125
	v_mov_b32_e32 v96, v125
	v_mov_b32_e32 v95, v125
	v_mov_b32_e32 v94, v125
	v_mov_b32_e32 v93, v125
	v_mov_b32_e32 v92, v125
	v_mov_b32_e32 v91, v125
	v_mov_b32_e32 v90, v125
	v_mov_b32_e32 v81, v125
	v_mov_b32_e32 v80, v125
	v_mov_b32_e32 v79, v125
	v_mov_b32_e32 v78, v125
	v_mov_b32_e32 v77, v125
	v_mov_b32_e32 v76, v125
	v_mov_b32_e32 v75, v125
	v_mov_b32_e32 v74, v125
	v_mov_b32_e32 v121, v125
	v_mov_b32_e32 v120, v125
	v_mov_b32_e32 v119, v125
	v_mov_b32_e32 v118, v125
	v_mov_b32_e32 v117, v125
	v_mov_b32_e32 v116, v125
	v_mov_b32_e32 v115, v125
	v_mov_b32_e32 v114, v125
	v_mov_b32_e32 v105, v125
	v_mov_b32_e32 v104, v125
	v_mov_b32_e32 v103, v125
	v_mov_b32_e32 v102, v125
	v_mov_b32_e32 v101, v125
	v_mov_b32_e32 v100, v125
	v_mov_b32_e32 v99, v125
	v_mov_b32_e32 v98, v125
	v_mov_b32_e32 v89, v125
	v_mov_b32_e32 v88, v125
	v_mov_b32_e32 v87, v125
	v_mov_b32_e32 v86, v125
	v_mov_b32_e32 v85, v125
	v_mov_b32_e32 v84, v125
	v_mov_b32_e32 v83, v125
	v_mov_b32_e32 v82, v125
	v_mov_b32_e32 v73, v125
	v_mov_b32_e32 v72, v125
	v_mov_b32_e32 v71, v125
	v_mov_b32_e32 v70, v125
	v_mov_b32_e32 v69, v125
	v_mov_b32_e32 v68, v125
	v_mov_b32_e32 v67, v125
	v_mov_b32_e32 v66, v125
	v_mov_b32_e32 v65, v125
	v_mov_b32_e32 v64, v125
	v_mov_b32_e32 v63, v125
	v_mov_b32_e32 v62, v125
	v_mov_b32_e32 v61, v125
	v_mov_b32_e32 v60, v125
	v_mov_b32_e32 v59, v125
	v_mov_b32_e32 v58, v125
	v_mov_b32_e32 v49, v125
	v_mov_b32_e32 v48, v125
	v_mov_b32_e32 v47, v125
	v_mov_b32_e32 v46, v125
	v_mov_b32_e32 v45, v125
	v_mov_b32_e32 v44, v125
	v_mov_b32_e32 v43, v125
	v_mov_b32_e32 v42, v125
	v_mov_b32_e32 v33, v125
	v_mov_b32_e32 v32, v125
	v_mov_b32_e32 v31, v125
	v_mov_b32_e32 v30, v125
	v_mov_b32_e32 v29, v125
	v_mov_b32_e32 v28, v125
	v_mov_b32_e32 v27, v125
	v_mov_b32_e32 v26, v125
	v_mov_b32_e32 v17, v125
	v_mov_b32_e32 v16, v125
	v_mov_b32_e32 v15, v125
	v_mov_b32_e32 v14, v125
	v_mov_b32_e32 v13, v125
	v_mov_b32_e32 v12, v125
	v_mov_b32_e32 v11, v125
	v_mov_b32_e32 v10, v125
	v_mov_b32_e32 v57, v125
	v_mov_b32_e32 v56, v125
	v_mov_b32_e32 v55, v125
	v_mov_b32_e32 v54, v125
	v_mov_b32_e32 v53, v125
	v_mov_b32_e32 v52, v125
	v_mov_b32_e32 v51, v125
	v_mov_b32_e32 v50, v125
	v_mov_b32_e32 v41, v125
	v_mov_b32_e32 v40, v125
	v_mov_b32_e32 v39, v125
	v_mov_b32_e32 v38, v125
	v_mov_b32_e32 v37, v125
	v_mov_b32_e32 v36, v125
	v_mov_b32_e32 v35, v125
	v_mov_b32_e32 v34, v125
	v_mov_b32_e32 v25, v125
	v_mov_b32_e32 v24, v125
	v_mov_b32_e32 v23, v125
	v_mov_b32_e32 v22, v125
	v_mov_b32_e32 v21, v125
	v_mov_b32_e32 v20, v125
	v_mov_b32_e32 v19, v125
	v_mov_b32_e32 v18, v125
	v_mov_b32_e32 v9, v125
	v_mov_b32_e32 v8, v125
	v_mov_b32_e32 v7, v125
	v_mov_b32_e32 v6, v125
	v_mov_b32_e32 v5, v125
	v_mov_b32_e32 v4, v125
	v_mov_b32_e32 v3, v125
	v_mov_b32_e32 v2, v125
	s_cbranch_vccnz .LBB0_1725
	s_add_u32 s44, s36, 0x100
	s_addc_u32 s45, s37, 0
	s_add_u32 s36, s38, 0x80
	v_mov_b32_e32 v2, 0
	s_addc_u32 s37, s39, 0
	s_mov_b32 s38, 0
	v_mov_b32_e32 v3, v2
	v_mov_b32_e32 v4, v2
	v_mov_b32_e32 v5, v2
	v_mov_b32_e32 v6, v2
	v_mov_b32_e32 v7, v2
	v_mov_b32_e32 v8, v2
	v_mov_b32_e32 v9, v2
	v_mov_b32_e32 v18, v2
	v_mov_b32_e32 v19, v2
	v_mov_b32_e32 v20, v2
	v_mov_b32_e32 v21, v2
	v_mov_b32_e32 v22, v2
	v_mov_b32_e32 v23, v2
	v_mov_b32_e32 v24, v2
	v_mov_b32_e32 v25, v2
	v_mov_b32_e32 v34, v2
	v_mov_b32_e32 v35, v2
	v_mov_b32_e32 v36, v2
	v_mov_b32_e32 v37, v2
	v_mov_b32_e32 v38, v2
	v_mov_b32_e32 v39, v2
	v_mov_b32_e32 v40, v2
	v_mov_b32_e32 v41, v2
	v_mov_b32_e32 v50, v2
	v_mov_b32_e32 v51, v2
	v_mov_b32_e32 v52, v2
	v_mov_b32_e32 v53, v2
	v_mov_b32_e32 v54, v2
	v_mov_b32_e32 v55, v2
	v_mov_b32_e32 v56, v2
	v_mov_b32_e32 v57, v2
	v_mov_b32_e32 v10, v2
	v_mov_b32_e32 v11, v2
	v_mov_b32_e32 v12, v2
	v_mov_b32_e32 v13, v2
	v_mov_b32_e32 v14, v2
	v_mov_b32_e32 v15, v2
	v_mov_b32_e32 v16, v2
	v_mov_b32_e32 v17, v2
	v_mov_b32_e32 v26, v2
	v_mov_b32_e32 v27, v2
	v_mov_b32_e32 v28, v2
	v_mov_b32_e32 v29, v2
	v_mov_b32_e32 v30, v2
	v_mov_b32_e32 v31, v2
	v_mov_b32_e32 v32, v2
	v_mov_b32_e32 v33, v2
	v_mov_b32_e32 v42, v2
	v_mov_b32_e32 v43, v2
	v_mov_b32_e32 v44, v2
	v_mov_b32_e32 v45, v2
	v_mov_b32_e32 v46, v2
	v_mov_b32_e32 v47, v2
	v_mov_b32_e32 v48, v2
	v_mov_b32_e32 v49, v2
	v_mov_b32_e32 v58, v2
	v_mov_b32_e32 v59, v2
	v_mov_b32_e32 v60, v2
	v_mov_b32_e32 v61, v2
	v_mov_b32_e32 v62, v2
	v_mov_b32_e32 v63, v2
	v_mov_b32_e32 v64, v2
	v_mov_b32_e32 v65, v2
	v_mov_b32_e32 v66, v2
	v_mov_b32_e32 v67, v2
	v_mov_b32_e32 v68, v2
	v_mov_b32_e32 v69, v2
	v_mov_b32_e32 v70, v2
	v_mov_b32_e32 v71, v2
	v_mov_b32_e32 v72, v2
	v_mov_b32_e32 v73, v2
	v_mov_b32_e32 v82, v2
	v_mov_b32_e32 v83, v2
	v_mov_b32_e32 v84, v2
	v_mov_b32_e32 v85, v2
	v_mov_b32_e32 v86, v2
	v_mov_b32_e32 v87, v2
	v_mov_b32_e32 v88, v2
	v_mov_b32_e32 v89, v2
	v_mov_b32_e32 v98, v2
	v_mov_b32_e32 v99, v2
	v_mov_b32_e32 v100, v2
	v_mov_b32_e32 v101, v2
	v_mov_b32_e32 v102, v2
	v_mov_b32_e32 v103, v2
	v_mov_b32_e32 v104, v2
	v_mov_b32_e32 v105, v2
	v_mov_b32_e32 v114, v2
	v_mov_b32_e32 v115, v2
	v_mov_b32_e32 v116, v2
	v_mov_b32_e32 v117, v2
	v_mov_b32_e32 v118, v2
	v_mov_b32_e32 v119, v2
	v_mov_b32_e32 v120, v2
	v_mov_b32_e32 v121, v2
	v_mov_b32_e32 v74, v2
	v_mov_b32_e32 v75, v2
	v_mov_b32_e32 v76, v2
	v_mov_b32_e32 v77, v2
	v_mov_b32_e32 v78, v2
	v_mov_b32_e32 v79, v2
	v_mov_b32_e32 v80, v2
	v_mov_b32_e32 v81, v2
	v_mov_b32_e32 v90, v2
	v_mov_b32_e32 v91, v2
	v_mov_b32_e32 v92, v2
	v_mov_b32_e32 v93, v2
	v_mov_b32_e32 v94, v2
	v_mov_b32_e32 v95, v2
	v_mov_b32_e32 v96, v2
	v_mov_b32_e32 v97, v2
	v_mov_b32_e32 v106, v2
	v_mov_b32_e32 v107, v2
	v_mov_b32_e32 v108, v2
	v_mov_b32_e32 v109, v2
	v_mov_b32_e32 v110, v2
	v_mov_b32_e32 v111, v2
	v_mov_b32_e32 v112, v2
	v_mov_b32_e32 v113, v2
	v_mov_b32_e32 v126, v2
	v_mov_b32_e32 v127, v2
	v_mov_b32_e32 v128, v2
	v_mov_b32_e32 v129, v2
	v_mov_b32_e32 v122, v2
	v_mov_b32_e32 v123, v2
	v_mov_b32_e32 v124, v2
	v_mov_b32_e32 v125, v2
	.p2align	6

; #define PG8_STAGE(bufoff, gbase, voff) do { _Pragma("unroll") for (int _i = 0; _i < 2; ++_i) \
;         __builtin_amdgcn_global_load_lds((const unsigned*)((const char*)(gbase) + (voff)[_i]), (PG8_LAS unsigned*)(lds + (bufoff) + ldsw + _i * 8192), 16, 0, 0); } while (0)
; #define PG8_WAIT_V(n) asm volatile("s_waitcnt vmcnt(" #n ")" ::: "memory")
; #define PG8_BAR __builtin_amdgcn_s_barrier()
; template <class Epi, class Sched, bool ALIGN_EPI = false, bool SP2 = false>
; __device__ __forceinline__ void gemm_phase(PG8_LAS unsigned char* lds, const Gemm g, const Sched& S, const Epi& E) {
;     const int tid = threadIdx.x, wid = __builtin_amdgcn_readfirstlane(tid >> 6), lane = tid & 63, wr = wid >> 2, wc = wid & 3, fr = lane & 15, fq = lane >> 4;
;     const int K = g.K, nt = K / BK;
;     unsigned voffA[2], voffB[2];
; #pragma unroll
;     for (int i = 0; i < 2; ++i) { int R, C; stage_rc(tid * 16 + i * 8192, R, C); const int Rb = Epi::PERM ? ((R & ~31) + perm32(R & 31)) : R;
;         voffA[i] = (unsigned)(R * K + C) * 2u; voffB[i] = (unsigned)(Rb * K + C) * 2u; }
;     const size_t kstep = (size_t)(BK * 2);
;     const size_t hstep = (size_t)HALF * K * 2;
;     const size_t tstep = 2 * hstep;
;     const unsigned ldsw = (unsigned)wid * 1024u;
;     const int aoff = lds_byte(wr * 64 + fr, fq * 8), boff = lds_byte(wc * 32 + fr, fq * 8);
;     ...
;         PG8_STAGE(PG8_SB(0, 0), cB, voffB); PG8_STAGE(PG8_SB(0, 1), cB + hstep, voffB); PG8_STAGE(PG8_SA(0, 0), cA, voffA); PG8_STAGE(PG8_SA(0, 1), cA + hstep, voffA);
;         if (wr == 1) PG8_BAR;
;         PG8_WAIT_V(2); PG8_BAR;
;         PG8_STAGE(PG8_SB(1, 0), cB + kstep, voffB); PG8_STAGE(PG8_SA(1, 0), cA + kstep, voffA); PG8_STAGE(PG8_SB(1, 1), cB + hstep + kstep, voffB);
;         PG8_WAIT_V(6); PG8_BAR;
.LBB0_1794:
	s_add_u32 s14, s4, 0x17500000
	s_mov_b64 s[16:17], 0x80
	s_addc_u32 s15, s5, 0
	s_add_i32 m0, s35, 0x18000
	v_lshl_add_u64 v[10:11], v[10:11], 0, s[16:17]
	s_waitcnt vmcnt(2)
	s_barrier
	global_load_lds_dwordx4 v[10:11], off
	v_lshl_add_u64 v[6:7], v[6:7], 0, s[16:17]
	s_add_i32 m0, s35, 0x1a000
	s_add_i32 s40, s35, 0x8000
	global_load_lds_dwordx4 v[6:7], off
	v_lshl_add_u64 v[6:7], v[8:9], 0, s[16:17]
	s_mov_b32 m0, s40
	s_add_i32 s41, s35, 0xa000
	global_load_lds_dwordx4 v[6:7], off
	v_lshl_add_u64 v[6:7], v[12:13], 0, s[16:17]
	s_mov_b32 m0, s41
	v_lshl_add_u64 v[4:5], v[4:5], 0, s[16:17]
	global_load_lds_dwordx4 v[6:7], off
	s_add_i32 m0, s35, 0x1c000
	v_lshl_add_u64 v[2:3], v[2:3], 0, s[16:17]
	global_load_lds_dwordx4 v[4:5], off
	s_add_i32 m0, s35, 0x1e000
	s_lshr_b32 s1, s1, 26
	global_load_lds_dwordx4 v[2:3], off
	v_and_b32_e32 v2, 15, v0
	s_add_i32 s1, s0, s1
	v_lshlrev_b32_e32 v3, 1, v18
	v_lshlrev_b32_e32 v4, 2, v0
	s_ashr_i32 s42, s1, 6
	v_lshl_or_b32 v1, s21, 6, v2
	v_lshl_or_b32 v2, v2, 6, v3
	s_lshl_b32 s1, s21, 13
	v_and_b32_e32 v4, 32, v4
	v_bitop3_b32 v5, v2, s1, v4 bitop3:0xde
	s_lshl_b32 s1, s19, 5
	s_and_b32 s1, s1, 0x60
	v_lshlrev_b32_e32 v2, 6, v0
	s_movk_i32 s4, 0x3c0
	v_and_or_b32 v2, v2, s4, v3
	s_lshl_b32 s4, s1, 7
	v_bitop3_b32 v146, s4, v2, v4 bitop3:0xf6
	v_add_u32_e32 v2, v19, v16
	v_mul_lo_u32 v2, s0, v2
	v_lshlrev_b32_e32 v2, 1, v2
	v_add3_u32 v2, v14, v2, v15
	v_mov_b32_e32 v3, v133
	s_cmp_gt_i32 s0, 63
	v_lshl_add_u64 v[138:139], s[8:9], 0, v[2:3]
	v_add_u32_e32 v2, v17, v16
	s_sext_i32_i8 s53, s18
	s_cselect_b64 s[18:19], -1, 0
	s_add_i32 s43, s42, -2
	v_mul_lo_u32 v2, s0, v2
	s_waitcnt vmcnt(6)
	s_cmpk_lt_u32 s20, 0x100
	v_lshlrev_b32_e32 v2, 1, v2
	s_cselect_b64 s[20:21], -1, 0
	v_add3_u32 v2, v14, v2, v15
	s_add_i32 s46, 0, 0x10000
	s_add_i32 s47, 0, 0x14000
	s_ashr_i32 s44, s82, 31
	s_mov_b32 s45, s82
	v_or_b32_e32 v147, s1, v18
	v_lshl_add_u64 v[140:141], s[8:9], 0, v[2:3]
	v_mov_b64_e32 v[142:143], 0x200
	v_mov_b64_e32 v[144:145], 0x1ff
	v_add_u32_e32 v148, s46, v146
	v_add_u32_e32 v149, s47, v146
	v_add_u32_e32 v150, 0, v5
	s_barrier
	s_waitcnt vmcnt(0)
	s_branch .LBB0_1797
	.p2align	6

; template <class Epi, class Sched, bool ALIGN_EPI = false, bool SP2 = false>
; __device__ __forceinline__ void gemm_phase(PG8_LAS unsigned char* lds, const Gemm g, const Sched& S, const Epi& E) {
;     ...
;         if (!has_next) break;
; #pragma unroll
;         for (int a = 0; a < 2; ++a)
; #pragma unroll
;             for (int b = 0; b < 2; ++b)
; #pragma unroll
;                 for (int m = 0; m < 4; ++m)
; #pragma unroll
;                     for (int n = 0; n < 2; ++n) acc[a][b][m][n] = (f32x4){0.f, 0.f, 0.f, 0.f};
;         cur = nxt; cA = nA; cB = nB; ++ui;
.LBB0_1807:
	v_mov_b32_e32 v125, 0
	s_andn2_b64 vcc, exec, s[18:19]
	v_mov_b32_e32 v124, v125
	v_mov_b32_e32 v123, v125
	v_mov_b32_e32 v122, v125
	v_mov_b32_e32 v129, v125
	v_mov_b32_e32 v128, v125
	v_mov_b32_e32 v127, v125
	v_mov_b32_e32 v126, v125
	v_mov_b32_e32 v113, v125
	v_mov_b32_e32 v112, v125
	v_mov_b32_e32 v111, v125
	v_mov_b32_e32 v110, v125
	v_mov_b32_e32 v109, v125
	v_mov_b32_e32 v108, v125
	v_mov_b32_e32 v107, v125
	v_mov_b32_e32 v106, v125
	v_mov_b32_e32 v97, v125
	v_mov_b32_e32 v96, v125
	v_mov_b32_e32 v95, v125
	v_mov_b32_e32 v94, v125
	v_mov_b32_e32 v93, v125
	v_mov_b32_e32 v92, v125
	v_mov_b32_e32 v91, v125
	v_mov_b32_e32 v90, v125
	v_mov_b32_e32 v81, v125
	v_mov_b32_e32 v80, v125
	v_mov_b32_e32 v79, v125
	v_mov_b32_e32 v78, v125
	v_mov_b32_e32 v77, v125
	v_mov_b32_e32 v76, v125
	v_mov_b32_e32 v75, v125
	v_mov_b32_e32 v74, v125
	v_mov_b32_e32 v121, v125
	v_mov_b32_e32 v120, v125
	v_mov_b32_e32 v119, v125
	v_mov_b32_e32 v118, v125
	v_mov_b32_e32 v117, v125
	v_mov_b32_e32 v116, v125
	v_mov_b32_e32 v115, v125
	v_mov_b32_e32 v114, v125
	v_mov_b32_e32 v105, v125
	v_mov_b32_e32 v104, v125
	v_mov_b32_e32 v103, v125
	v_mov_b32_e32 v102, v125
	v_mov_b32_e32 v101, v125
	v_mov_b32_e32 v100, v125
	v_mov_b32_e32 v99, v125
	v_mov_b32_e32 v98, v125
	v_mov_b32_e32 v89, v125
	v_mov_b32_e32 v88, v125
	v_mov_b32_e32 v87, v125
	v_mov_b32_e32 v86, v125
	v_mov_b32_e32 v85, v125
	v_mov_b32_e32 v84, v125
	v_mov_b32_e32 v83, v125
	v_mov_b32_e32 v82, v125
	v_mov_b32_e32 v73, v125
	v_mov_b32_e32 v72, v125
	v_mov_b32_e32 v71, v125
	v_mov_b32_e32 v70, v125
	v_mov_b32_e32 v69, v125
	v_mov_b32_e32 v68, v125
	v_mov_b32_e32 v67, v125
	v_mov_b32_e32 v66, v125
	v_mov_b32_e32 v65, v125
	v_mov_b32_e32 v64, v125
	v_mov_b32_e32 v63, v125
	v_mov_b32_e32 v62, v125
	v_mov_b32_e32 v61, v125
	v_mov_b32_e32 v60, v125
	v_mov_b32_e32 v59, v125
	v_mov_b32_e32 v58, v125
	v_mov_b32_e32 v49, v125
	v_mov_b32_e32 v48, v125
	v_mov_b32_e32 v47, v125
	v_mov_b32_e32 v46, v125
	v_mov_b32_e32 v45, v125
	v_mov_b32_e32 v44, v125
	v_mov_b32_e32 v43, v125
	v_mov_b32_e32 v42, v125
	v_mov_b32_e32 v33, v125
	v_mov_b32_e32 v32, v125
	v_mov_b32_e32 v31, v125
	v_mov_b32_e32 v30, v125
	v_mov_b32_e32 v29, v125
	v_mov_b32_e32 v28, v125
	v_mov_b32_e32 v27, v125
	v_mov_b32_e32 v26, v125
	v_mov_b32_e32 v17, v125
	v_mov_b32_e32 v16, v125
	v_mov_b32_e32 v15, v125
	v_mov_b32_e32 v14, v125
	v_mov_b32_e32 v13, v125
	v_mov_b32_e32 v12, v125
	v_mov_b32_e32 v11, v125
	v_mov_b32_e32 v10, v125
	v_mov_b32_e32 v57, v125
	v_mov_b32_e32 v56, v125
	v_mov_b32_e32 v55, v125
	v_mov_b32_e32 v54, v125
	v_mov_b32_e32 v53, v125
	v_mov_b32_e32 v52, v125
	v_mov_b32_e32 v51, v125
	v_mov_b32_e32 v50, v125
	v_mov_b32_e32 v41, v125
	v_mov_b32_e32 v40, v125
	v_mov_b32_e32 v39, v125
	v_mov_b32_e32 v38, v125
	v_mov_b32_e32 v37, v125
	v_mov_b32_e32 v36, v125
	v_mov_b32_e32 v35, v125
	v_mov_b32_e32 v34, v125
	v_mov_b32_e32 v25, v125
	v_mov_b32_e32 v24, v125
	v_mov_b32_e32 v23, v125
	v_mov_b32_e32 v22, v125
	v_mov_b32_e32 v21, v125
	v_mov_b32_e32 v20, v125
	v_mov_b32_e32 v19, v125
	v_mov_b32_e32 v18, v125
	v_mov_b32_e32 v9, v125
	v_mov_b32_e32 v8, v125
	v_mov_b32_e32 v7, v125
	v_mov_b32_e32 v6, v125
	v_mov_b32_e32 v5, v125
	v_mov_b32_e32 v4, v125
	v_mov_b32_e32 v3, v125
	v_mov_b32_e32 v2, v125
	s_cbranch_vccnz .LBB0_1810
	s_add_u32 s54, s24, 0x100
	s_addc_u32 s55, s25, 0
	s_add_u32 s24, s26, 0x80
	v_mov_b32_e32 v2, 0
	s_addc_u32 s25, s27, 0
	s_mov_b32 s26, 0
	v_mov_b32_e32 v3, v2
	v_mov_b32_e32 v4, v2
	v_mov_b32_e32 v5, v2
	v_mov_b32_e32 v6, v2
	v_mov_b32_e32 v7, v2
	v_mov_b32_e32 v8, v2
	v_mov_b32_e32 v9, v2
	v_mov_b32_e32 v18, v2
	v_mov_b32_e32 v19, v2
	v_mov_b32_e32 v20, v2
	v_mov_b32_e32 v21, v2
	v_mov_b32_e32 v22, v2
	v_mov_b32_e32 v23, v2
	v_mov_b32_e32 v24, v2
	v_mov_b32_e32 v25, v2
	v_mov_b32_e32 v34, v2
	v_mov_b32_e32 v35, v2
	v_mov_b32_e32 v36, v2
	v_mov_b32_e32 v37, v2
	v_mov_b32_e32 v38, v2
	v_mov_b32_e32 v39, v2
	v_mov_b32_e32 v40, v2
	v_mov_b32_e32 v41, v2
	v_mov_b32_e32 v50, v2
	v_mov_b32_e32 v51, v2
	v_mov_b32_e32 v52, v2
	v_mov_b32_e32 v53, v2
	v_mov_b32_e32 v54, v2
	v_mov_b32_e32 v55, v2
	v_mov_b32_e32 v56, v2
	v_mov_b32_e32 v57, v2
	v_mov_b32_e32 v10, v2
	v_mov_b32_e32 v11, v2
	v_mov_b32_e32 v12, v2
	v_mov_b32_e32 v13, v2
	v_mov_b32_e32 v14, v2
	v_mov_b32_e32 v15, v2
	v_mov_b32_e32 v16, v2
	v_mov_b32_e32 v17, v2
	v_mov_b32_e32 v26, v2
	v_mov_b32_e32 v27, v2
	v_mov_b32_e32 v28, v2
	v_mov_b32_e32 v29, v2
	v_mov_b32_e32 v30, v2
	v_mov_b32_e32 v31, v2
	v_mov_b32_e32 v32, v2
	v_mov_b32_e32 v33, v2
	v_mov_b32_e32 v42, v2
	v_mov_b32_e32 v43, v2
	v_mov_b32_e32 v44, v2
	v_mov_b32_e32 v45, v2
	v_mov_b32_e32 v46, v2
	v_mov_b32_e32 v47, v2
	v_mov_b32_e32 v48, v2
	v_mov_b32_e32 v49, v2
	v_mov_b32_e32 v58, v2
	v_mov_b32_e32 v59, v2
	v_mov_b32_e32 v60, v2
	v_mov_b32_e32 v61, v2
	v_mov_b32_e32 v62, v2
	v_mov_b32_e32 v63, v2
	v_mov_b32_e32 v64, v2
	v_mov_b32_e32 v65, v2
	v_mov_b32_e32 v66, v2
	v_mov_b32_e32 v67, v2
	v_mov_b32_e32 v68, v2
	v_mov_b32_e32 v69, v2
	v_mov_b32_e32 v70, v2
	v_mov_b32_e32 v71, v2
	v_mov_b32_e32 v72, v2
	v_mov_b32_e32 v73, v2
	v_mov_b32_e32 v82, v2
	v_mov_b32_e32 v83, v2
	v_mov_b32_e32 v84, v2
	v_mov_b32_e32 v85, v2
	v_mov_b32_e32 v86, v2
	v_mov_b32_e32 v87, v2
	v_mov_b32_e32 v88, v2
	v_mov_b32_e32 v89, v2
	v_mov_b32_e32 v98, v2
	v_mov_b32_e32 v99, v2
	v_mov_b32_e32 v100, v2
	v_mov_b32_e32 v101, v2
	v_mov_b32_e32 v102, v2
	v_mov_b32_e32 v103, v2
	v_mov_b32_e32 v104, v2
	v_mov_b32_e32 v105, v2
	v_mov_b32_e32 v114, v2
	v_mov_b32_e32 v115, v2
	v_mov_b32_e32 v116, v2
	v_mov_b32_e32 v117, v2
	v_mov_b32_e32 v118, v2
	v_mov_b32_e32 v119, v2
	v_mov_b32_e32 v120, v2
	v_mov_b32_e32 v121, v2
	v_mov_b32_e32 v74, v2
	v_mov_b32_e32 v75, v2
	v_mov_b32_e32 v76, v2
	v_mov_b32_e32 v77, v2
	v_mov_b32_e32 v78, v2
	v_mov_b32_e32 v79, v2
	v_mov_b32_e32 v80, v2
	v_mov_b32_e32 v81, v2
	v_mov_b32_e32 v90, v2
	v_mov_b32_e32 v91, v2
	v_mov_b32_e32 v92, v2
	v_mov_b32_e32 v93, v2
	v_mov_b32_e32 v94, v2
	v_mov_b32_e32 v95, v2
	v_mov_b32_e32 v96, v2
	v_mov_b32_e32 v97, v2
	v_mov_b32_e32 v106, v2
	v_mov_b32_e32 v107, v2
	v_mov_b32_e32 v108, v2
	v_mov_b32_e32 v109, v2
	v_mov_b32_e32 v110, v2
	v_mov_b32_e32 v111, v2
	v_mov_b32_e32 v112, v2
	v_mov_b32_e32 v113, v2
	v_mov_b32_e32 v126, v2
	v_mov_b32_e32 v127, v2
	v_mov_b32_e32 v128, v2
	v_mov_b32_e32 v129, v2
	v_mov_b32_e32 v122, v2
	v_mov_b32_e32 v123, v2
	v_mov_b32_e32 v124, v2
	v_mov_b32_e32 v125, v2
	.p2align	6

; #define PG8_STAGE(bufoff, gbase, voff) do { _Pragma("unroll") for (int _i = 0; _i < 2; ++_i) \
;         __builtin_amdgcn_global_load_lds((const unsigned*)((const char*)(gbase) + (voff)[_i]), (PG8_LAS unsigned*)(lds + (bufoff) + ldsw + _i * 8192), 16, 0, 0); } while (0)
; #define PG8_WAIT_V(n) asm volatile("s_waitcnt vmcnt(" #n ")" ::: "memory")
; #define PG8_BAR __builtin_amdgcn_s_barrier()
; template <class Epi, class Sched, bool ALIGN_EPI = false, bool SP2 = false>
; __device__ __forceinline__ void gemm_phase(PG8_LAS unsigned char* lds, const Gemm g, const Sched& S, const Epi& E) {
;     const int tid = threadIdx.x, wid = __builtin_amdgcn_readfirstlane(tid >> 6), lane = tid & 63, wr = wid >> 2, wc = wid & 3, fr = lane & 15, fq = lane >> 4;
;     const int K = g.K, nt = K / BK;
;     unsigned voffA[2], voffB[2];
; #pragma unroll
;     for (int i = 0; i < 2; ++i) { int R, C; stage_rc(tid * 16 + i * 8192, R, C); const int Rb = Epi::PERM ? ((R & ~31) + perm32(R & 31)) : R;
;         voffA[i] = (unsigned)(R * K + C) * 2u; voffB[i] = (unsigned)(Rb * K + C) * 2u; }
;     const size_t kstep = (size_t)(BK * 2);
;     const size_t hstep = (size_t)HALF * K * 2;
;     const size_t tstep = 2 * hstep;
;     const unsigned ldsw = (unsigned)wid * 1024u;
;     const int aoff = lds_byte(wr * 64 + fr, fq * 8), boff = lds_byte(wc * 32 + fr, fq * 8);
;     ...
;         PG8_STAGE(PG8_SB(0, 0), cB, voffB); PG8_STAGE(PG8_SB(0, 1), cB + hstep, voffB); PG8_STAGE(PG8_SA(0, 0), cA, voffA); PG8_STAGE(PG8_SA(0, 1), cA + hstep, voffA);
;         if (wr == 1) PG8_BAR;
;         PG8_WAIT_V(2); PG8_BAR;
;         PG8_STAGE(PG8_SB(1, 0), cB + kstep, voffB); PG8_STAGE(PG8_SA(1, 0), cA + kstep, voffA); PG8_STAGE(PG8_SB(1, 1), cB + hstep + kstep, voffB);
;         PG8_WAIT_V(6); PG8_BAR;
.LBB0_1965:
	s_add_u32 s14, s4, 0xc500000
	s_mov_b64 s[16:17], 0x80
	s_addc_u32 s15, s5, 0
	s_add_i32 m0, s36, 0x18000
	v_lshl_add_u64 v[10:11], v[10:11], 0, s[16:17]
	s_waitcnt vmcnt(2)
	s_barrier
	global_load_lds_dwordx4 v[10:11], off
	v_lshl_add_u64 v[6:7], v[6:7], 0, s[16:17]
	s_add_i32 m0, s36, 0x1a000
	s_add_i32 s41, s36, 0x8000
	global_load_lds_dwordx4 v[6:7], off
	v_lshl_add_u64 v[6:7], v[8:9], 0, s[16:17]
	s_mov_b32 m0, s41
	s_add_i32 s42, s36, 0xa000
	global_load_lds_dwordx4 v[6:7], off
	v_lshl_add_u64 v[6:7], v[12:13], 0, s[16:17]
	s_mov_b32 m0, s42
	v_lshl_add_u64 v[4:5], v[4:5], 0, s[16:17]
	global_load_lds_dwordx4 v[6:7], off
	s_add_i32 m0, s36, 0x1c000
	v_lshl_add_u64 v[2:3], v[2:3], 0, s[16:17]
	global_load_lds_dwordx4 v[4:5], off
	s_add_i32 m0, s36, 0x1e000
	s_lshr_b32 s1, s1, 26
	global_load_lds_dwordx4 v[2:3], off
	v_and_b32_e32 v2, 15, v0
	s_add_i32 s1, s0, s1
	v_lshlrev_b32_e32 v3, 1, v16
	v_lshlrev_b32_e32 v4, 2, v0
	s_ashr_i32 s43, s1, 6
	v_lshl_or_b32 v1, s21, 6, v2
	v_lshl_or_b32 v2, v2, 6, v3
	s_lshl_b32 s1, s21, 13
	v_and_b32_e32 v4, 32, v4
	v_bitop3_b32 v5, v2, s1, v4 bitop3:0xde
	s_lshl_b32 s1, s19, 5
	s_and_b32 s1, s1, 0x60
	v_lshlrev_b32_e32 v2, 6, v0
	s_movk_i32 s4, 0x3c0
	v_and_or_b32 v2, v2, s4, v3
	s_lshl_b32 s4, s1, 7
	v_bitop3_b32 v146, s4, v2, v4 bitop3:0xf6
	v_add_u32_e32 v2, v18, v17
	v_mul_lo_u32 v2, s0, v2
	v_lshlrev_b32_e32 v2, 1, v2
	v_add3_u32 v2, v14, v2, v15
	v_mov_b32_e32 v3, v135
	s_cmp_gt_i32 s0, 63
	v_lshl_add_u64 v[138:139], s[8:9], 0, v[2:3]
	v_add_u32_e32 v2, v19, v17
	s_sext_i32_i16 s55, s18
	s_cselect_b64 s[18:19], -1, 0
	s_add_i32 s44, s43, -2
	v_mul_lo_u32 v2, s0, v2
	s_waitcnt vmcnt(6)
	s_cmpk_lt_u32 s20, 0x100
	v_lshlrev_b32_e32 v2, 1, v2
	s_cselect_b64 s[20:21], -1, 0
	v_add3_u32 v2, v14, v2, v15
	s_add_i32 s47, 0, 0x10000
	s_add_i32 s48, 0, 0x14000
	s_ashr_i32 s45, s82, 31
	s_mov_b32 s46, s82
	v_or_b32_e32 v147, s1, v16
	v_lshl_add_u64 v[140:141], s[8:9], 0, v[2:3]
	v_mov_b64_e32 v[142:143], 0xb00
	v_mov_b64_e32 v[144:145], 0xaff
	v_add_u32_e32 v148, s47, v146
	v_add_u32_e32 v149, s48, v146
	v_add_u32_e32 v150, 0, v5
	s_movk_i32 s49, 0x2c00
	s_barrier
	s_waitcnt vmcnt(0)
	s_branch .LBB0_1968
	.p2align	6

; template <class Epi, class Sched, bool ALIGN_EPI = false, bool SP2 = false>
; __device__ __forceinline__ void gemm_phase(PG8_LAS unsigned char* lds, const Gemm g, const Sched& S, const Epi& E) {
;     ...
;         if (!has_next) break;
; #pragma unroll
;         for (int a = 0; a < 2; ++a)
; #pragma unroll
;             for (int b = 0; b < 2; ++b)
; #pragma unroll
;                 for (int m = 0; m < 4; ++m)
; #pragma unroll
;                     for (int n = 0; n < 2; ++n) acc[a][b][m][n] = (f32x4){0.f, 0.f, 0.f, 0.f};
;         cur = nxt; cA = nA; cB = nB; ++ui;
.LBB0_1974:
	v_mov_b32_e32 v125, 0
	s_andn2_b64 vcc, exec, s[18:19]
	v_mov_b32_e32 v124, v125
	v_mov_b32_e32 v123, v125
	v_mov_b32_e32 v122, v125
	v_mov_b32_e32 v121, v125
	v_mov_b32_e32 v120, v125
	v_mov_b32_e32 v119, v125
	v_mov_b32_e32 v118, v125
	v_mov_b32_e32 v113, v125
	v_mov_b32_e32 v112, v125
	v_mov_b32_e32 v111, v125
	v_mov_b32_e32 v110, v125
	v_mov_b32_e32 v105, v125
	v_mov_b32_e32 v104, v125
	v_mov_b32_e32 v103, v125
	v_mov_b32_e32 v102, v125
	v_mov_b32_e32 v97, v125
	v_mov_b32_e32 v96, v125
	v_mov_b32_e32 v95, v125
	v_mov_b32_e32 v94, v125
	v_mov_b32_e32 v89, v125
	v_mov_b32_e32 v88, v125
	v_mov_b32_e32 v87, v125
	v_mov_b32_e32 v86, v125
	v_mov_b32_e32 v81, v125
	v_mov_b32_e32 v80, v125
	v_mov_b32_e32 v79, v125
	v_mov_b32_e32 v78, v125
	v_mov_b32_e32 v73, v125
	v_mov_b32_e32 v72, v125
	v_mov_b32_e32 v71, v125
	v_mov_b32_e32 v70, v125
	v_mov_b32_e32 v129, v125
	v_mov_b32_e32 v128, v125
	v_mov_b32_e32 v127, v125
	v_mov_b32_e32 v126, v125
	v_mov_b32_e32 v117, v125
	v_mov_b32_e32 v116, v125
	v_mov_b32_e32 v115, v125
	v_mov_b32_e32 v114, v125
	v_mov_b32_e32 v109, v125
	v_mov_b32_e32 v108, v125
	v_mov_b32_e32 v107, v125
	v_mov_b32_e32 v106, v125
	v_mov_b32_e32 v101, v125
	v_mov_b32_e32 v100, v125
	v_mov_b32_e32 v99, v125
	v_mov_b32_e32 v98, v125
	v_mov_b32_e32 v93, v125
	v_mov_b32_e32 v92, v125
	v_mov_b32_e32 v91, v125
	v_mov_b32_e32 v90, v125
	v_mov_b32_e32 v85, v125
	v_mov_b32_e32 v84, v125
	v_mov_b32_e32 v83, v125
	v_mov_b32_e32 v82, v125
	v_mov_b32_e32 v77, v125
	v_mov_b32_e32 v76, v125
	v_mov_b32_e32 v75, v125
	v_mov_b32_e32 v74, v125
	v_mov_b32_e32 v69, v125
	v_mov_b32_e32 v68, v125
	v_mov_b32_e32 v67, v125
	v_mov_b32_e32 v66, v125
	v_mov_b32_e32 v65, v125
	v_mov_b32_e32 v64, v125
	v_mov_b32_e32 v63, v125
	v_mov_b32_e32 v62, v125
	v_mov_b32_e32 v57, v125
	v_mov_b32_e32 v56, v125
	v_mov_b32_e32 v55, v125
	v_mov_b32_e32 v54, v125
	v_mov_b32_e32 v49, v125
	v_mov_b32_e32 v48, v125
	v_mov_b32_e32 v47, v125
	v_mov_b32_e32 v46, v125
	v_mov_b32_e32 v41, v125
	v_mov_b32_e32 v40, v125
	v_mov_b32_e32 v39, v125
	v_mov_b32_e32 v38, v125
	v_mov_b32_e32 v33, v125
	v_mov_b32_e32 v32, v125
	v_mov_b32_e32 v31, v125
	v_mov_b32_e32 v30, v125
	v_mov_b32_e32 v25, v125
	v_mov_b32_e32 v24, v125
	v_mov_b32_e32 v23, v125
	v_mov_b32_e32 v22, v125
	v_mov_b32_e32 v17, v125
	v_mov_b32_e32 v16, v125
	v_mov_b32_e32 v15, v125
	v_mov_b32_e32 v14, v125
	v_mov_b32_e32 v9, v125
	v_mov_b32_e32 v8, v125
	v_mov_b32_e32 v7, v125
	v_mov_b32_e32 v6, v125
	v_mov_b32_e32 v61, v125
	v_mov_b32_e32 v60, v125
	v_mov_b32_e32 v59, v125
	v_mov_b32_e32 v58, v125
	v_mov_b32_e32 v53, v125
	v_mov_b32_e32 v52, v125
	v_mov_b32_e32 v51, v125
	v_mov_b32_e32 v50, v125
	v_mov_b32_e32 v45, v125
	v_mov_b32_e32 v44, v125
	v_mov_b32_e32 v43, v125
	v_mov_b32_e32 v42, v125
	v_mov_b32_e32 v37, v125
	v_mov_b32_e32 v36, v125
	v_mov_b32_e32 v35, v125
	v_mov_b32_e32 v34, v125
	v_mov_b32_e32 v29, v125
	v_mov_b32_e32 v28, v125
	v_mov_b32_e32 v27, v125
	v_mov_b32_e32 v26, v125
	v_mov_b32_e32 v21, v125
	v_mov_b32_e32 v20, v125
	v_mov_b32_e32 v19, v125
	v_mov_b32_e32 v18, v125
	v_mov_b32_e32 v13, v125
	v_mov_b32_e32 v12, v125
	v_mov_b32_e32 v11, v125
	v_mov_b32_e32 v10, v125
	v_mov_b32_e32 v5, v125
	v_mov_b32_e32 v4, v125
	v_mov_b32_e32 v3, v125
	v_mov_b32_e32 v2, v125
	s_cbranch_vccnz .LBB0_1977
	s_add_u32 s56, s24, 0x100
	s_addc_u32 s57, s25, 0
	s_add_u32 s24, s26, 0x80
	v_mov_b32_e32 v2, 0
	s_addc_u32 s25, s27, 0
	s_mov_b32 s26, 0
	v_mov_b32_e32 v3, v2
	v_mov_b32_e32 v4, v2
	v_mov_b32_e32 v5, v2
	v_mov_b32_e32 v10, v2
	v_mov_b32_e32 v11, v2
	v_mov_b32_e32 v12, v2
	v_mov_b32_e32 v13, v2
	v_mov_b32_e32 v18, v2
	v_mov_b32_e32 v19, v2
	v_mov_b32_e32 v20, v2
	v_mov_b32_e32 v21, v2
	v_mov_b32_e32 v26, v2
	v_mov_b32_e32 v27, v2
	v_mov_b32_e32 v28, v2
	v_mov_b32_e32 v29, v2
	v_mov_b32_e32 v34, v2
	v_mov_b32_e32 v35, v2
	v_mov_b32_e32 v36, v2
	v_mov_b32_e32 v37, v2
	v_mov_b32_e32 v42, v2
	v_mov_b32_e32 v43, v2
	v_mov_b32_e32 v44, v2
	v_mov_b32_e32 v45, v2
	v_mov_b32_e32 v50, v2
	v_mov_b32_e32 v51, v2
	v_mov_b32_e32 v52, v2
	v_mov_b32_e32 v53, v2
	v_mov_b32_e32 v58, v2
	v_mov_b32_e32 v59, v2
	v_mov_b32_e32 v60, v2
	v_mov_b32_e32 v61, v2
	v_mov_b32_e32 v6, v2
	v_mov_b32_e32 v7, v2
	v_mov_b32_e32 v8, v2
	v_mov_b32_e32 v9, v2
	v_mov_b32_e32 v14, v2
	v_mov_b32_e32 v15, v2
	v_mov_b32_e32 v16, v2
	v_mov_b32_e32 v17, v2
	v_mov_b32_e32 v22, v2
	v_mov_b32_e32 v23, v2
	v_mov_b32_e32 v24, v2
	v_mov_b32_e32 v25, v2
	v_mov_b32_e32 v30, v2
	v_mov_b32_e32 v31, v2
	v_mov_b32_e32 v32, v2
	v_mov_b32_e32 v33, v2
	v_mov_b32_e32 v38, v2
	v_mov_b32_e32 v39, v2
	v_mov_b32_e32 v40, v2
	v_mov_b32_e32 v41, v2
	v_mov_b32_e32 v46, v2
	v_mov_b32_e32 v47, v2
	v_mov_b32_e32 v48, v2
	v_mov_b32_e32 v49, v2
	v_mov_b32_e32 v54, v2
	v_mov_b32_e32 v55, v2
	v_mov_b32_e32 v56, v2
	v_mov_b32_e32 v57, v2
	v_mov_b32_e32 v62, v2
	v_mov_b32_e32 v63, v2
	v_mov_b32_e32 v64, v2
	v_mov_b32_e32 v65, v2
	v_mov_b32_e32 v66, v2
	v_mov_b32_e32 v67, v2
	v_mov_b32_e32 v68, v2
	v_mov_b32_e32 v69, v2
	v_mov_b32_e32 v74, v2
	v_mov_b32_e32 v75, v2
	v_mov_b32_e32 v76, v2
	v_mov_b32_e32 v77, v2
	v_mov_b32_e32 v82, v2
	v_mov_b32_e32 v83, v2
	v_mov_b32_e32 v84, v2
	v_mov_b32_e32 v85, v2
	v_mov_b32_e32 v90, v2
	v_mov_b32_e32 v91, v2
	v_mov_b32_e32 v92, v2
	v_mov_b32_e32 v93, v2
	v_mov_b32_e32 v98, v2
	v_mov_b32_e32 v99, v2
	v_mov_b32_e32 v100, v2
	v_mov_b32_e32 v101, v2
	v_mov_b32_e32 v106, v2
	v_mov_b32_e32 v107, v2
	v_mov_b32_e32 v108, v2
	v_mov_b32_e32 v109, v2
	v_mov_b32_e32 v114, v2
	v_mov_b32_e32 v115, v2
	v_mov_b32_e32 v116, v2
	v_mov_b32_e32 v117, v2
	v_mov_b32_e32 v126, v2
	v_mov_b32_e32 v127, v2
	v_mov_b32_e32 v128, v2
	v_mov_b32_e32 v129, v2
	v_mov_b32_e32 v70, v2
	v_mov_b32_e32 v71, v2
	v_mov_b32_e32 v72, v2
	v_mov_b32_e32 v73, v2
	v_mov_b32_e32 v78, v2
	v_mov_b32_e32 v79, v2
	v_mov_b32_e32 v80, v2
	v_mov_b32_e32 v81, v2
	v_mov_b32_e32 v86, v2
	v_mov_b32_e32 v87, v2
	v_mov_b32_e32 v88, v2
	v_mov_b32_e32 v89, v2
	v_mov_b32_e32 v94, v2
	v_mov_b32_e32 v95, v2
	v_mov_b32_e32 v96, v2
	v_mov_b32_e32 v97, v2
	v_mov_b32_e32 v102, v2
	v_mov_b32_e32 v103, v2
	v_mov_b32_e32 v104, v2
	v_mov_b32_e32 v105, v2
	v_mov_b32_e32 v110, v2
	v_mov_b32_e32 v111, v2
	v_mov_b32_e32 v112, v2
	v_mov_b32_e32 v113, v2
	v_mov_b32_e32 v118, v2
	v_mov_b32_e32 v119, v2
	v_mov_b32_e32 v120, v2
	v_mov_b32_e32 v121, v2
	v_mov_b32_e32 v122, v2
	v_mov_b32_e32 v123, v2
	v_mov_b32_e32 v124, v2
	v_mov_b32_e32 v125, v2
	.p2align	6
